# GEMM main loops: register staging replaced by direct-to-LDS loads (global_load_lds_dwordx4, swizzle on the source address), all 8 GEMMs
# speedup vs baseline: 1.0425x; 1.0205x over previous
.LBB0_286:
	s_and_b32 s0, s33, 7
	s_or_b32 s0, s0, s3
	s_lshl_b32 s34, s0, 7
	v_or_b32_e32 v0, s34, v149
	v_lshl_or_b32 v128, v0, 11, v158
	v_lshl_add_u64 v[98:99], s[14:15], 0, v[128:129]
	v_add_co_u32_e32 v6, vcc, 0x10000, v98
	s_lshl_b32 s1, s33, 4
	s_nop 0
	v_addc_co_u32_e32 v7, vcc, 0, v99, vcc
	s_and_b32 s0, s1, 0x7fffff80
	v_add_co_u32_e32 v8, vcc, 0x20000, v98
	v_or_b32_e32 v0, s0, v149
	s_nop 0
	v_addc_co_u32_e32 v9, vcc, 0, v99, vcc
	v_lshl_or_b32 v96, v0, 11, v158
	v_add_co_u32_e32 v10, vcc, 0x30000, v98
	v_mov_b32_e32 v97, v129
	s_nop 0
	v_addc_co_u32_e32 v11, vcc, 0, v99, vcc
	v_lshl_add_u64 v[100:101], s[12:13], 0, v[96:97]
	v_add_co_u32_e32 v12, vcc, s4, v100
	v_addc_co_u32_e32 v13, vcc, 0, v101, vcc
	v_add_co_u32_e32 v46, vcc, s5, v100
	v_addc_co_u32_e32 v47, vcc, 0, v101, vcc
	v_add_co_u32_e32 v48, vcc, s26, v100
	v_addc_co_u32_e32 v49, vcc, 0, v101, vcc
	s_movk_i32 s1, 0x100
	s_mov_b32 s6, s23
	v_mov_b32_e32 v0, 0
	v_mov_b32_e32 v1, v129
	v_mov_b32_e32 v2, v129
	v_mov_b32_e32 v3, v129
	v_mov_b32_e32 v4, 0
	v_mov_b32_e32 v5, v129
	v_mov_b32_e32 v6, v129
	v_mov_b32_e32 v7, v129
	v_mov_b32_e32 v8, 0
	v_mov_b32_e32 v9, v129
	v_mov_b32_e32 v10, v129
	v_mov_b32_e32 v11, v129
	v_mov_b32_e32 v12, 0
	v_mov_b32_e32 v13, v129
	v_lshl_add_u64 v[102:103], v[100:101], 0, s[10:11]
	v_lshl_add_u64 v[104:105], v[100:101], 0, s[18:19]
	v_lshl_add_u64 v[106:107], v[100:101], 0, s[20:21]
	v_lshl_add_u64 v[108:109], v[98:99], 0, s[10:11]
	v_lshl_add_u64 v[110:111], v[98:99], 0, s[18:19]
	v_lshl_add_u64 v[112:113], v[98:99], 0, s[20:21]
	s_barrier
	v_mov_b32_e32 v46, v129
	v_mov_b32_e32 v47, v129
	v_mov_b32_e32 v48, 0
	v_mov_b32_e32 v49, v129
	v_mov_b32_e32 v50, v129
	v_mov_b32_e32 v51, v129
	v_mov_b32_e32 v52, 0
	v_mov_b32_e32 v53, v129
	v_mov_b32_e32 v54, v129
	v_mov_b32_e32 v55, v129
	v_mov_b32_e32 v56, 0
	v_mov_b32_e32 v57, v129
	v_mov_b32_e32 v58, v129
	v_mov_b32_e32 v59, v129
	v_mov_b32_e32 v60, 0
	v_mov_b32_e32 v61, v129
	v_mov_b32_e32 v62, v129
	v_mov_b32_e32 v63, v129
	v_mov_b32_e32 v14, v129
	v_mov_b32_e32 v15, v129
	v_mov_b32_e32 v16, 0
	v_mov_b32_e32 v17, v129
	v_mov_b32_e32 v18, v129
	v_mov_b32_e32 v19, v129
	v_mov_b32_e32 v20, 0
	v_mov_b32_e32 v21, v129
	v_mov_b32_e32 v22, v129
	v_mov_b32_e32 v23, v129
	v_mov_b32_e32 v24, 0
	v_mov_b32_e32 v25, v129
	v_mov_b32_e32 v26, v129
	v_mov_b32_e32 v27, v129
	v_mov_b32_e32 v28, 0
	v_mov_b32_e32 v29, v129
	v_mov_b32_e32 v30, v129
	v_mov_b32_e32 v31, v129
	v_mov_b32_e32 v32, 0
	v_mov_b32_e32 v33, v129
	v_mov_b32_e32 v34, v129
	v_mov_b32_e32 v35, v129
	v_mov_b32_e32 v36, 0
	v_mov_b32_e32 v37, v129
	v_mov_b32_e32 v38, v129
	v_mov_b32_e32 v39, v129
	v_mov_b32_e32 v40, 0
	v_mov_b32_e32 v41, v129
	v_mov_b32_e32 v42, v129
	v_mov_b32_e32 v43, v129
	v_mov_b32_e32 v44, 0
	v_mov_b32_e32 v45, v129
	v_readlane_b32 s100, v253, 0
	v_readlane_b32 s101, v253, 1
	s_load_dwordx2 s[100:101], s[100:101], 0x160
	v_lshrrev_b32_e32 v71, 6, v146
	s_nop 0
	v_readfirstlane_b32 s24, v71
	v_lshrrev_b32_e32 v69, 3, v146
	v_and_b32_e32 v70, 7, v146
	v_xor_b32_e32 v70, v69, v70
	v_and_b32_e32 v70, 7, v70
	v_lshlrev_b32_e32 v70, 4, v70
	v_lshl_or_b32 v68, v69, 11, v70
	v_add_u32_e32 v69, 0x10000, v68
	v_add_u32_e32 v70, 0x20000, v68
	v_add_u32_e32 v71, 0x30000, v68
	s_and_b32 s98, s33, 7
	s_and_b32 s99, s69, 7
	s_lshl_b32 s99, s99, 3
	s_or_b32 s98, s98, s99
	s_lshl_b32 s98, s98, 18
	s_add_u32 s98, s98, 0x2000000
	s_lshr_b32 s99, s33, 3
	s_lshl_b32 s99, s99, 18
	s_add_u32 s99, s99, 0x7200000
	s_lshl_b32 s24, s24, 10
	s_waitcnt lgkmcnt(0)
	s_mov_b32 m0, s99
	s_add_u32 s98, s100, s98
	s_addc_u32 s99, s101, 0
	s_add_u32 s100, s100, m0
	s_addc_u32 s101, s101, 0
	s_add_u32 m0, s24, 0x0
	s_nop 0
	global_load_lds_dwordx4 v68, s[98:99]
	s_add_u32 m0, s24, 0x1000
	s_nop 0
	global_load_lds_dwordx4 v69, s[98:99]
	s_add_u32 m0, s24, 0x2000
	s_nop 0
	global_load_lds_dwordx4 v70, s[98:99]
	s_add_u32 m0, s24, 0x3000
	s_nop 0
	global_load_lds_dwordx4 v71, s[98:99]
	s_add_u32 m0, s24, 0x8000
	s_nop 0
	global_load_lds_dwordx4 v68, s[100:101]
	s_add_u32 m0, s24, 0x9000
	s_nop 0
	global_load_lds_dwordx4 v69, s[100:101]
	s_add_u32 m0, s24, 0xa000
	s_nop 0
	global_load_lds_dwordx4 v70, s[100:101]
	s_add_u32 m0, s24, 0xb000
	s_nop 0
	global_load_lds_dwordx4 v71, s[100:101]
	s_add_u32 s98, s98, 0x80
	s_addc_u32 s99, s99, 0
	s_add_u32 s100, s100, 0x80
	s_addc_u32 s101, s101, 0
	s_waitcnt vmcnt(0)
	s_waitcnt lgkmcnt(0)
	s_barrier
.LBB0_287:
	s_add_i32 s2, s6, 2
	s_setprio 1
	ds_read_b128 v[114:117], v165 offset:32768
	ds_read_b128 v[122:125], v165 offset:34816
	ds_read_b128 v[118:121], v161
	ds_read_b128 v[138:141], v161 offset:2048
	ds_read_b128 v[174:177], v161 offset:4096
	ds_read_b128 v[178:181], v161 offset:6144
	s_waitcnt lgkmcnt(3)
	v_mfma_f32_16x16x32_bf16 v[0:3], v[114:117], v[118:121], v[0:3]
	ds_read_b128 v[182:185], v165 offset:36864
	v_mfma_f32_16x16x32_bf16 v[4:7], v[122:125], v[118:121], v[4:7]
	ds_read_b128 v[186:189], v165 offset:38912
	s_waitcnt lgkmcnt(1)
	v_mfma_f32_16x16x32_bf16 v[8:11], v[182:185], v[118:121], v[8:11]
	s_waitcnt lgkmcnt(0)
	v_mfma_f32_16x16x32_bf16 v[12:15], v[186:189], v[118:121], v[12:15]
	s_add_u32 m0, s24, 0x4000
	s_nop 0
	global_load_lds_dwordx4 v68, s[98:99]
	ds_read_b128 v[190:193], v166
	v_mfma_f32_16x16x32_bf16 v[16:19], v[114:117], v[138:141], v[16:19]
	v_mfma_f32_16x16x32_bf16 v[20:23], v[122:125], v[138:141], v[20:23]
	s_add_u32 m0, s24, 0x5000
	s_nop 0
	global_load_lds_dwordx4 v69, s[98:99]
	ds_read_b128 v[198:201], v166 offset:2048
	v_mfma_f32_16x16x32_bf16 v[24:27], v[182:185], v[138:141], v[24:27]
	v_mfma_f32_16x16x32_bf16 v[28:31], v[186:189], v[138:141], v[28:31]
	s_add_u32 m0, s24, 0x6000
	s_nop 0
	global_load_lds_dwordx4 v70, s[98:99]
	ds_read_b128 v[202:205], v166 offset:4096
	v_mfma_f32_16x16x32_bf16 v[32:35], v[114:117], v[174:177], v[32:35]
	v_mfma_f32_16x16x32_bf16 v[36:39], v[122:125], v[174:177], v[36:39]
	s_add_u32 m0, s24, 0x7000
	s_nop 0
	global_load_lds_dwordx4 v71, s[98:99]
	ds_read_b128 v[210:213], v166 offset:6144
	v_mfma_f32_16x16x32_bf16 v[40:43], v[182:185], v[174:177], v[40:43]
	v_mfma_f32_16x16x32_bf16 v[44:47], v[186:189], v[174:177], v[44:47]
	s_add_u32 m0, s24, 0xc000
	s_nop 0
	global_load_lds_dwordx4 v68, s[100:101]
	ds_read_b128 v[214:217], v167 offset:32768
	v_mfma_f32_16x16x32_bf16 v[48:51], v[114:117], v[178:181], v[48:51]
	v_mfma_f32_16x16x32_bf16 v[52:55], v[122:125], v[178:181], v[52:55]
	s_add_u32 m0, s24, 0xd000
	s_nop 0
	global_load_lds_dwordx4 v69, s[100:101]
	ds_read_b128 v[122:125], v167 offset:34816
	v_mfma_f32_16x16x32_bf16 v[56:59], v[182:185], v[178:181], v[56:59]
	v_mfma_f32_16x16x32_bf16 v[60:63], v[186:189], v[178:181], v[60:63]
	s_add_u32 m0, s24, 0xe000
	s_nop 0
	global_load_lds_dwordx4 v70, s[100:101]
	ds_read_b128 v[182:185], v167 offset:36864
	s_waitcnt lgkmcnt(2)
	v_mfma_f32_16x16x32_bf16 v[0:3], v[214:217], v[190:193], v[0:3]
	s_waitcnt lgkmcnt(1)
	v_mfma_f32_16x16x32_bf16 v[4:7], v[122:125], v[190:193], v[4:7]
	s_add_u32 m0, s24, 0xf000
	s_nop 0
	global_load_lds_dwordx4 v71, s[100:101]
	s_add_u32 s98, s98, 0x80
	s_addc_u32 s99, s99, 0
	s_add_u32 s100, s100, 0x80
	s_addc_u32 s101, s101, 0
	ds_read_b128 v[218:221], v167 offset:38912
	s_waitcnt lgkmcnt(1)
	v_mfma_f32_16x16x32_bf16 v[8:11], v[182:185], v[190:193], v[8:11]
	s_waitcnt lgkmcnt(0)
	v_mfma_f32_16x16x32_bf16 v[12:15], v[218:221], v[190:193], v[12:15]
	v_mfma_f32_16x16x32_bf16 v[16:19], v[214:217], v[198:201], v[16:19]
	v_mfma_f32_16x16x32_bf16 v[20:23], v[122:125], v[198:201], v[20:23]
	v_mfma_f32_16x16x32_bf16 v[24:27], v[182:185], v[198:201], v[24:27]
	v_mfma_f32_16x16x32_bf16 v[28:31], v[218:221], v[198:201], v[28:31]
	v_mfma_f32_16x16x32_bf16 v[32:35], v[214:217], v[202:205], v[32:35]
	v_mfma_f32_16x16x32_bf16 v[36:39], v[122:125], v[202:205], v[36:39]
	v_mfma_f32_16x16x32_bf16 v[40:43], v[182:185], v[202:205], v[40:43]
	v_mfma_f32_16x16x32_bf16 v[44:47], v[218:221], v[202:205], v[44:47]
	v_mfma_f32_16x16x32_bf16 v[48:51], v[214:217], v[210:213], v[48:51]
	v_mfma_f32_16x16x32_bf16 v[52:55], v[122:125], v[210:213], v[52:55]
	v_mfma_f32_16x16x32_bf16 v[56:59], v[182:185], v[210:213], v[56:59]
	v_mfma_f32_16x16x32_bf16 v[60:63], v[218:221], v[210:213], v[60:63]
	s_setprio 0
	s_waitcnt vmcnt(0) lgkmcnt(0)
	s_barrier
	s_setprio 1
	ds_read_b128 v[84:87], v165 offset:49152
	ds_read_b128 v[88:91], v165 offset:51200
	ds_read_b128 v[64:67], v161 offset:16384
	ds_read_b128 v[72:75], v161 offset:18432
	ds_read_b128 v[76:79], v161 offset:20480
	ds_read_b128 v[92:95], v161 offset:22528
	s_waitcnt lgkmcnt(3)
	v_mfma_f32_16x16x32_bf16 v[0:3], v[84:87], v[64:67], v[0:3]
	ds_read_b128 v[122:125], v165 offset:53248
	v_mfma_f32_16x16x32_bf16 v[4:7], v[88:91], v[64:67], v[4:7]
	ds_read_b128 v[182:185], v165 offset:55296
	s_waitcnt lgkmcnt(1)
	v_mfma_f32_16x16x32_bf16 v[8:11], v[122:125], v[64:67], v[8:11]
	s_waitcnt lgkmcnt(0)
	v_mfma_f32_16x16x32_bf16 v[12:15], v[182:185], v[64:67], v[12:15]
	s_add_u32 m0, s24, 0x0
	s_nop 0
	global_load_lds_dwordx4 v68, s[98:99]
	ds_read_b128 v[190:193], v166 offset:16384
	v_mfma_f32_16x16x32_bf16 v[16:19], v[84:87], v[72:75], v[16:19]
	v_mfma_f32_16x16x32_bf16 v[20:23], v[88:91], v[72:75], v[20:23]
	s_add_u32 m0, s24, 0x1000
	s_nop 0
	global_load_lds_dwordx4 v69, s[98:99]
	ds_read_b128 v[198:201], v166 offset:18432
	v_mfma_f32_16x16x32_bf16 v[24:27], v[122:125], v[72:75], v[24:27]
	v_mfma_f32_16x16x32_bf16 v[28:31], v[182:185], v[72:75], v[28:31]
	s_add_u32 m0, s24, 0x2000
	s_nop 0
	global_load_lds_dwordx4 v70, s[98:99]
	ds_read_b128 v[202:205], v166 offset:20480
	v_mfma_f32_16x16x32_bf16 v[32:35], v[84:87], v[76:79], v[32:35]
	v_mfma_f32_16x16x32_bf16 v[36:39], v[88:91], v[76:79], v[36:39]
	s_add_u32 m0, s24, 0x3000
	s_nop 0
	global_load_lds_dwordx4 v71, s[98:99]
	ds_read_b128 v[210:213], v166 offset:22528
	v_mfma_f32_16x16x32_bf16 v[40:43], v[122:125], v[76:79], v[40:43]
	v_mfma_f32_16x16x32_bf16 v[44:47], v[182:185], v[76:79], v[44:47]
	s_add_u32 m0, s24, 0x8000
	s_nop 0
	global_load_lds_dwordx4 v68, s[100:101]
	ds_read_b128 v[214:217], v167 offset:49152
	v_mfma_f32_16x16x32_bf16 v[48:51], v[84:87], v[92:95], v[48:51]
	v_mfma_f32_16x16x32_bf16 v[52:55], v[88:91], v[92:95], v[52:55]
	s_add_u32 m0, s24, 0x9000
	s_nop 0
	global_load_lds_dwordx4 v69, s[100:101]
	ds_read_b128 v[218:221], v167 offset:51200
	v_mfma_f32_16x16x32_bf16 v[56:59], v[122:125], v[92:95], v[56:59]
	v_mfma_f32_16x16x32_bf16 v[60:63], v[182:185], v[92:95], v[60:63]
	s_add_u32 m0, s24, 0xa000
	s_nop 0
	global_load_lds_dwordx4 v70, s[100:101]
	ds_read_b128 v[122:125], v167 offset:53248
	s_waitcnt lgkmcnt(2)
	v_mfma_f32_16x16x32_bf16 v[0:3], v[214:217], v[190:193], v[0:3]
	s_waitcnt lgkmcnt(1)
	v_mfma_f32_16x16x32_bf16 v[4:7], v[218:221], v[190:193], v[4:7]
	s_add_u32 m0, s24, 0xb000
	s_nop 0
	global_load_lds_dwordx4 v71, s[100:101]
	s_add_u32 s98, s98, 0x80
	s_addc_u32 s99, s99, 0
	s_add_u32 s100, s100, 0x80
	s_addc_u32 s101, s101, 0
	ds_read_b128 v[182:185], v167 offset:55296
	s_waitcnt lgkmcnt(1)
	v_mfma_f32_16x16x32_bf16 v[8:11], v[122:125], v[190:193], v[8:11]
	s_waitcnt lgkmcnt(0)
	v_mfma_f32_16x16x32_bf16 v[12:15], v[182:185], v[190:193], v[12:15]
	v_mfma_f32_16x16x32_bf16 v[16:19], v[214:217], v[198:201], v[16:19]
	v_mfma_f32_16x16x32_bf16 v[20:23], v[218:221], v[198:201], v[20:23]
	v_mfma_f32_16x16x32_bf16 v[24:27], v[122:125], v[198:201], v[24:27]
	v_mfma_f32_16x16x32_bf16 v[28:31], v[182:185], v[198:201], v[28:31]
	v_mfma_f32_16x16x32_bf16 v[32:35], v[214:217], v[202:205], v[32:35]
	v_mfma_f32_16x16x32_bf16 v[36:39], v[218:221], v[202:205], v[36:39]
	v_mfma_f32_16x16x32_bf16 v[40:43], v[122:125], v[202:205], v[40:43]
	v_mfma_f32_16x16x32_bf16 v[44:47], v[182:185], v[202:205], v[44:47]
	v_mfma_f32_16x16x32_bf16 v[48:51], v[214:217], v[210:213], v[48:51]
	v_mfma_f32_16x16x32_bf16 v[52:55], v[218:221], v[210:213], v[52:55]
	v_mfma_f32_16x16x32_bf16 v[56:59], v[122:125], v[210:213], v[56:59]
	v_mfma_f32_16x16x32_bf16 v[60:63], v[182:185], v[210:213], v[60:63]
	s_setprio 0
	s_mov_b32 s6, s2
	s_waitcnt vmcnt(0) lgkmcnt(0)
	s_barrier
	s_cmp_lt_u32 s6, 16
	s_cbranch_scc1 .LBB0_287
	s_cmpk_lt_u32 s33, 0x50
	v_or_b32_e32 v138, s0, v234
	v_add_u32_e32 v128, s34, v164
	s_cselect_b64 s[24:25], -1, 0
	s_and_b32 s0, s33, 0x7ffffff0
	v_or_b32_e32 v173, v128, v148
	s_cmpk_lg_i32 s0, 0x50
	s_mov_b64 s[6:7], -1
	s_cbranch_scc0 .LBB0_298
	s_waitcnt vmcnt(7)
	v_lshlrev_b32_e32 v64, 1, v128
	s_and_b64 s[0:1], s[16:17], s[24:25]
	v_and_b32_e32 v128, 0x780, v64
	v_cndmask_b32_e64 v64, 0, 1, s[0:1]
	v_cmp_ne_u32_e64 s[6:7], 1, v64
	v_mov_b64_e32 v[66:67], v[2:3]
	s_waitcnt vmcnt(6)
	v_mov_b64_e32 v[70:71], v[6:7]
	s_waitcnt vmcnt(5)
	v_mov_b64_e32 v[74:75], v[10:11]
	s_waitcnt vmcnt(3)
	v_mov_b64_e32 v[78:79], v[14:15]
	v_lshl_add_u64 v[140:141], v[132:133], 0, v[128:129]
	s_andn2_b64 vcc, exec, s[0:1]
	v_lshlrev_b32_e32 v137, 7, v173
	v_mov_b64_e32 v[64:65], v[0:1]
	v_mov_b64_e32 v[68:69], v[4:5]
	v_mov_b64_e32 v[72:73], v[8:9]
	v_mov_b64_e32 v[76:77], v[12:13]
	s_cbranch_vccnz .LBB0_291
	v_and_b32_e32 v128, 0x780, v137
	v_lshl_add_u64 v[76:77], v[132:133], 0, v[128:129]
	global_load_dwordx4 v[64:67], v[140:141], off
	global_load_dwordx4 v[68:71], v[140:141], off offset:16
	global_load_dwordx4 v[72:75], v[76:77], off
	s_nop 0
	global_load_dwordx4 v[76:79], v[76:77], off offset:16
	v_mov_b32_e32 v80, v3
	v_mov_b32_e32 v81, v7
	v_mov_b32_e32 v82, v7
	v_mov_b32_e32 v83, v3
	s_waitcnt vmcnt(6)
	v_mov_b32_e32 v84, v11
	v_mov_b32_e32 v85, v15
	v_mov_b32_e32 v86, v15
	v_mov_b32_e32 v87, v11
	s_waitcnt vmcnt(3)
	v_mov_b32_e32 v88, v64
	v_mov_b32_e32 v89, v66
	v_mov_b32_e32 v66, v65
	s_waitcnt vmcnt(2)
	v_mul_f32_e32 v90, v2, v68
	v_mul_f32_e32 v92, v6, v69
	v_mul_f32_e32 v94, v6, v68
	v_mul_f32_e32 v96, v2, v69
	v_pk_mul_f32 v[64:65], v[80:81], v[70:71]
	v_pk_mul_f32 v[68:69], v[82:83], v[70:71]
	s_waitcnt vmcnt(1)
	v_mov_b32_e32 v80, v72
	v_mov_b32_e32 v81, v74
	v_mov_b32_e32 v74, v73
	s_waitcnt vmcnt(0)
	v_mul_f32_e32 v82, v10, v76
	v_mul_f32_e32 v98, v14, v77
	v_mul_f32_e32 v100, v14, v76
	v_mul_f32_e32 v102, v10, v77
	v_pk_mul_f32 v[72:73], v[84:85], v[78:79]
	v_pk_mul_f32 v[76:77], v[86:87], v[78:79]
	v_pk_mul_f32 v[70:71], v[0:1], v[66:67]
	v_pk_mul_f32 v[66:67], v[4:5], v[66:67]
	v_mov_b32_e32 v91, v64
	v_mov_b32_e32 v93, v65
	v_mov_b32_e32 v95, v68
	v_mov_b32_e32 v97, v69
	v_pk_mul_f32 v[78:79], v[8:9], v[74:75]
	v_pk_mul_f32 v[74:75], v[12:13], v[74:75]
	v_mov_b32_e32 v83, v72
	v_mov_b32_e32 v99, v73
	v_mov_b32_e32 v101, v76
	v_mov_b32_e32 v103, v77
	v_pk_fma_f32 v[64:65], v[0:1], v[88:89], v[66:67] neg_lo:[0,0,1] neg_hi:[0,0,1]
	v_pk_add_f32 v[66:67], v[90:91], v[92:93] neg_lo:[0,1] neg_hi:[0,1]
	v_pk_fma_f32 v[68:69], v[4:5], v[88:89], v[70:71]
	v_pk_add_f32 v[70:71], v[94:95], v[96:97]
	v_pk_fma_f32 v[72:73], v[8:9], v[80:81], v[74:75] neg_lo:[0,0,1] neg_hi:[0,0,1]
	v_pk_add_f32 v[74:75], v[82:83], v[98:99] neg_lo:[0,1] neg_hi:[0,1]
	v_pk_fma_f32 v[76:77], v[12:13], v[80:81], v[78:79]
	v_pk_add_f32 v[78:79], v[100:101], v[102:103]

.LBB0_462:
	s_and_b32 s0, s49, 7
	s_or_b32 s0, s0, s3
	s_lshl_b32 s1, s0, 7
	v_or_b32_e32 v0, s1, v149
	v_lshl_or_b32 v96, v0, 11, v116
	v_lshl_add_u64 v[100:101], s[16:17], 0, v[96:97]
	v_add_co_u32_e32 v12, vcc, 0x10000, v100
	s_lshl_b32 s2, s49, 4
	s_nop 0
	v_addc_co_u32_e32 v13, vcc, 0, v101, vcc
	s_and_b32 s0, s2, 0x7fffff80
	v_add_co_u32_e32 v26, vcc, 0x20000, v100
	v_or_b32_e32 v0, s0, v149
	s_nop 0
	v_addc_co_u32_e32 v27, vcc, 0, v101, vcc
	v_lshl_or_b32 v98, v0, 11, v116
	v_add_co_u32_e32 v28, vcc, 0x30000, v100
	v_mov_b32_e32 v99, v97
	s_nop 0
	v_addc_co_u32_e32 v29, vcc, 0, v101, vcc
	v_lshl_add_u64 v[102:103], s[14:15], 0, v[98:99]
	v_add_co_u32_e32 v30, vcc, s33, v102
	s_waitcnt lgkmcnt(0)
	v_addc_co_u32_e32 v31, vcc, 0, v103, vcc
	v_add_co_u32_e32 v42, vcc, s46, v102
	s_nop 0
	v_addc_co_u32_e32 v43, vcc, 0, v103, vcc
	v_add_co_u32_e32 v44, vcc, s47, v102
	s_nop 0
	v_addc_co_u32_e32 v45, vcc, 0, v103, vcc
	s_movk_i32 s2, 0x100
	s_mov_b32 s43, s27
	v_mov_b32_e32 v60, 0
	v_mov_b32_e32 v61, v97
	v_mov_b32_e32 v62, v97
	v_mov_b32_e32 v63, v97
	v_mov_b32_e32 v40, 0
	v_mov_b32_e32 v41, v97
	v_mov_b32_e32 v42, v97
	v_mov_b32_e32 v43, v97
	v_mov_b32_e32 v28, 0
	v_mov_b32_e32 v29, v97
	v_mov_b32_e32 v30, v97
	v_mov_b32_e32 v31, v97
	v_mov_b32_e32 v12, 0
	v_mov_b32_e32 v13, v97
	v_lshl_add_u64 v[104:105], v[102:103], 0, s[30:31]
	v_lshl_add_u64 v[106:107], v[102:103], 0, s[34:35]
	v_lshl_add_u64 v[108:109], v[102:103], 0, s[36:37]
	v_lshl_add_u64 v[110:111], v[100:101], 0, s[30:31]
	v_lshl_add_u64 v[112:113], v[100:101], 0, s[34:35]
	v_lshl_add_u64 v[114:115], v[100:101], 0, s[36:37]
	s_waitcnt lgkmcnt(0)
	s_barrier
	v_mov_b32_e32 v56, 0
	v_mov_b32_e32 v57, v97
	v_mov_b32_e32 v58, v97
	v_mov_b32_e32 v59, v97
	v_mov_b32_e32 v44, 0
	v_mov_b32_e32 v45, v97
	v_mov_b32_e32 v46, v97
	v_mov_b32_e32 v47, v97
	v_mov_b32_e32 v26, v97
	v_mov_b32_e32 v27, v97
	v_mov_b32_e32 v52, 0
	v_mov_b32_e32 v53, v97
	v_mov_b32_e32 v54, v97
	v_mov_b32_e32 v55, v97
	v_mov_b32_e32 v48, 0
	v_mov_b32_e32 v49, v97
	v_mov_b32_e32 v50, v97
	v_mov_b32_e32 v51, v97
	v_mov_b32_e32 v14, v97
	v_mov_b32_e32 v15, v97
	v_mov_b32_e32 v24, 0
	v_mov_b32_e32 v25, v97
	v_mov_b32_e32 v8, 0
	v_mov_b32_e32 v9, v97
	v_mov_b32_e32 v10, v97
	v_mov_b32_e32 v11, v97
	v_mov_b32_e32 v36, 0
	v_mov_b32_e32 v37, v97
	v_mov_b32_e32 v38, v97
	v_mov_b32_e32 v39, v97
	v_mov_b32_e32 v20, 0
	v_mov_b32_e32 v21, v97
	v_mov_b32_e32 v22, v97
	v_mov_b32_e32 v23, v97
	v_mov_b32_e32 v4, 0
	v_mov_b32_e32 v5, v97
	v_mov_b32_e32 v6, v97
	v_mov_b32_e32 v7, v97
	v_mov_b32_e32 v32, 0
	v_mov_b32_e32 v33, v97
	v_mov_b32_e32 v34, v97
	v_mov_b32_e32 v35, v97
	v_mov_b32_e32 v16, 0
	v_mov_b32_e32 v17, v97
	v_mov_b32_e32 v18, v97
	v_mov_b32_e32 v19, v97
	v_mov_b32_e32 v0, 0
	v_mov_b32_e32 v1, v97
	v_mov_b32_e32 v2, v97
	v_mov_b32_e32 v3, v97
	v_readlane_b32 s100, v253, 0
	v_readlane_b32 s101, v253, 1
	s_load_dwordx2 s[100:101], s[100:101], 0x160
	v_lshrrev_b32_e32 v71, 6, v146
	s_nop 0
	v_readfirstlane_b32 s44, v71
	v_lshrrev_b32_e32 v69, 3, v146
	v_and_b32_e32 v70, 7, v146
	v_xor_b32_e32 v70, v69, v70
	v_and_b32_e32 v70, 7, v70
	v_lshlrev_b32_e32 v70, 4, v70
	v_lshl_or_b32 v68, v69, 11, v70
	v_add_u32_e32 v69, 0x10000, v68
	v_add_u32_e32 v70, 0x20000, v68
	v_add_u32_e32 v71, 0x30000, v68
	s_and_b32 s98, s49, 7
	s_and_b32 s99, s69, 7
	s_lshl_b32 s99, s99, 3
	s_or_b32 s98, s98, s99
	s_lshl_b32 s98, s98, 18
	s_add_u32 s98, s98, 0x2000000
	s_lshr_b32 s99, s49, 3
	s_lshl_b32 s99, s99, 18
	s_add_u32 s99, s99, 0x8c40000
	s_lshl_b32 s44, s44, 10
	s_waitcnt lgkmcnt(0)
	s_mov_b32 m0, s99
	s_add_u32 s98, s100, s98
	s_addc_u32 s99, s101, 0
	s_add_u32 s100, s100, m0
	s_addc_u32 s101, s101, 0
	s_add_u32 m0, s44, 0x0
	s_nop 0
	global_load_lds_dwordx4 v68, s[98:99]
	s_add_u32 m0, s44, 0x1000
	s_nop 0
	global_load_lds_dwordx4 v69, s[98:99]
	s_add_u32 m0, s44, 0x2000
	s_nop 0
	global_load_lds_dwordx4 v70, s[98:99]
	s_add_u32 m0, s44, 0x3000
	s_nop 0
	global_load_lds_dwordx4 v71, s[98:99]
	s_add_u32 m0, s44, 0x8000
	s_nop 0
	global_load_lds_dwordx4 v68, s[100:101]
	s_add_u32 m0, s44, 0x9000
	s_nop 0
	global_load_lds_dwordx4 v69, s[100:101]
	s_add_u32 m0, s44, 0xa000
	s_nop 0
	global_load_lds_dwordx4 v70, s[100:101]
	s_add_u32 m0, s44, 0xb000
	s_nop 0
	global_load_lds_dwordx4 v71, s[100:101]
	s_add_u32 s98, s98, 0x80
	s_addc_u32 s99, s99, 0
	s_add_u32 s100, s100, 0x80
	s_addc_u32 s101, s101, 0
	s_waitcnt vmcnt(0)
	s_waitcnt lgkmcnt(0)
	s_barrier
.LBB0_463:
	s_add_i32 s42, s43, 2
	s_setprio 1
	ds_read_b128 v[126:129], v120 offset:32768
	ds_read_b128 v[134:137], v120 offset:34816
	ds_read_b128 v[130:133], v119
	ds_read_b128 v[138:141], v119 offset:2048
	ds_read_b128 v[164:167], v119 offset:4096
	ds_read_b128 v[168:171], v119 offset:6144
	s_waitcnt lgkmcnt(3)
	v_mfma_f32_16x16x32_bf16 v[60:63], v[126:129], v[130:133], v[60:63]
	ds_read_b128 v[172:175], v120 offset:36864
	v_mfma_f32_16x16x32_bf16 v[40:43], v[134:137], v[130:133], v[40:43]
	ds_read_b128 v[176:179], v120 offset:38912
	s_waitcnt lgkmcnt(1)
	v_mfma_f32_16x16x32_bf16 v[28:31], v[172:175], v[130:133], v[28:31]
	s_waitcnt lgkmcnt(0)
	v_mfma_f32_16x16x32_bf16 v[12:15], v[176:179], v[130:133], v[12:15]
	s_add_u32 m0, s44, 0x4000
	s_nop 0
	global_load_lds_dwordx4 v68, s[98:99]
	ds_read_b128 v[180:183], v121
	v_mfma_f32_16x16x32_bf16 v[56:59], v[126:129], v[138:141], v[56:59]
	v_mfma_f32_16x16x32_bf16 v[44:47], v[134:137], v[138:141], v[44:47]
	s_add_u32 m0, s44, 0x5000
	s_nop 0
	global_load_lds_dwordx4 v69, s[98:99]
	ds_read_b128 v[188:191], v121 offset:2048
	v_mfma_f32_16x16x32_bf16 v[24:27], v[172:175], v[138:141], v[24:27]
	v_mfma_f32_16x16x32_bf16 v[8:11], v[176:179], v[138:141], v[8:11]
	s_add_u32 m0, s44, 0x6000
	s_nop 0
	global_load_lds_dwordx4 v70, s[98:99]
	ds_read_b128 v[192:195], v121 offset:4096
	v_mfma_f32_16x16x32_bf16 v[52:55], v[126:129], v[164:167], v[52:55]
	v_mfma_f32_16x16x32_bf16 v[36:39], v[134:137], v[164:167], v[36:39]
	s_add_u32 m0, s44, 0x7000
	s_nop 0
	global_load_lds_dwordx4 v71, s[98:99]
	ds_read_b128 v[200:203], v121 offset:6144
	v_mfma_f32_16x16x32_bf16 v[20:23], v[172:175], v[164:167], v[20:23]
	v_mfma_f32_16x16x32_bf16 v[4:7], v[176:179], v[164:167], v[4:7]
	s_add_u32 m0, s44, 0xc000
	s_nop 0
	global_load_lds_dwordx4 v68, s[100:101]
	ds_read_b128 v[204:207], v122 offset:32768
	v_mfma_f32_16x16x32_bf16 v[48:51], v[126:129], v[168:171], v[48:51]
	v_mfma_f32_16x16x32_bf16 v[32:35], v[134:137], v[168:171], v[32:35]
	s_add_u32 m0, s44, 0xd000
	s_nop 0
	global_load_lds_dwordx4 v69, s[100:101]
	ds_read_b128 v[134:137], v122 offset:34816
	v_mfma_f32_16x16x32_bf16 v[16:19], v[172:175], v[168:171], v[16:19]
	v_mfma_f32_16x16x32_bf16 v[0:3], v[176:179], v[168:171], v[0:3]
	s_add_u32 m0, s44, 0xe000
	s_nop 0
	global_load_lds_dwordx4 v70, s[100:101]
	ds_read_b128 v[172:175], v122 offset:36864
	s_waitcnt lgkmcnt(2)
	v_mfma_f32_16x16x32_bf16 v[60:63], v[204:207], v[180:183], v[60:63]
	s_waitcnt lgkmcnt(1)
	v_mfma_f32_16x16x32_bf16 v[40:43], v[134:137], v[180:183], v[40:43]
	s_add_u32 m0, s44, 0xf000
	s_nop 0
	global_load_lds_dwordx4 v71, s[100:101]
	s_add_u32 s98, s98, 0x80
	s_addc_u32 s99, s99, 0
	s_add_u32 s100, s100, 0x80
	s_addc_u32 s101, s101, 0
	ds_read_b128 v[208:211], v122 offset:38912
	s_waitcnt lgkmcnt(1)
	v_mfma_f32_16x16x32_bf16 v[28:31], v[172:175], v[180:183], v[28:31]
	s_waitcnt lgkmcnt(0)
	v_mfma_f32_16x16x32_bf16 v[12:15], v[208:211], v[180:183], v[12:15]
	v_mfma_f32_16x16x32_bf16 v[56:59], v[204:207], v[188:191], v[56:59]
	v_mfma_f32_16x16x32_bf16 v[44:47], v[134:137], v[188:191], v[44:47]
	v_mfma_f32_16x16x32_bf16 v[24:27], v[172:175], v[188:191], v[24:27]
	v_mfma_f32_16x16x32_bf16 v[8:11], v[208:211], v[188:191], v[8:11]
	v_mfma_f32_16x16x32_bf16 v[52:55], v[204:207], v[192:195], v[52:55]
	v_mfma_f32_16x16x32_bf16 v[36:39], v[134:137], v[192:195], v[36:39]
	v_mfma_f32_16x16x32_bf16 v[20:23], v[172:175], v[192:195], v[20:23]
	v_mfma_f32_16x16x32_bf16 v[4:7], v[208:211], v[192:195], v[4:7]
	v_mfma_f32_16x16x32_bf16 v[48:51], v[204:207], v[200:203], v[48:51]
	v_mfma_f32_16x16x32_bf16 v[32:35], v[134:137], v[200:203], v[32:35]
	v_mfma_f32_16x16x32_bf16 v[16:19], v[172:175], v[200:203], v[16:19]
	v_mfma_f32_16x16x32_bf16 v[0:3], v[208:211], v[200:203], v[0:3]
	s_setprio 0
	s_waitcnt vmcnt(0) lgkmcnt(0)
	s_barrier
	s_setprio 1
	ds_read_b128 v[84:87], v120 offset:49152
	ds_read_b128 v[88:91], v120 offset:51200
	ds_read_b128 v[64:67], v119 offset:16384
	ds_read_b128 v[72:75], v119 offset:18432
	ds_read_b128 v[76:79], v119 offset:20480
	ds_read_b128 v[92:95], v119 offset:22528
	s_waitcnt lgkmcnt(3)
	v_mfma_f32_16x16x32_bf16 v[60:63], v[84:87], v[64:67], v[60:63]
	ds_read_b128 v[134:137], v120 offset:53248
	v_mfma_f32_16x16x32_bf16 v[40:43], v[88:91], v[64:67], v[40:43]
	ds_read_b128 v[172:175], v120 offset:55296
	s_waitcnt lgkmcnt(1)
	v_mfma_f32_16x16x32_bf16 v[28:31], v[134:137], v[64:67], v[28:31]
	s_waitcnt lgkmcnt(0)
	v_mfma_f32_16x16x32_bf16 v[12:15], v[172:175], v[64:67], v[12:15]
	s_add_u32 m0, s44, 0x0
	s_nop 0
	global_load_lds_dwordx4 v68, s[98:99]
	ds_read_b128 v[180:183], v121 offset:16384
	v_mfma_f32_16x16x32_bf16 v[56:59], v[84:87], v[72:75], v[56:59]
	v_mfma_f32_16x16x32_bf16 v[44:47], v[88:91], v[72:75], v[44:47]
	s_add_u32 m0, s44, 0x1000
	s_nop 0
	global_load_lds_dwordx4 v69, s[98:99]
	ds_read_b128 v[188:191], v121 offset:18432
	v_mfma_f32_16x16x32_bf16 v[24:27], v[134:137], v[72:75], v[24:27]
	v_mfma_f32_16x16x32_bf16 v[8:11], v[172:175], v[72:75], v[8:11]
	s_add_u32 m0, s44, 0x2000
	s_nop 0
	global_load_lds_dwordx4 v70, s[98:99]
	ds_read_b128 v[192:195], v121 offset:20480
	v_mfma_f32_16x16x32_bf16 v[52:55], v[84:87], v[76:79], v[52:55]
	v_mfma_f32_16x16x32_bf16 v[36:39], v[88:91], v[76:79], v[36:39]
	s_add_u32 m0, s44, 0x3000
	s_nop 0
	global_load_lds_dwordx4 v71, s[98:99]
	ds_read_b128 v[200:203], v121 offset:22528
	v_mfma_f32_16x16x32_bf16 v[20:23], v[134:137], v[76:79], v[20:23]
	v_mfma_f32_16x16x32_bf16 v[4:7], v[172:175], v[76:79], v[4:7]
	s_add_u32 m0, s44, 0x8000
	s_nop 0
	global_load_lds_dwordx4 v68, s[100:101]
	ds_read_b128 v[204:207], v122 offset:49152
	v_mfma_f32_16x16x32_bf16 v[48:51], v[84:87], v[92:95], v[48:51]
	v_mfma_f32_16x16x32_bf16 v[32:35], v[88:91], v[92:95], v[32:35]
	s_add_u32 m0, s44, 0x9000
	s_nop 0
	global_load_lds_dwordx4 v69, s[100:101]
	ds_read_b128 v[208:211], v122 offset:51200
	v_mfma_f32_16x16x32_bf16 v[16:19], v[134:137], v[92:95], v[16:19]
	v_mfma_f32_16x16x32_bf16 v[0:3], v[172:175], v[92:95], v[0:3]
	s_add_u32 m0, s44, 0xa000
	s_nop 0
	global_load_lds_dwordx4 v70, s[100:101]
	ds_read_b128 v[134:137], v122 offset:53248
	s_waitcnt lgkmcnt(2)
	v_mfma_f32_16x16x32_bf16 v[60:63], v[204:207], v[180:183], v[60:63]
	s_waitcnt lgkmcnt(1)
	v_mfma_f32_16x16x32_bf16 v[40:43], v[208:211], v[180:183], v[40:43]
	s_add_u32 m0, s44, 0xb000
	s_nop 0
	global_load_lds_dwordx4 v71, s[100:101]
	s_add_u32 s98, s98, 0x80
	s_addc_u32 s99, s99, 0
	s_add_u32 s100, s100, 0x80
	s_addc_u32 s101, s101, 0
	ds_read_b128 v[172:175], v122 offset:55296
	s_waitcnt lgkmcnt(1)
	v_mfma_f32_16x16x32_bf16 v[28:31], v[134:137], v[180:183], v[28:31]
	s_waitcnt lgkmcnt(0)
	v_mfma_f32_16x16x32_bf16 v[12:15], v[172:175], v[180:183], v[12:15]
	v_mfma_f32_16x16x32_bf16 v[56:59], v[204:207], v[188:191], v[56:59]
	v_mfma_f32_16x16x32_bf16 v[44:47], v[208:211], v[188:191], v[44:47]
	v_mfma_f32_16x16x32_bf16 v[24:27], v[134:137], v[188:191], v[24:27]
	v_mfma_f32_16x16x32_bf16 v[8:11], v[172:175], v[188:191], v[8:11]
	v_mfma_f32_16x16x32_bf16 v[52:55], v[204:207], v[192:195], v[52:55]
	v_mfma_f32_16x16x32_bf16 v[36:39], v[208:211], v[192:195], v[36:39]
	v_mfma_f32_16x16x32_bf16 v[20:23], v[134:137], v[192:195], v[20:23]
	v_mfma_f32_16x16x32_bf16 v[4:7], v[172:175], v[192:195], v[4:7]
	v_mfma_f32_16x16x32_bf16 v[48:51], v[204:207], v[200:203], v[48:51]
	v_mfma_f32_16x16x32_bf16 v[32:35], v[208:211], v[200:203], v[32:35]
	v_mfma_f32_16x16x32_bf16 v[16:19], v[134:137], v[200:203], v[16:19]
	v_mfma_f32_16x16x32_bf16 v[0:3], v[172:175], v[200:203], v[0:3]
	s_setprio 0
	s_mov_b32 s43, s42
	s_waitcnt vmcnt(0) lgkmcnt(0)
	s_barrier
	s_cmp_lt_u32 s43, 16
	s_cbranch_scc1 .LBB0_463
	s_waitcnt vmcnt(6)
	v_add_u32_e32 v70, s1, v118
	s_addk_i32 s1, 0xf000
	s_ashr_i32 s1, s1, 10
	s_add_i32 s1, s1, 1
	s_and_b64 s[42:43], s[20:21], exec
	s_cselect_b32 s1, 0, s1
	s_mul_i32 s26, s1, 0x3000
	s_mul_hi_i32 s2, s1, 0x3000
	s_add_u32 s42, s4, s26
	s_addc_u32 s2, s5, s2
	v_or_b32_e32 v98, v70, v148
	s_add_u32 s44, s42, 0x2000
	s_addc_u32 s45, s2, 0
	s_add_i32 s1, s1, 5
	s_add_i32 s26, s26, 0xf000
	v_add_u32_e32 v66, 0xfffff000, v98
	v_mov_b32_e32 v67, v97
	s_mul_hi_u32 s1, s1, 0x3000
	s_add_u32 s2, s4, s26
	s_waitcnt vmcnt(5)
	v_lshlrev_b32_e32 v72, 12, v98
	v_mov_b32_e32 v73, v97
	v_lshlrev_b64 v[66:67], 12, v[66:67]
	s_addc_u32 s1, s5, s1
	v_or_b32_e32 v96, s0, v123
	v_lshl_add_u64 v[64:65], s[8:9], 0, v[72:73]
	v_lshl_add_u64 v[66:67], s[10:11], 0, v[66:67]
	v_cmp_gt_u32_e32 vcc, s48, v70
	s_add_u32 s42, s2, 0x1000
	s_waitcnt vmcnt(0)
	v_lshlrev_b64 v[92:93], 2, v[96:97]
	v_cndmask_b32_e32 v65, v67, v65, vcc
	v_cndmask_b32_e32 v64, v66, v64, vcc
	v_lshl_add_u64 v[68:69], s[44:45], 0, v[92:93]
	v_lshl_add_u64 v[76:77], v[64:65], 0, v[92:93]
	s_addc_u32 s43, s1, 0
	global_load_dwordx4 v[64:67], v[76:77], off nt
	global_load_dwordx4 v[100:103], v[68:69], off
	v_lshl_add_u64 v[68:69], s[42:43], 0, v[92:93]
	global_load_dwordx4 v[82:85], v[68:69], off
	v_lshl_add_u64 v[68:69], s[28:29], 0, v[92:93]
	global_load_dwordx4 v[86:89], v[68:69], off
	v_lshlrev_b32_e32 v99, 10, v98
	v_mov_b32_e32 v91, v97
	v_mov_b32_e32 v81, v97
	v_lshl_add_u64 v[70:71], s[12:13], 0, v[92:93]
	v_add_u32_e32 v80, 0xfffff010, v98
	v_or_b32_e32 v90, 0x4000, v99
	v_lshl_add_u64 v[78:79], v[70:71], 0, v[72:73]
	v_lshlrev_b64 v[80:81], 12, v[80:81]
	v_lshlrev_b64 v[72:73], 2, v[90:91]
	v_lshl_add_u64 v[80:81], s[10:11], 0, v[80:81]
	v_lshl_add_u64 v[106:107], s[8:9], 0, v[72:73]
	v_mov_b32_e32 v75, v97
	v_lshlrev_b32_e32 v74, 1, v96
	v_cndmask_b32_e32 v81, v81, v107, vcc
	v_cndmask_b32_e32 v80, v80, v106, vcc
	v_mov_b32_e32 v95, v97
	v_lshl_add_u64 v[104:105], s[22:23], 0, v[74:75]
	v_lshlrev_b32_e32 v94, 11, v98
	v_lshl_add_u64 v[74:75], v[104:105], 0, v[94:95]
	v_lshl_add_u64 v[80:81], v[80:81], 0, v[92:93]
	v_lshl_add_u64 v[94:95], s[22:23], 0, v[94:95]
	s_waitcnt vmcnt(2)
	v_pk_fma_f32 v[60:61], v[60:61], v[100:101], v[64:65]
	v_pk_fma_f32 v[62:63], v[62:63], v[102:103], v[66:67]
	s_waitcnt vmcnt(1)
	v_pk_add_f32 v[64:65], v[82:83], 1.0 op_sel_hi:[1,0]
	v_pk_add_f32 v[66:67], v[84:85], 1.0 op_sel_hi:[1,0]
	s_waitcnt vmcnt(0)
	v_pk_mul_f32 v[106:107], v[86:87], v[64:65]
	v_pk_mul_f32 v[108:109], v[88:89], v[66:67]
	v_pk_mul_f32 v[64:65], v[106:107], v[60:61]
	v_pk_mul_f32 v[66:67], v[108:109], v[62:63]
	v_cvt_pk_bf16_f32 v64, v64, v65
	v_cvt_pk_bf16_f32 v65, v66, v67
	global_store_dwordx4 v[78:79], v[60:63], off
	global_store_dwordx2 v[74:75], v[64:65], off
	global_load_dwordx4 v[64:67], v[80:81], off nt
	v_mov_b32_e32 v75, v97
	v_mov_b32_e32 v85, v97
	v_add_u32_e32 v84, 0xfffff020, v98
	v_or_b32_e32 v74, 0x8000, v99
	v_lshlrev_b64 v[86:87], 12, v[84:85]
	v_lshlrev_b64 v[84:85], 2, v[74:75]
	v_mov_b32_e32 v83, v97
	v_lshlrev_b32_e32 v82, 1, v90
	v_lshl_add_u64 v[86:87], s[10:11], 0, v[86:87]
	v_lshl_add_u64 v[110:111], s[8:9], 0, v[84:85]
	v_lshl_add_u64 v[88:89], v[70:71], 0, v[72:73]
	v_lshl_add_u64 v[90:91], v[104:105], 0, v[82:83]
	v_cndmask_b32_e32 v87, v87, v111, vcc
	v_cndmask_b32_e32 v86, v86, v110, vcc
	v_lshl_add_u64 v[86:87], v[86:87], 0, v[92:93]
	v_mov_b32_e32 v111, v97
	v_add_u32_e32 v110, 0xfffff030, v98
	v_lshlrev_b64 v[110:111], 12, v[110:111]
	v_lshl_add_u64 v[110:111], s[10:11], 0, v[110:111]
	v_lshl_add_u64 v[112:113], v[70:71], 0, v[84:85]
	v_pk_mul_f32 v[60:61], v[60:61], v[60:61]
	v_pk_mul_f32 v[62:63], v[62:63], v[62:63]
	v_add_f32_e32 v60, v61, v60
	v_add_f32_e32 v60, v62, v60
	s_waitcnt vmcnt(0)
	v_pk_fma_f32 v[56:57], v[56:57], v[100:101], v[64:65]
	v_pk_fma_f32 v[58:59], v[58:59], v[102:103], v[66:67]
	v_pk_mul_f32 v[64:65], v[106:107], v[56:57]
	v_pk_mul_f32 v[66:67], v[108:109], v[58:59]
	v_cvt_pk_bf16_f32 v64, v64, v65
	v_cvt_pk_bf16_f32 v65, v66, v67
	global_store_dwordx4 v[88:89], v[56:59], off
	global_store_dwordx2 v[90:91], v[64:65], off
	global_load_dwordx4 v[64:67], v[86:87], off nt
	v_mov_b32_e32 v89, v97
	v_or_b32_e32 v88, 0xc000, v99
	v_lshlrev_b32_e32 v90, 1, v74
	v_lshlrev_b64 v[74:75], 2, v[88:89]
	v_mov_b32_e32 v91, v97
	v_lshl_add_u64 v[126:127], s[8:9], 0, v[74:75]
	v_lshl_add_u64 v[114:115], v[104:105], 0, v[90:91]
	v_cndmask_b32_e32 v111, v111, v127, vcc
	v_cndmask_b32_e32 v110, v110, v126, vcc
	v_lshl_add_u64 v[92:93], v[110:111], 0, v[92:93]
	v_lshlrev_b32_e32 v88, 1, v88
	v_lshl_add_u64 v[104:105], v[104:105], 0, v[88:89]
	s_waitcnt vmcnt(0)
	v_pk_fma_f32 v[52:53], v[52:53], v[100:101], v[64:65]
	v_pk_fma_f32 v[54:55], v[54:55], v[102:103], v[66:67]
	v_pk_mul_f32 v[64:65], v[106:107], v[52:53]
	v_pk_mul_f32 v[66:67], v[108:109], v[54:55]
	v_cvt_pk_bf16_f32 v64, v64, v65
	v_cvt_pk_bf16_f32 v65, v66, v67
	global_store_dwordx4 v[112:113], v[52:55], off
	global_store_dwordx2 v[114:115], v[64:65], off
	global_load_dwordx4 v[64:67], v[92:93], off nt
	v_mov_b32_e32 v113, v97
	v_or_b32_e32 v112, 16, v96
	v_lshl_add_u64 v[114:115], v[70:71], 0, v[74:75]
	v_lshlrev_b64 v[110:111], 2, v[112:113]
	v_lshl_add_u64 v[126:127], s[44:45], 0, v[110:111]
	v_lshlrev_b32_e32 v112, 1, v112
	s_waitcnt vmcnt(0)
	v_pk_fma_f32 v[48:49], v[48:49], v[100:101], v[64:65]
	v_pk_fma_f32 v[50:51], v[50:51], v[102:103], v[66:67]
	v_pk_mul_f32 v[64:65], v[106:107], v[48:49]
	v_pk_mul_f32 v[66:67], v[108:109], v[50:51]
	v_cvt_pk_bf16_f32 v64, v64, v65
	v_cvt_pk_bf16_f32 v65, v66, v67
	global_store_dwordx4 v[114:115], v[48:51], off
	global_store_dwordx2 v[104:105], v[64:65], off
	global_load_dwordx4 v[64:67], v[76:77], off offset:64 nt
	s_nop 0
	global_load_dwordx4 v[100:103], v[126:127], off
	v_lshl_add_u64 v[104:105], s[42:43], 0, v[110:111]
	global_load_dwordx4 v[104:107], v[104:105], off
	s_nop 0
	global_load_dwordx4 v[108:111], v[68:69], off offset:64
	v_lshl_add_u64 v[114:115], v[94:95], 0, v[112:113]
	s_waitcnt vmcnt(2)
	v_pk_fma_f32 v[64:65], v[40:41], v[100:101], v[64:65]
	v_pk_fma_f32 v[66:67], v[42:43], v[102:103], v[66:67]
	s_waitcnt vmcnt(1)
	v_pk_add_f32 v[40:41], v[104:105], 1.0 op_sel_hi:[1,0]
	v_pk_add_f32 v[42:43], v[106:107], 1.0 op_sel_hi:[1,0]
	s_waitcnt vmcnt(0)
	v_pk_mul_f32 v[104:105], v[108:109], v[40:41]
	v_pk_mul_f32 v[106:107], v[110:111], v[42:43]
	v_pk_mul_f32 v[40:41], v[104:105], v[64:65]
	v_pk_mul_f32 v[42:43], v[106:107], v[66:67]
	v_cvt_pk_bf16_f32 v40, v40, v41
	v_cvt_pk_bf16_f32 v41, v42, v43
	global_store_dwordx4 v[78:79], v[64:67], off offset:64
	global_store_dwordx2 v[114:115], v[40:41], off
	global_load_dwordx4 v[40:43], v[80:81], off offset:64 nt
	v_lshl_add_u64 v[108:109], v[70:71], 0, 64
	v_lshl_add_u64 v[110:111], s[22:23], 0, v[112:113]
	v_lshl_add_u64 v[112:113], v[108:109], 0, v[72:73]
	v_lshl_add_u64 v[114:115], v[110:111], 0, v[82:83]
	s_waitcnt vmcnt(0)
	v_pk_fma_f32 v[40:41], v[44:45], v[100:101], v[40:41]
	v_pk_fma_f32 v[42:43], v[46:47], v[102:103], v[42:43]
	v_pk_mul_f32 v[44:45], v[104:105], v[40:41]
	v_pk_mul_f32 v[46:47], v[106:107], v[42:43]
	v_cvt_pk_bf16_f32 v44, v44, v45
	v_cvt_pk_bf16_f32 v45, v46, v47
	global_store_dwordx4 v[112:113], v[40:43], off
	global_store_dwordx2 v[114:115], v[44:45], off
	global_load_dwordx4 v[44:47], v[86:87], off offset:64 nt
	v_lshl_add_u64 v[112:113], v[108:109], 0, v[84:85]
	v_lshl_add_u64 v[114:115], v[110:111], 0, v[90:91]
	v_lshl_add_u64 v[108:109], v[108:109], 0, v[74:75]
	v_lshl_add_u64 v[110:111], v[110:111], 0, v[88:89]
	s_waitcnt vmcnt(0)
	v_pk_fma_f32 v[36:37], v[36:37], v[100:101], v[44:45]
	v_pk_fma_f32 v[38:39], v[38:39], v[102:103], v[46:47]
	v_pk_mul_f32 v[44:45], v[104:105], v[36:37]
	v_pk_mul_f32 v[46:47], v[106:107], v[38:39]
	v_cvt_pk_bf16_f32 v44, v44, v45
	v_cvt_pk_bf16_f32 v45, v46, v47
	global_store_dwordx4 v[112:113], v[36:39], off
	global_store_dwordx2 v[114:115], v[44:45], off
	global_load_dwordx4 v[44:47], v[92:93], off offset:64 nt
	v_mov_b32_e32 v113, v97
	v_or_b32_e32 v112, 32, v96
	v_lshlrev_b64 v[114:115], 2, v[112:113]
	v_lshl_add_u64 v[126:127], s[44:45], 0, v[114:115]
	v_lshlrev_b32_e32 v112, 1, v112
	v_or_b32_e32 v96, 48, v96
	s_waitcnt vmcnt(0)
	v_pk_fma_f32 v[32:33], v[32:33], v[100:101], v[44:45]
	v_pk_fma_f32 v[34:35], v[34:35], v[102:103], v[46:47]
	v_pk_mul_f32 v[44:45], v[104:105], v[32:33]
	v_pk_mul_f32 v[46:47], v[106:107], v[34:35]
	v_cvt_pk_bf16_f32 v44, v44, v45
	v_cvt_pk_bf16_f32 v45, v46, v47
	global_store_dwordx4 v[108:109], v[32:35], off
	global_store_dwordx2 v[110:111], v[44:45], off
	global_load_dwordx4 v[44:47], v[76:77], off offset:128 nt
	s_nop 0
	global_load_dwordx4 v[100:103], v[126:127], off
	v_lshl_add_u64 v[104:105], s[42:43], 0, v[114:115]
	global_load_dwordx4 v[104:107], v[104:105], off
	s_nop 0
	global_load_dwordx4 v[108:111], v[68:69], off offset:128
	v_lshl_add_u64 v[114:115], v[94:95], 0, v[112:113]
	s_waitcnt vmcnt(2)
	v_pk_fma_f32 v[28:29], v[28:29], v[100:101], v[44:45]
	v_pk_fma_f32 v[30:31], v[30:31], v[102:103], v[46:47]
	s_waitcnt vmcnt(1)
	v_pk_add_f32 v[44:45], v[104:105], 1.0 op_sel_hi:[1,0]
	v_pk_add_f32 v[46:47], v[106:107], 1.0 op_sel_hi:[1,0]
	s_waitcnt vmcnt(0)
	v_pk_mul_f32 v[104:105], v[108:109], v[44:45]
	v_pk_mul_f32 v[106:107], v[110:111], v[46:47]
	v_pk_mul_f32 v[44:45], v[104:105], v[28:29]
	v_pk_mul_f32 v[46:47], v[106:107], v[30:31]
	v_cvt_pk_bf16_f32 v44, v44, v45
	v_cvt_pk_bf16_f32 v45, v46, v47
	global_store_dwordx4 v[78:79], v[28:31], off offset:128
	global_store_dwordx2 v[114:115], v[44:45], off
	global_load_dwordx4 v[44:47], v[80:81], off offset:128 nt
	v_lshl_add_u64 v[108:109], v[70:71], 0, s[38:39]
	v_lshl_add_u64 v[110:111], s[22:23], 0, v[112:113]
	v_lshl_add_u64 v[112:113], v[108:109], 0, v[72:73]
	v_lshl_add_u64 v[114:115], v[110:111], 0, v[82:83]
	v_pk_mul_f32 v[28:29], v[28:29], v[28:29]
	v_pk_mul_f32 v[30:31], v[30:31], v[30:31]
	v_add_f32_e32 v28, v29, v28
	v_add_f32_e32 v28, v30, v28
	v_add_f32_e32 v28, v31, v28
	s_waitcnt vmcnt(0)
	v_pk_fma_f32 v[24:25], v[24:25], v[100:101], v[44:45]
	v_pk_fma_f32 v[26:27], v[26:27], v[102:103], v[46:47]
	v_pk_mul_f32 v[44:45], v[104:105], v[24:25]
	v_pk_mul_f32 v[46:47], v[106:107], v[26:27]
	v_cvt_pk_bf16_f32 v44, v44, v45
	v_cvt_pk_bf16_f32 v45, v46, v47
	global_store_dwordx4 v[112:113], v[24:27], off
	global_store_dwordx2 v[114:115], v[44:45], off
	global_load_dwordx4 v[44:47], v[86:87], off offset:128 nt
	v_lshl_add_u64 v[112:113], v[108:109], 0, v[84:85]
	v_lshl_add_u64 v[114:115], v[110:111], 0, v[90:91]
	v_lshl_add_u64 v[108:109], v[108:109], 0, v[74:75]
	v_lshl_add_u64 v[110:111], v[110:111], 0, v[88:89]
	s_waitcnt vmcnt(0)
	v_pk_fma_f32 v[20:21], v[20:21], v[100:101], v[44:45]
	v_pk_fma_f32 v[22:23], v[22:23], v[102:103], v[46:47]
	v_pk_mul_f32 v[44:45], v[104:105], v[20:21]
	v_pk_mul_f32 v[46:47], v[106:107], v[22:23]
	v_cvt_pk_bf16_f32 v44, v44, v45
	v_cvt_pk_bf16_f32 v45, v46, v47
	global_store_dwordx4 v[112:113], v[20:23], off
	global_store_dwordx2 v[114:115], v[44:45], off
	global_load_dwordx4 v[44:47], v[92:93], off offset:128 nt
	v_lshlrev_b64 v[112:113], 2, v[96:97]
	v_lshl_add_u64 v[114:115], s[44:45], 0, v[112:113]
	v_lshlrev_b32_e32 v96, 1, v96
	s_waitcnt vmcnt(0)
	v_pk_fma_f32 v[16:17], v[16:17], v[100:101], v[44:45]
	v_pk_fma_f32 v[18:19], v[18:19], v[102:103], v[46:47]
	v_pk_mul_f32 v[44:45], v[104:105], v[16:17]
	v_pk_mul_f32 v[46:47], v[106:107], v[18:19]
	v_cvt_pk_bf16_f32 v44, v44, v45
	v_cvt_pk_bf16_f32 v45, v46, v47
	global_store_dwordx4 v[108:109], v[16:19], off
	global_store_dwordx2 v[110:111], v[44:45], off
	global_load_dwordx4 v[44:47], v[76:77], off offset:192 nt
	s_nop 0
	global_load_dwordx4 v[100:103], v[114:115], off
	v_lshl_add_u64 v[76:77], s[42:43], 0, v[112:113]
	global_load_dwordx4 v[104:107], v[76:77], off
	global_load_dwordx4 v[108:111], v[68:69], off offset:192
	v_lshl_add_u64 v[68:69], v[94:95], 0, v[96:97]
	s_waitcnt vmcnt(2)
	v_pk_fma_f32 v[12:13], v[12:13], v[100:101], v[44:45]
	v_pk_fma_f32 v[14:15], v[14:15], v[102:103], v[46:47]
	s_waitcnt vmcnt(1)
	v_pk_add_f32 v[44:45], v[104:105], 1.0 op_sel_hi:[1,0]
	v_pk_add_f32 v[46:47], v[106:107], 1.0 op_sel_hi:[1,0]
	s_waitcnt vmcnt(0)
	v_pk_mul_f32 v[76:77], v[108:109], v[44:45]
	v_pk_mul_f32 v[94:95], v[110:111], v[46:47]
	v_pk_mul_f32 v[44:45], v[76:77], v[12:13]
	v_pk_mul_f32 v[46:47], v[94:95], v[14:15]
	v_cvt_pk_bf16_f32 v44, v44, v45
	v_cvt_pk_bf16_f32 v45, v46, v47
	global_store_dwordx4 v[78:79], v[12:15], off offset:192
	global_store_dwordx2 v[68:69], v[44:45], off
	global_load_dwordx4 v[44:47], v[80:81], off offset:192 nt
	v_lshl_add_u64 v[68:69], v[70:71], 0, s[40:41]
	v_lshl_add_u64 v[70:71], s[22:23], 0, v[96:97]
	v_lshl_add_u64 v[72:73], v[68:69], 0, v[72:73]
	v_lshl_add_u64 v[78:79], v[70:71], 0, v[82:83]
	v_pk_mul_f32 v[12:13], v[12:13], v[12:13]
	v_pk_mul_f32 v[14:15], v[14:15], v[14:15]
	v_add_f32_e32 v12, v13, v12
	v_add_f32_e32 v12, v14, v12
	v_add_f32_e32 v12, v15, v12
	v_lshlrev_b32_e32 v96, 2, v98
	s_waitcnt vmcnt(0)
	v_pk_fma_f32 v[8:9], v[8:9], v[100:101], v[44:45]
	v_pk_fma_f32 v[10:11], v[10:11], v[102:103], v[46:47]
	v_pk_mul_f32 v[44:45], v[76:77], v[8:9]
	v_pk_mul_f32 v[46:47], v[94:95], v[10:11]
	v_cvt_pk_bf16_f32 v44, v44, v45
	v_cvt_pk_bf16_f32 v45, v46, v47
	global_store_dwordx4 v[72:73], v[8:11], off
	global_store_dwordx2 v[78:79], v[44:45], off
	global_load_dwordx4 v[44:47], v[86:87], off offset:192 nt
	v_lshl_add_u64 v[72:73], v[68:69], 0, v[84:85]
	v_lshl_add_u64 v[78:79], v[70:71], 0, v[90:91]
	s_waitcnt vmcnt(0)
	v_pk_fma_f32 v[4:5], v[4:5], v[100:101], v[44:45]
	v_pk_fma_f32 v[6:7], v[6:7], v[102:103], v[46:47]
	v_pk_mul_f32 v[44:45], v[76:77], v[4:5]
	v_pk_mul_f32 v[46:47], v[94:95], v[6:7]
	v_cvt_pk_bf16_f32 v44, v44, v45
	v_cvt_pk_bf16_f32 v45, v46, v47
	global_store_dwordx4 v[72:73], v[4:7], off
	global_store_dwordx2 v[78:79], v[44:45], off
	global_load_dwordx4 v[44:47], v[92:93], off offset:192 nt
	v_add_f32_e32 v72, v63, v60
	v_pk_mul_f32 v[60:61], v[64:65], v[64:65]
	v_pk_mul_f32 v[62:63], v[66:67], v[66:67]
	v_add_f32_e32 v60, v61, v60
	v_add_f32_e32 v60, v62, v60
	v_add_f32_e32 v60, v63, v60
	v_add_f32_e32 v60, v72, v60
	v_add_f32_e32 v28, v60, v28
	v_add_f32_e32 v14, v28, v12
	ds_bpermute_b32 v15, v124, v14
	v_lshl_add_u64 v[12:13], v[68:69], 0, v[74:75]
	v_lshl_add_u64 v[28:29], v[70:71], 0, v[88:89]
	s_waitcnt lgkmcnt(0)
	v_add_f32_e32 v14, v14, v15
	ds_bpermute_b32 v15, v125, v14
	s_waitcnt vmcnt(0)
	v_pk_fma_f32 v[0:1], v[0:1], v[100:101], v[44:45]
	v_pk_fma_f32 v[2:3], v[2:3], v[102:103], v[46:47]
	global_store_dwordx4 v[12:13], v[0:3], off
	v_pk_mul_f32 v[12:13], v[76:77], v[0:1]
	v_pk_mul_f32 v[30:31], v[94:95], v[2:3]
	v_cvt_pk_bf16_f32 v12, v12, v13
	v_cvt_pk_bf16_f32 v13, v30, v31
	global_store_dwordx2 v[28:29], v[12:13], off
	v_lshl_add_u64 v[12:13], s[24:25], 0, v[96:97]
	s_and_saveexec_b64 s[42:43], s[6:7]
	s_cbranch_execz .LBB0_466
	s_waitcnt lgkmcnt(0)
	v_add_f32_e32 v14, v14, v15
	global_atomic_add_f32 v[12:13], v14, off

.LBB0_527:
	s_and_b32 s0, s43, 7
	s_or_b32 s0, s0, s3
	s_lshl_b32 s44, s0, 7
	v_or_b32_e32 v0, s44, v149
	v_lshl_or_b32 v160, v0, 11, v159
	v_lshl_add_u64 v[30:31], s[22:23], 0, v[160:161]
	v_add_co_u32_e32 v4, vcc, 0x10000, v30
	s_lshl_b32 s1, s43, 4
	s_nop 0
	v_addc_co_u32_e32 v5, vcc, 0, v31, vcc
	s_and_b32 s0, s1, 0x7fffff80
	v_add_co_u32_e32 v12, vcc, 0x20000, v30
	v_or_b32_e32 v0, s0, v149
	s_nop 0
	v_addc_co_u32_e32 v13, vcc, 0, v31, vcc
	v_lshl_or_b32 v24, v0, 11, v159
	v_add_co_u32_e32 v16, vcc, 0x30000, v30
	v_mov_b32_e32 v25, v161
	s_nop 0
	v_addc_co_u32_e32 v17, vcc, 0, v31, vcc
	v_lshl_add_u64 v[52:53], s[16:17], 0, v[24:25]
	v_add_co_u32_e32 v18, vcc, s38, v52
	s_nop 0
	v_addc_co_u32_e32 v19, vcc, 0, v53, vcc
	v_add_co_u32_e32 v28, vcc, s39, v52
	s_nop 0
	v_addc_co_u32_e32 v29, vcc, 0, v53, vcc
	v_add_co_u32_e32 v58, vcc, s40, v52
	s_nop 0
	v_addc_co_u32_e32 v59, vcc, 0, v53, vcc
	s_nop 0
	s_nop 0
	s_nop 0
	s_movk_i32 s1, 0x100
	s_mov_b32 s6, s37
	v_mov_b32_e32 v8, 0
	v_mov_b32_e32 v9, v161
	v_mov_b32_e32 v10, v161
	v_mov_b32_e32 v11, v161
	v_mov_b32_e32 v26, 0
	v_mov_b32_e32 v27, v161
	v_mov_b32_e32 v28, v161
	v_mov_b32_e32 v29, v161
	v_mov_b32_e32 v16, 0
	v_mov_b32_e32 v17, v161
	v_mov_b32_e32 v18, v161
	v_mov_b32_e32 v19, v161
	v_mov_b32_e32 v60, 0
	v_mov_b32_e32 v61, v161
	v_lshl_add_u64 v[58:59], v[52:53], 0, s[14:15]
	v_lshl_add_u64 v[104:105], v[52:53], 0, s[30:31]
	v_lshl_add_u64 v[106:107], v[52:53], 0, s[34:35]
	v_lshl_add_u64 v[108:109], v[30:31], 0, s[14:15]
	v_lshl_add_u64 v[110:111], v[30:31], 0, s[30:31]
	v_lshl_add_u64 v[112:113], v[30:31], 0, s[34:35]
	s_barrier
	v_mov_b32_e32 v88, 0
	v_mov_b32_e32 v89, v161
	v_mov_b32_e32 v90, v161
	v_mov_b32_e32 v91, v161
	v_mov_b32_e32 v76, 0
	v_mov_b32_e32 v77, v161
	v_mov_b32_e32 v78, v161
	v_mov_b32_e32 v79, v161
	v_mov_b32_e32 v80, 0
	v_mov_b32_e32 v81, v161
	v_mov_b32_e32 v82, v161
	v_mov_b32_e32 v83, v161
	v_mov_b32_e32 v84, 0
	v_mov_b32_e32 v85, v161
	v_mov_b32_e32 v86, v161
	v_mov_b32_e32 v87, v161
	v_mov_b32_e32 v74, v161
	v_mov_b32_e32 v75, v161
	v_mov_b32_e32 v62, v161
	v_mov_b32_e32 v63, v161
	v_mov_b32_e32 v36, 0
	v_mov_b32_e32 v37, v161
	v_mov_b32_e32 v38, v161
	v_mov_b32_e32 v39, v161
	v_mov_b32_e32 v54, 0
	v_mov_b32_e32 v55, v161
	v_mov_b32_e32 v56, v161
	v_mov_b32_e32 v57, v161
	v_mov_b32_e32 v32, 0
	v_mov_b32_e32 v33, v161
	v_mov_b32_e32 v34, v161
	v_mov_b32_e32 v35, v161
	v_mov_b32_e32 v64, 0
	v_mov_b32_e32 v65, v161
	v_mov_b32_e32 v66, v161
	v_mov_b32_e32 v67, v161
	v_mov_b32_e32 v40, 0
	v_mov_b32_e32 v41, v161
	v_mov_b32_e32 v42, v161
	v_mov_b32_e32 v43, v161
	v_mov_b32_e32 v48, 0
	v_mov_b32_e32 v49, v161
	v_mov_b32_e32 v50, v161
	v_mov_b32_e32 v51, v161
	v_mov_b32_e32 v68, 0
	v_mov_b32_e32 v69, v161
	v_mov_b32_e32 v70, v161
	v_mov_b32_e32 v71, v161
	v_mov_b32_e32 v72, 0
	v_mov_b32_e32 v73, v161
	v_readlane_b32 s100, v253, 0
	v_readlane_b32 s101, v253, 1
	s_load_dwordx2 s[100:101], s[100:101], 0x160
	v_lshrrev_b32_e32 v7, 6, v146
	s_nop 0
	v_readfirstlane_b32 s8, v7
	v_lshrrev_b32_e32 v5, 3, v146
	v_and_b32_e32 v6, 7, v146
	v_xor_b32_e32 v6, v5, v6
	v_and_b32_e32 v6, 7, v6
	v_lshlrev_b32_e32 v6, 4, v6
	v_lshl_or_b32 v4, v5, 11, v6
	v_add_u32_e32 v5, 0x10000, v4
	v_add_u32_e32 v6, 0x20000, v4
	v_add_u32_e32 v7, 0x30000, v4
	s_and_b32 s98, s43, 7
	s_and_b32 s99, s69, 7
	s_lshl_b32 s99, s99, 3
	s_or_b32 s98, s98, s99
	s_lshl_b32 s98, s98, 18
	s_add_u32 s98, s98, 0xdc40000
	s_lshr_b32 s99, s43, 3
	s_lshl_b32 s99, s99, 18
	s_add_u32 s99, s99, 0x7700000
	s_lshl_b32 s8, s8, 10
	s_waitcnt lgkmcnt(0)
	s_mov_b32 m0, s99
	s_add_u32 s98, s100, s98
	s_addc_u32 s99, s101, 0
	s_add_u32 s100, s100, m0
	s_addc_u32 s101, s101, 0
	s_add_u32 m0, s8, 0x0
	s_nop 0
	global_load_lds_dwordx4 v4, s[98:99]
	s_add_u32 m0, s8, 0x1000
	s_nop 0
	global_load_lds_dwordx4 v5, s[98:99]
	s_add_u32 m0, s8, 0x2000
	s_nop 0
	global_load_lds_dwordx4 v6, s[98:99]
	s_add_u32 m0, s8, 0x3000
	s_nop 0
	global_load_lds_dwordx4 v7, s[98:99]
	s_add_u32 m0, s8, 0x8000
	s_nop 0
	global_load_lds_dwordx4 v4, s[100:101]
	s_add_u32 m0, s8, 0x9000
	s_nop 0
	global_load_lds_dwordx4 v5, s[100:101]
	s_add_u32 m0, s8, 0xa000
	s_nop 0
	global_load_lds_dwordx4 v6, s[100:101]
	s_add_u32 m0, s8, 0xb000
	s_nop 0
	global_load_lds_dwordx4 v7, s[100:101]
	s_add_u32 s98, s98, 0x80
	s_addc_u32 s99, s99, 0
	s_add_u32 s100, s100, 0x80
	s_addc_u32 s101, s101, 0
	s_waitcnt vmcnt(0)
	s_waitcnt lgkmcnt(0)
	s_barrier
.LBB0_528:
	s_add_i32 s2, s6, 2
	s_setprio 1
	ds_read_b128 v[114:117], v175 offset:32768
	ds_read_b128 v[122:125], v175 offset:34816
	ds_read_b128 v[118:121], v174
	ds_read_b128 v[136:139], v174 offset:2048
	ds_read_b128 v[140:143], v174 offset:4096
	ds_read_b128 v[162:165], v174 offset:6144
	s_waitcnt lgkmcnt(3)
	v_mfma_f32_16x16x32_bf16 v[8:11], v[114:117], v[118:121], v[8:11]
	ds_read_b128 v[166:169], v175 offset:36864
	v_mfma_f32_16x16x32_bf16 v[26:29], v[122:125], v[118:121], v[26:29]
	ds_read_b128 v[182:185], v175 offset:38912
	s_waitcnt lgkmcnt(1)
	v_mfma_f32_16x16x32_bf16 v[16:19], v[166:169], v[118:121], v[16:19]
	s_waitcnt lgkmcnt(0)
	v_mfma_f32_16x16x32_bf16 v[60:63], v[182:185], v[118:121], v[60:63]
	s_add_u32 m0, s8, 0x4000
	s_nop 0
	global_load_lds_dwordx4 v4, s[98:99]
	ds_read_b128 v[186:189], v176
	v_mfma_f32_16x16x32_bf16 v[36:39], v[114:117], v[136:139], v[36:39]
	v_mfma_f32_16x16x32_bf16 v[54:57], v[122:125], v[136:139], v[54:57]
	s_add_u32 m0, s8, 0x5000
	s_nop 0
	global_load_lds_dwordx4 v5, s[98:99]
	ds_read_b128 v[194:197], v176 offset:2048
	v_mfma_f32_16x16x32_bf16 v[32:35], v[166:169], v[136:139], v[32:35]
	v_mfma_f32_16x16x32_bf16 v[64:67], v[182:185], v[136:139], v[64:67]
	s_add_u32 m0, s8, 0x6000
	s_nop 0
	global_load_lds_dwordx4 v6, s[98:99]
	ds_read_b128 v[198:201], v176 offset:4096
	v_mfma_f32_16x16x32_bf16 v[40:43], v[114:117], v[140:143], v[40:43]
	v_mfma_f32_16x16x32_bf16 v[88:91], v[122:125], v[140:143], v[88:91]
	s_add_u32 m0, s8, 0x7000
	s_nop 0
	global_load_lds_dwordx4 v7, s[98:99]
	ds_read_b128 v[206:209], v176 offset:6144
	v_mfma_f32_16x16x32_bf16 v[48:51], v[166:169], v[140:143], v[48:51]
	v_mfma_f32_16x16x32_bf16 v[76:79], v[182:185], v[140:143], v[76:79]
	s_add_u32 m0, s8, 0xc000
	s_nop 0
	global_load_lds_dwordx4 v4, s[100:101]
	ds_read_b128 v[210:213], v177 offset:32768
	v_mfma_f32_16x16x32_bf16 v[80:83], v[114:117], v[162:165], v[80:83]
	v_mfma_f32_16x16x32_bf16 v[84:87], v[122:125], v[162:165], v[84:87]
	s_add_u32 m0, s8, 0xd000
	s_nop 0
	global_load_lds_dwordx4 v5, s[100:101]
	ds_read_b128 v[122:125], v177 offset:34816
	v_mfma_f32_16x16x32_bf16 v[68:71], v[166:169], v[162:165], v[68:71]
	v_mfma_f32_16x16x32_bf16 v[72:75], v[182:185], v[162:165], v[72:75]
	s_add_u32 m0, s8, 0xe000
	s_nop 0
	global_load_lds_dwordx4 v6, s[100:101]
	ds_read_b128 v[166:169], v177 offset:36864
	s_waitcnt lgkmcnt(2)
	v_mfma_f32_16x16x32_bf16 v[8:11], v[210:213], v[186:189], v[8:11]
	s_waitcnt lgkmcnt(1)
	v_mfma_f32_16x16x32_bf16 v[26:29], v[122:125], v[186:189], v[26:29]
	s_add_u32 m0, s8, 0xf000
	s_nop 0
	global_load_lds_dwordx4 v7, s[100:101]
	s_add_u32 s98, s98, 0x80
	s_addc_u32 s99, s99, 0
	s_add_u32 s100, s100, 0x80
	s_addc_u32 s101, s101, 0
	ds_read_b128 v[214:217], v177 offset:38912
	s_waitcnt lgkmcnt(1)
	v_mfma_f32_16x16x32_bf16 v[16:19], v[166:169], v[186:189], v[16:19]
	s_waitcnt lgkmcnt(0)
	v_mfma_f32_16x16x32_bf16 v[60:63], v[214:217], v[186:189], v[60:63]
	v_mfma_f32_16x16x32_bf16 v[36:39], v[210:213], v[194:197], v[36:39]
	v_mfma_f32_16x16x32_bf16 v[54:57], v[122:125], v[194:197], v[54:57]
	v_mfma_f32_16x16x32_bf16 v[32:35], v[166:169], v[194:197], v[32:35]
	v_mfma_f32_16x16x32_bf16 v[64:67], v[214:217], v[194:197], v[64:67]
	v_mfma_f32_16x16x32_bf16 v[40:43], v[210:213], v[198:201], v[40:43]
	v_mfma_f32_16x16x32_bf16 v[88:91], v[122:125], v[198:201], v[88:91]
	v_mfma_f32_16x16x32_bf16 v[48:51], v[166:169], v[198:201], v[48:51]
	v_mfma_f32_16x16x32_bf16 v[76:79], v[214:217], v[198:201], v[76:79]
	v_mfma_f32_16x16x32_bf16 v[80:83], v[210:213], v[206:209], v[80:83]
	v_mfma_f32_16x16x32_bf16 v[84:87], v[122:125], v[206:209], v[84:87]
	v_mfma_f32_16x16x32_bf16 v[68:71], v[166:169], v[206:209], v[68:71]
	v_mfma_f32_16x16x32_bf16 v[72:75], v[214:217], v[206:209], v[72:75]
	s_setprio 0
	s_waitcnt vmcnt(0) lgkmcnt(0)
	s_barrier
	s_setprio 1
	ds_read_b128 v[92:95], v175 offset:49152
	ds_read_b128 v[96:99], v175 offset:51200
	ds_read_b128 v[0:3], v174 offset:16384
	ds_read_b128 v[12:15], v174 offset:18432
	ds_read_b128 v[20:23], v174 offset:20480
	ds_read_b128 v[100:103], v174 offset:22528
	s_waitcnt lgkmcnt(3)
	v_mfma_f32_16x16x32_bf16 v[8:11], v[92:95], v[0:3], v[8:11]
	ds_read_b128 v[122:125], v175 offset:53248
	v_mfma_f32_16x16x32_bf16 v[26:29], v[96:99], v[0:3], v[26:29]
	ds_read_b128 v[166:169], v175 offset:55296
	s_waitcnt lgkmcnt(1)
	v_mfma_f32_16x16x32_bf16 v[16:19], v[122:125], v[0:3], v[16:19]
	s_waitcnt lgkmcnt(0)
	v_mfma_f32_16x16x32_bf16 v[60:63], v[166:169], v[0:3], v[60:63]
	s_add_u32 m0, s8, 0x0
	s_nop 0
	global_load_lds_dwordx4 v4, s[98:99]
	ds_read_b128 v[186:189], v176 offset:16384
	v_mfma_f32_16x16x32_bf16 v[36:39], v[92:95], v[12:15], v[36:39]
	v_mfma_f32_16x16x32_bf16 v[54:57], v[96:99], v[12:15], v[54:57]
	s_add_u32 m0, s8, 0x1000
	s_nop 0
	global_load_lds_dwordx4 v5, s[98:99]
	ds_read_b128 v[194:197], v176 offset:18432
	v_mfma_f32_16x16x32_bf16 v[32:35], v[122:125], v[12:15], v[32:35]
	v_mfma_f32_16x16x32_bf16 v[64:67], v[166:169], v[12:15], v[64:67]
	s_add_u32 m0, s8, 0x2000
	s_nop 0
	global_load_lds_dwordx4 v6, s[98:99]
	ds_read_b128 v[198:201], v176 offset:20480
	v_mfma_f32_16x16x32_bf16 v[40:43], v[92:95], v[20:23], v[40:43]
	v_mfma_f32_16x16x32_bf16 v[88:91], v[96:99], v[20:23], v[88:91]
	s_add_u32 m0, s8, 0x3000
	s_nop 0
	global_load_lds_dwordx4 v7, s[98:99]
	ds_read_b128 v[206:209], v176 offset:22528
	v_mfma_f32_16x16x32_bf16 v[48:51], v[122:125], v[20:23], v[48:51]
	v_mfma_f32_16x16x32_bf16 v[76:79], v[166:169], v[20:23], v[76:79]
	s_add_u32 m0, s8, 0x8000
	s_nop 0
	global_load_lds_dwordx4 v4, s[100:101]
	ds_read_b128 v[210:213], v177 offset:49152
	v_mfma_f32_16x16x32_bf16 v[80:83], v[92:95], v[100:103], v[80:83]
	v_mfma_f32_16x16x32_bf16 v[84:87], v[96:99], v[100:103], v[84:87]
	s_add_u32 m0, s8, 0x9000
	s_nop 0
	global_load_lds_dwordx4 v5, s[100:101]
	ds_read_b128 v[214:217], v177 offset:51200
	v_mfma_f32_16x16x32_bf16 v[68:71], v[122:125], v[100:103], v[68:71]
	v_mfma_f32_16x16x32_bf16 v[72:75], v[166:169], v[100:103], v[72:75]
	s_add_u32 m0, s8, 0xa000
	s_nop 0
	global_load_lds_dwordx4 v6, s[100:101]
	ds_read_b128 v[122:125], v177 offset:53248
	s_waitcnt lgkmcnt(2)
	v_mfma_f32_16x16x32_bf16 v[8:11], v[210:213], v[186:189], v[8:11]
	s_waitcnt lgkmcnt(1)
	v_mfma_f32_16x16x32_bf16 v[26:29], v[214:217], v[186:189], v[26:29]
	s_add_u32 m0, s8, 0xb000
	s_nop 0
	global_load_lds_dwordx4 v7, s[100:101]
	s_add_u32 s98, s98, 0x80
	s_addc_u32 s99, s99, 0
	s_add_u32 s100, s100, 0x80
	s_addc_u32 s101, s101, 0
	ds_read_b128 v[166:169], v177 offset:55296
	s_waitcnt lgkmcnt(1)
	v_mfma_f32_16x16x32_bf16 v[16:19], v[122:125], v[186:189], v[16:19]
	s_waitcnt lgkmcnt(0)
	v_mfma_f32_16x16x32_bf16 v[60:63], v[166:169], v[186:189], v[60:63]
	v_mfma_f32_16x16x32_bf16 v[36:39], v[210:213], v[194:197], v[36:39]
	v_mfma_f32_16x16x32_bf16 v[54:57], v[214:217], v[194:197], v[54:57]
	v_mfma_f32_16x16x32_bf16 v[32:35], v[122:125], v[194:197], v[32:35]
	v_mfma_f32_16x16x32_bf16 v[64:67], v[166:169], v[194:197], v[64:67]
	v_mfma_f32_16x16x32_bf16 v[40:43], v[210:213], v[198:201], v[40:43]
	v_mfma_f32_16x16x32_bf16 v[88:91], v[214:217], v[198:201], v[88:91]
	v_mfma_f32_16x16x32_bf16 v[48:51], v[122:125], v[198:201], v[48:51]
	v_mfma_f32_16x16x32_bf16 v[76:79], v[166:169], v[198:201], v[76:79]
	v_mfma_f32_16x16x32_bf16 v[80:83], v[210:213], v[206:209], v[80:83]
	v_mfma_f32_16x16x32_bf16 v[84:87], v[214:217], v[206:209], v[84:87]
	v_mfma_f32_16x16x32_bf16 v[68:71], v[122:125], v[206:209], v[68:71]
	v_mfma_f32_16x16x32_bf16 v[72:75], v[166:169], v[206:209], v[72:75]
	s_setprio 0
	s_mov_b32 s6, s2
	s_waitcnt vmcnt(0) lgkmcnt(0)
	s_barrier
	s_cmp_lt_u32 s6, 16
	s_cbranch_scc1 .LBB0_528
	s_waitcnt vmcnt(5)
	v_add_u32_e32 v15, s44, v173
	v_or_b32_e32 v181, v15, v148
	v_or_b32_e32 v160, s0, v234
	s_add_i32 s0, s44, 0xfffff000
	v_lshlrev_b32_e32 v0, 2, v181
	s_ashr_i32 s0, s0, 10
	global_load_dword v14, v0, s[28:29]
	global_load_dword v30, v0, s[28:29] offset:64
	global_load_dword v31, v0, s[28:29] offset:128
	global_load_dword v44, v0, s[28:29] offset:192
	s_add_i32 s2, s0, 6
	s_and_b64 s[0:1], s[24:25], exec
	s_cselect_b32 s0, 5, s2
	s_mul_hi_u32 s1, s0, 0x4200
	s_mulk_i32 s0, 0x4200
	s_add_u32 s0, s4, s0
	s_addc_u32 s1, s5, s1
	v_mov_b32_e32 v135, v161
	v_lshl_add_u64 v[0:1], v[160:161], 2, s[0:1]
	v_lshl_add_u64 v[4:5], v[0:1], 0, v[134:135]
	global_load_dwordx4 v[22:25], v[4:5], off
	global_load_dwordx4 v[0:3], v[4:5], off offset:64
	global_load_dwordx4 v[92:95], v[4:5], off offset:128
	s_nop 0
	global_load_dwordx4 v[4:7], v[4:5], off offset:192
	v_mov_b32_e32 v12, v26
	v_mov_b32_e32 v13, v9
	v_mov_b32_e32 v9, v27
	s_waitcnt vmcnt(11)
	v_mov_b32_e32 v20, v54
	v_mov_b32_e32 v21, v37
	v_mov_b32_e32 v37, v55
	s_cmpk_lt_u32 s43, 0x80
	s_waitcnt vmcnt(7)
	v_fmamk_f32 v14, v14, 0x3a800000, v179
	s_waitcnt vmcnt(6)
	v_fmamk_f32 v26, v30, 0x3a800000, v179
	v_cmp_gt_f32_e64 s[6:7], s41, v26
	s_waitcnt vmcnt(4)
	v_fmamk_f32 v30, v44, 0x3a800000, v179
	v_mul_f32_e32 v44, 0x4b800000, v26
	v_fmamk_f32 v27, v31, 0x3a800000, v179
	v_mul_f32_e32 v46, 0x4b800000, v30
	v_cndmask_b32_e64 v26, v26, v44, s[6:7]
	v_cmp_gt_f32_e64 s[10:11], s41, v30
	v_mul_f32_e32 v31, 0x4b800000, v14
	v_mul_f32_e32 v45, 0x4b800000, v27
	v_cmp_gt_f32_e32 vcc, s41, v14
	v_cmp_gt_f32_e64 s[8:9], s41, v27
	v_cndmask_b32_e64 v30, v30, v46, s[10:11]
	v_rsq_f32_e32 v26, v26
	v_cndmask_b32_e32 v14, v14, v31, vcc
	v_cndmask_b32_e64 v27, v27, v45, s[8:9]
	v_rsq_f32_e32 v30, v30
	v_rsq_f32_e32 v14, v14
	v_rsq_f32_e32 v27, v27
	s_waitcnt vmcnt(2)
	v_mov_b32_e32 v97, v3
	v_mul_f32_e32 v3, 0x45800000, v26
	v_mov_b32_e32 v96, v25
	v_mul_f32_e32 v25, 0x45800000, v30
	v_cndmask_b32_e64 v102, v26, v3, s[6:7]
	v_mul_f32_e32 v31, 0x45800000, v14
	s_waitcnt vmcnt(0)
	v_mov_b32_e32 v99, v7
	v_mul_f32_e32 v7, 0x45800000, v27
	v_cndmask_b32_e64 v106, v30, v25, s[10:11]
	v_fma_f32 v30, v56, v102, v2
	v_mov_b32_e32 v56, v39
	v_mov_b32_e32 v53, v1
	v_mov_b32_e32 v1, v23
	v_cndmask_b32_e32 v100, v14, v31, vcc
	v_cndmask_b32_e64 v104, v27, v7, s[8:9]
	v_pk_fma_f32 v[140:141], v[56:57], v[102:103], v[96:97] op_sel_hi:[1,0,1]
	v_mov_b32_e32 v56, v88
	v_mov_b32_e32 v57, v41
	v_mov_b32_e32 v98, v95
	v_mov_b32_e32 v52, v22
	v_fma_f32 v14, v28, v100, v2
	v_mov_b32_e32 v28, v11
	v_fma_f32 v26, v38, v102, v24
	v_fma_f32 v38, v66, v102, v6
	v_mov_b32_e32 v66, v35
	v_mov_b32_e32 v41, v89
	v_pk_fma_f32 v[162:163], v[56:57], v[104:105], v[0:1] op_sel_hi:[1,0,1]
	v_mov_b32_e32 v56, v80
	v_mov_b32_e32 v57, v85
	v_mov_b32_e32 v85, v81
	v_fma_f32 v10, v10, v100, v24
	v_fma_f32 v42, v42, v104, v24
	v_fma_f32 v58, v82, v106, v24
	v_pk_fma_f32 v[8:9], v[8:9], v[100:101], v[52:53] op_sel_hi:[1,0,1]
	v_pk_fma_f32 v[136:137], v[12:13], v[100:101], v[0:1] op_sel_hi:[1,0,1]
	v_pk_fma_f32 v[24:25], v[36:37], v[102:103], v[52:53] op_sel_hi:[1,0,1]
	v_pk_fma_f32 v[20:21], v[20:21], v[102:103], v[0:1] op_sel_hi:[1,0,1]
	v_pk_fma_f32 v[138:139], v[28:29], v[100:101], v[96:97] op_sel_hi:[1,0,1]
	v_pk_fma_f32 v[28:29], v[66:67], v[102:103], v[98:99] op_sel_hi:[1,0,1]
	v_pk_fma_f32 v[40:41], v[40:41], v[104:105], v[52:53] op_sel_hi:[1,0,1]
	v_pk_fma_f32 v[56:57], v[56:57], v[106:107], v[52:53] op_sel_hi:[1,0,1]
	v_pk_fma_f32 v[52:53], v[84:85], v[106:107], v[0:1] op_sel_hi:[1,0,1]
	v_mov_b32_e32 v0, v60
	v_mov_b32_e32 v1, v17
	v_mov_b32_e32 v66, v4
	v_mov_b32_e32 v67, v93
	v_pk_fma_f32 v[142:143], v[0:1], v[100:101], v[66:67] op_sel_hi:[1,0,1]
	v_mov_b32_e32 v0, v64
	v_mov_b32_e32 v1, v33
	v_pk_fma_f32 v[164:165], v[0:1], v[102:103], v[66:67] op_sel_hi:[1,0,1]
	v_mov_b32_e32 v0, v76
	v_mov_b32_e32 v1, v49
	v_fma_f32 v22, v62, v100, v6
	v_mov_b32_e32 v62, v19
	v_fma_f32 v46, v90, v104, v2
	v_mov_b32_e32 v90, v43
	v_fma_f32 v54, v78, v104, v6
	v_mov_b32_e32 v78, v51
	v_fmac_f32_e32 v2, v86, v106
	v_mov_b32_e32 v86, v83
	v_mov_b32_e32 v17, v61
	v_mov_b32_e32 v93, v5
	v_mov_b32_e32 v33, v65
	v_pk_fma_f32 v[168:169], v[0:1], v[104:105], v[66:67] op_sel_hi:[1,0,1]
	v_mov_b32_e32 v49, v77
	v_mov_b32_e32 v0, v68
	v_mov_b32_e32 v1, v73
	v_mov_b32_e32 v73, v69
	v_fmac_f32_e32 v6, v74, v106
	v_mov_b32_e32 v74, v71
	s_cselect_b64 s[8:9], -1, 0
	s_and_b32 s0, s43, 0x7fffffc0
	v_fma_f32 v18, v18, v100, v94
	v_fma_f32 v34, v34, v102, v94
	v_fma_f32 v50, v50, v104, v94
	v_pk_fma_f32 v[12:13], v[62:63], v[100:101], v[98:99] op_sel_hi:[1,0,1]
	v_pk_fma_f32 v[36:37], v[90:91], v[104:105], v[96:97] op_sel_hi:[1,0,1]
	v_pk_fma_f32 v[44:45], v[78:79], v[104:105], v[98:99] op_sel_hi:[1,0,1]
	v_pk_fma_f32 v[166:167], v[86:87], v[106:107], v[96:97] op_sel_hi:[1,0,1]
	v_fma_f32 v62, v70, v106, v94
	v_pk_fma_f32 v[16:17], v[16:17], v[100:101], v[92:93] op_sel_hi:[1,0,1]
	v_pk_fma_f32 v[32:33], v[32:33], v[102:103], v[92:93] op_sel_hi:[1,0,1]
	v_pk_fma_f32 v[48:49], v[48:49], v[104:105], v[92:93] op_sel_hi:[1,0,1]
	v_pk_fma_f32 v[60:61], v[0:1], v[106:107], v[92:93] op_sel_hi:[1,0,1]
	v_pk_fma_f32 v[0:1], v[72:73], v[106:107], v[66:67] op_sel_hi:[1,0,1]
	v_pk_fma_f32 v[170:171], v[74:75], v[106:107], v[98:99] op_sel_hi:[1,0,1]
	s_cmpk_lg_i32 s0, 0x80
	s_mov_b64 s[6:7], -1
	s_cbranch_scc0 .LBB0_543
	v_lshlrev_b32_e32 v3, 1, v15
	s_and_b64 s[0:1], s[26:27], s[8:9]
	v_and_b32_e32 v4, 0x780, v3
	v_mov_b32_e32 v5, v161
	v_cndmask_b32_e64 v3, 0, 1, s[0:1]
	v_cmp_ne_u32_e64 s[6:7], 1, v3
	s_andn2_b64 vcc, exec, s[0:1]
	v_lshl_add_u64 v[112:113], v[130:131], 0, v[4:5]
	s_cbranch_vccnz .LBB0_532
	v_lshlrev_b32_e32 v3, 7, v181
	global_load_dwordx4 v[64:67], v[112:113], off
	global_load_dwordx4 v[68:71], v[112:113], off offset:16
	v_mov_b32_e32 v5, v161
	v_and_b32_e32 v4, 0x780, v3
	v_lshl_add_u64 v[4:5], v[130:131], 0, v[4:5]
	global_load_dwordx4 v[72:75], v[4:5], off
	global_load_dwordx4 v[76:79], v[4:5], off offset:16
	v_mov_b32_e32 v4, v136
	v_mov_b32_e32 v5, v9
	v_mov_b32_e32 v80, v8
	v_mov_b32_e32 v81, v137
	v_mov_b32_e32 v82, v142
	v_mov_b32_e32 v83, v17
	v_mov_b32_e32 v84, v16
	v_mov_b32_e32 v85, v143
	s_waitcnt vmcnt(3)
	v_mov_b32_e32 v86, v65
	v_mov_b32_e32 v87, v66
	v_mov_b32_e32 v88, v64
	v_mov_b32_e32 v89, v67
	v_mov_b32_e32 v90, v65
	v_mov_b32_e32 v91, v67
	v_mov_b32_e32 v65, v66
	s_waitcnt vmcnt(2)
	v_mul_f32_e32 v66, v10, v68
	v_mul_f32_e32 v92, v14, v69
	v_mul_f32_e32 v94, v14, v68
	v_mul_f32_e32 v96, v10, v69
	v_pk_mul_f32 v[68:69], v[138:139], v[70:71]
	v_pk_mul_f32 v[88:89], v[136:137], v[88:89]
	v_pk_mul_f32 v[4:5], v[4:5], v[90:91]
	v_mov_b32_e32 v67, v68
	v_mov_b32_e32 v93, v69
	v_pk_mul_f32 v[70:71], v[138:139], v[70:71] op_sel:[1,0] op_sel_hi:[0,1]
	v_pk_fma_f32 v[64:65], v[80:81], v[64:65], v[4:5] neg_lo:[0,0,1] neg_hi:[0,0,1]
	v_pk_add_f32 v[66:67], v[66:67], v[92:93] neg_lo:[0,1] neg_hi:[0,1]
	v_pk_fma_f32 v[68:69], v[8:9], v[86:87], v[88:89]
	s_waitcnt vmcnt(1)
	v_mov_b32_e32 v4, v73
	v_mov_b32_e32 v5, v74
	v_mov_b32_e32 v80, v72
	v_mov_b32_e32 v81, v75
	v_mov_b32_e32 v86, v73
	v_mov_b32_e32 v87, v75
	v_mov_b32_e32 v73, v74
	s_waitcnt vmcnt(0)
	v_mul_f32_e32 v74, v18, v76
	v_mul_f32_e32 v88, v22, v77
	v_mul_f32_e32 v90, v22, v76
	v_mul_f32_e32 v92, v18, v77
	v_pk_mul_f32 v[76:77], v[12:13], v[78:79]
	v_pk_mul_f32 v[78:79], v[12:13], v[78:79] op_sel:[1,0] op_sel_hi:[0,1]
	v_mov_b32_e32 v95, v70
	v_mov_b32_e32 v97, v71
	v_pk_mul_f32 v[80:81], v[142:143], v[80:81]
	v_pk_mul_f32 v[82:83], v[82:83], v[86:87]
	v_mov_b32_e32 v75, v76
	v_mov_b32_e32 v89, v77
	v_mov_b32_e32 v91, v78
	v_mov_b32_e32 v93, v79
	v_pk_add_f32 v[70:71], v[94:95], v[96:97]
	v_pk_fma_f32 v[72:73], v[84:85], v[72:73], v[82:83] neg_lo:[0,0,1] neg_hi:[0,0,1]
	v_pk_add_f32 v[74:75], v[74:75], v[88:89] neg_lo:[0,1] neg_hi:[0,1]
	v_pk_fma_f32 v[76:77], v[16:17], v[4:5], v[80:81]
	v_pk_add_f32 v[78:79], v[90:91], v[92:93]
	s_branch .LBB0_533

.LBB0_675:
	s_and_b32 s0, s9, 7
	s_or_b32 s0, s0, s3
	s_lshl_b32 s1, s0, 7
	v_or_b32_e32 v0, s1, v149
	v_lshl_or_b32 v96, v0, 11, v116
	s_waitcnt vmcnt(1)
	v_lshl_add_u64 v[100:101], s[18:19], 0, v[96:97]
	v_add_co_u32_e32 v12, vcc, 0x10000, v100
	s_lshl_b32 s2, s9, 4
	s_nop 0
	v_addc_co_u32_e32 v13, vcc, 0, v101, vcc
	s_and_b32 s0, s2, 0x7fffff80
	v_add_co_u32_e32 v26, vcc, 0x20000, v100
	v_or_b32_e32 v0, s0, v149
	s_nop 0
	v_addc_co_u32_e32 v27, vcc, 0, v101, vcc
	v_lshl_or_b32 v98, v0, 11, v116
	v_add_co_u32_e32 v28, vcc, 0x30000, v100
	v_mov_b32_e32 v99, v97
	s_nop 0
	v_addc_co_u32_e32 v29, vcc, 0, v101, vcc
	v_lshl_add_u64 v[102:103], s[16:17], 0, v[98:99]
	v_add_co_u32_e32 v30, vcc, s6, v102
	s_waitcnt lgkmcnt(0)
	v_addc_co_u32_e32 v31, vcc, 0, v103, vcc
	v_add_co_u32_e32 v42, vcc, s7, v102
	s_nop 0
	v_addc_co_u32_e32 v43, vcc, 0, v103, vcc
	v_add_co_u32_e32 v44, vcc, s8, v102
	s_nop 0
	v_addc_co_u32_e32 v45, vcc, 0, v103, vcc
	s_movk_i32 s2, 0x100
	s_mov_b32 s42, s29
	v_mov_b32_e32 v64, 0
	v_mov_b32_e32 v65, v97
	v_mov_b32_e32 v66, v97
	v_mov_b32_e32 v67, v97
	v_mov_b32_e32 v40, 0
	v_mov_b32_e32 v41, v97
	v_mov_b32_e32 v42, v97
	v_mov_b32_e32 v43, v97
	v_mov_b32_e32 v28, 0
	v_mov_b32_e32 v29, v97
	v_mov_b32_e32 v30, v97
	v_mov_b32_e32 v31, v97
	v_mov_b32_e32 v12, 0
	v_mov_b32_e32 v13, v97
	v_lshl_add_u64 v[104:105], v[102:103], 0, s[30:31]
	v_lshl_add_u64 v[106:107], v[102:103], 0, s[34:35]
	v_lshl_add_u64 v[108:109], v[102:103], 0, s[36:37]
	v_lshl_add_u64 v[110:111], v[100:101], 0, s[30:31]
	v_lshl_add_u64 v[112:113], v[100:101], 0, s[34:35]
	v_lshl_add_u64 v[114:115], v[100:101], 0, s[36:37]
	s_waitcnt lgkmcnt(0)
	s_barrier
	v_mov_b32_e32 v60, 0
	v_mov_b32_e32 v61, v97
	v_mov_b32_e32 v62, v97
	v_mov_b32_e32 v63, v97
	v_mov_b32_e32 v44, 0
	v_mov_b32_e32 v45, v97
	v_mov_b32_e32 v46, v97
	v_mov_b32_e32 v47, v97
	v_mov_b32_e32 v26, v97
	v_mov_b32_e32 v27, v97
	v_mov_b32_e32 v52, 0
	v_mov_b32_e32 v53, v97
	v_mov_b32_e32 v54, v97
	v_mov_b32_e32 v55, v97
	v_mov_b32_e32 v48, 0
	v_mov_b32_e32 v49, v97
	v_mov_b32_e32 v50, v97
	v_mov_b32_e32 v51, v97
	v_mov_b32_e32 v14, v97
	v_mov_b32_e32 v15, v97
	v_mov_b32_e32 v24, 0
	v_mov_b32_e32 v25, v97
	v_mov_b32_e32 v8, 0
	v_mov_b32_e32 v9, v97
	v_mov_b32_e32 v10, v97
	v_mov_b32_e32 v11, v97
	v_mov_b32_e32 v36, 0
	v_mov_b32_e32 v37, v97
	v_mov_b32_e32 v38, v97
	v_mov_b32_e32 v39, v97
	v_mov_b32_e32 v20, 0
	v_mov_b32_e32 v21, v97
	v_mov_b32_e32 v22, v97
	v_mov_b32_e32 v23, v97
	v_mov_b32_e32 v4, 0
	v_mov_b32_e32 v5, v97
	v_mov_b32_e32 v6, v97
	v_mov_b32_e32 v7, v97
	v_mov_b32_e32 v32, 0
	v_mov_b32_e32 v33, v97
	v_mov_b32_e32 v34, v97
	v_mov_b32_e32 v35, v97
	v_mov_b32_e32 v16, 0
	v_mov_b32_e32 v17, v97
	v_mov_b32_e32 v18, v97
	v_mov_b32_e32 v19, v97
	v_mov_b32_e32 v0, 0
	v_mov_b32_e32 v1, v97
	v_mov_b32_e32 v2, v97
	v_mov_b32_e32 v3, v97
	v_readlane_b32 s100, v253, 0
	v_readlane_b32 s101, v253, 1
	s_load_dwordx2 s[100:101], s[100:101], 0x160
	v_lshrrev_b32_e32 v71, 6, v146
	s_nop 0
	v_readfirstlane_b32 s44, v71
	v_lshrrev_b32_e32 v69, 3, v146
	v_and_b32_e32 v70, 7, v146
	v_xor_b32_e32 v70, v69, v70
	v_and_b32_e32 v70, 7, v70
	v_lshlrev_b32_e32 v70, 4, v70
	v_lshl_or_b32 v68, v69, 11, v70
	v_add_u32_e32 v69, 0x10000, v68
	v_add_u32_e32 v70, 0x20000, v68
	v_add_u32_e32 v71, 0x30000, v68
	s_and_b32 s98, s9, 7
	s_and_b32 s99, s69, 7
	s_lshl_b32 s99, s99, 3
	s_or_b32 s98, s98, s99
	s_lshl_b32 s98, s98, 18
	s_add_u32 s98, s98, 0x2000000
	s_lshr_b32 s99, s9, 3
	s_lshl_b32 s99, s99, 18
	s_add_u32 s99, s99, 0x8e40000
	s_lshl_b32 s44, s44, 10
	s_waitcnt lgkmcnt(0)
	s_mov_b32 m0, s99
	s_add_u32 s98, s100, s98
	s_addc_u32 s99, s101, 0
	s_add_u32 s100, s100, m0
	s_addc_u32 s101, s101, 0
	s_add_u32 m0, s44, 0x0
	s_nop 0
	global_load_lds_dwordx4 v68, s[98:99]
	s_add_u32 m0, s44, 0x1000
	s_nop 0
	global_load_lds_dwordx4 v69, s[98:99]
	s_add_u32 m0, s44, 0x2000
	s_nop 0
	global_load_lds_dwordx4 v70, s[98:99]
	s_add_u32 m0, s44, 0x3000
	s_nop 0
	global_load_lds_dwordx4 v71, s[98:99]
	s_add_u32 m0, s44, 0x8000
	s_nop 0
	global_load_lds_dwordx4 v68, s[100:101]
	s_add_u32 m0, s44, 0x9000
	s_nop 0
	global_load_lds_dwordx4 v69, s[100:101]
	s_add_u32 m0, s44, 0xa000
	s_nop 0
	global_load_lds_dwordx4 v70, s[100:101]
	s_add_u32 m0, s44, 0xb000
	s_nop 0
	global_load_lds_dwordx4 v71, s[100:101]
	s_add_u32 s98, s98, 0x80
	s_addc_u32 s99, s99, 0
	s_add_u32 s100, s100, 0x80
	s_addc_u32 s101, s101, 0
	s_waitcnt vmcnt(0)
	s_waitcnt lgkmcnt(0)
	s_barrier
.LBB0_676:
	s_add_i32 s33, s42, 2
	s_setprio 1
	ds_read_b128 v[126:129], v119 offset:32768
	ds_read_b128 v[134:137], v119 offset:34816
	ds_read_b128 v[130:133], v118
	ds_read_b128 v[138:141], v118 offset:2048
	ds_read_b128 v[162:165], v118 offset:4096
	ds_read_b128 v[166:169], v118 offset:6144
	s_waitcnt lgkmcnt(3)
	v_mfma_f32_16x16x32_bf16 v[64:67], v[126:129], v[130:133], v[64:67]
	ds_read_b128 v[170:173], v119 offset:36864
	v_mfma_f32_16x16x32_bf16 v[40:43], v[134:137], v[130:133], v[40:43]
	ds_read_b128 v[174:177], v119 offset:38912
	s_waitcnt lgkmcnt(1)
	v_mfma_f32_16x16x32_bf16 v[28:31], v[170:173], v[130:133], v[28:31]
	s_waitcnt lgkmcnt(0)
	v_mfma_f32_16x16x32_bf16 v[12:15], v[174:177], v[130:133], v[12:15]
	s_add_u32 m0, s44, 0x4000
	s_nop 0
	global_load_lds_dwordx4 v68, s[98:99]
	ds_read_b128 v[178:181], v120
	v_mfma_f32_16x16x32_bf16 v[60:63], v[126:129], v[138:141], v[60:63]
	v_mfma_f32_16x16x32_bf16 v[44:47], v[134:137], v[138:141], v[44:47]
	s_add_u32 m0, s44, 0x5000
	s_nop 0
	global_load_lds_dwordx4 v69, s[98:99]
	ds_read_b128 v[186:189], v120 offset:2048
	v_mfma_f32_16x16x32_bf16 v[24:27], v[170:173], v[138:141], v[24:27]
	v_mfma_f32_16x16x32_bf16 v[8:11], v[174:177], v[138:141], v[8:11]
	s_add_u32 m0, s44, 0x6000
	s_nop 0
	global_load_lds_dwordx4 v70, s[98:99]
	ds_read_b128 v[190:193], v120 offset:4096
	v_mfma_f32_16x16x32_bf16 v[52:55], v[126:129], v[162:165], v[52:55]
	v_mfma_f32_16x16x32_bf16 v[36:39], v[134:137], v[162:165], v[36:39]
	s_add_u32 m0, s44, 0x7000
	s_nop 0
	global_load_lds_dwordx4 v71, s[98:99]
	ds_read_b128 v[198:201], v120 offset:6144
	v_mfma_f32_16x16x32_bf16 v[20:23], v[170:173], v[162:165], v[20:23]
	v_mfma_f32_16x16x32_bf16 v[4:7], v[174:177], v[162:165], v[4:7]
	s_add_u32 m0, s44, 0xc000
	s_nop 0
	global_load_lds_dwordx4 v68, s[100:101]
	ds_read_b128 v[202:205], v121 offset:32768
	v_mfma_f32_16x16x32_bf16 v[48:51], v[126:129], v[166:169], v[48:51]
	v_mfma_f32_16x16x32_bf16 v[32:35], v[134:137], v[166:169], v[32:35]
	s_add_u32 m0, s44, 0xd000
	s_nop 0
	global_load_lds_dwordx4 v69, s[100:101]
	ds_read_b128 v[134:137], v121 offset:34816
	v_mfma_f32_16x16x32_bf16 v[16:19], v[170:173], v[166:169], v[16:19]
	v_mfma_f32_16x16x32_bf16 v[0:3], v[174:177], v[166:169], v[0:3]
	s_add_u32 m0, s44, 0xe000
	s_nop 0
	global_load_lds_dwordx4 v70, s[100:101]
	ds_read_b128 v[170:173], v121 offset:36864
	s_waitcnt lgkmcnt(2)
	v_mfma_f32_16x16x32_bf16 v[64:67], v[202:205], v[178:181], v[64:67]
	s_waitcnt lgkmcnt(1)
	v_mfma_f32_16x16x32_bf16 v[40:43], v[134:137], v[178:181], v[40:43]
	s_add_u32 m0, s44, 0xf000
	s_nop 0
	global_load_lds_dwordx4 v71, s[100:101]
	s_add_u32 s98, s98, 0x80
	s_addc_u32 s99, s99, 0
	s_add_u32 s100, s100, 0x80
	s_addc_u32 s101, s101, 0
	ds_read_b128 v[206:209], v121 offset:38912
	s_waitcnt lgkmcnt(1)
	v_mfma_f32_16x16x32_bf16 v[28:31], v[170:173], v[178:181], v[28:31]
	s_waitcnt lgkmcnt(0)
	v_mfma_f32_16x16x32_bf16 v[12:15], v[206:209], v[178:181], v[12:15]
	v_mfma_f32_16x16x32_bf16 v[60:63], v[202:205], v[186:189], v[60:63]
	v_mfma_f32_16x16x32_bf16 v[44:47], v[134:137], v[186:189], v[44:47]
	v_mfma_f32_16x16x32_bf16 v[24:27], v[170:173], v[186:189], v[24:27]
	v_mfma_f32_16x16x32_bf16 v[8:11], v[206:209], v[186:189], v[8:11]
	v_mfma_f32_16x16x32_bf16 v[52:55], v[202:205], v[190:193], v[52:55]
	v_mfma_f32_16x16x32_bf16 v[36:39], v[134:137], v[190:193], v[36:39]
	v_mfma_f32_16x16x32_bf16 v[20:23], v[170:173], v[190:193], v[20:23]
	v_mfma_f32_16x16x32_bf16 v[4:7], v[206:209], v[190:193], v[4:7]
	v_mfma_f32_16x16x32_bf16 v[48:51], v[202:205], v[198:201], v[48:51]
	v_mfma_f32_16x16x32_bf16 v[32:35], v[134:137], v[198:201], v[32:35]
	v_mfma_f32_16x16x32_bf16 v[16:19], v[170:173], v[198:201], v[16:19]
	v_mfma_f32_16x16x32_bf16 v[0:3], v[206:209], v[198:201], v[0:3]
	s_setprio 0
	s_waitcnt vmcnt(0) lgkmcnt(0)
	s_barrier
	s_setprio 1
	ds_read_b128 v[84:87], v119 offset:49152
	ds_read_b128 v[88:91], v119 offset:51200
	ds_read_b128 v[56:59], v118 offset:16384
	ds_read_b128 v[72:75], v118 offset:18432
	ds_read_b128 v[76:79], v118 offset:20480
	ds_read_b128 v[92:95], v118 offset:22528
	s_waitcnt lgkmcnt(3)
	v_mfma_f32_16x16x32_bf16 v[64:67], v[84:87], v[56:59], v[64:67]
	ds_read_b128 v[134:137], v119 offset:53248
	v_mfma_f32_16x16x32_bf16 v[40:43], v[88:91], v[56:59], v[40:43]
	ds_read_b128 v[170:173], v119 offset:55296
	s_waitcnt lgkmcnt(1)
	v_mfma_f32_16x16x32_bf16 v[28:31], v[134:137], v[56:59], v[28:31]
	s_waitcnt lgkmcnt(0)
	v_mfma_f32_16x16x32_bf16 v[12:15], v[170:173], v[56:59], v[12:15]
	s_add_u32 m0, s44, 0x0
	s_nop 0
	global_load_lds_dwordx4 v68, s[98:99]
	ds_read_b128 v[178:181], v120 offset:16384
	v_mfma_f32_16x16x32_bf16 v[60:63], v[84:87], v[72:75], v[60:63]
	v_mfma_f32_16x16x32_bf16 v[44:47], v[88:91], v[72:75], v[44:47]
	s_add_u32 m0, s44, 0x1000
	s_nop 0
	global_load_lds_dwordx4 v69, s[98:99]
	ds_read_b128 v[186:189], v120 offset:18432
	v_mfma_f32_16x16x32_bf16 v[24:27], v[134:137], v[72:75], v[24:27]
	v_mfma_f32_16x16x32_bf16 v[8:11], v[170:173], v[72:75], v[8:11]
	s_add_u32 m0, s44, 0x2000
	s_nop 0
	global_load_lds_dwordx4 v70, s[98:99]
	ds_read_b128 v[190:193], v120 offset:20480
	v_mfma_f32_16x16x32_bf16 v[52:55], v[84:87], v[76:79], v[52:55]
	v_mfma_f32_16x16x32_bf16 v[36:39], v[88:91], v[76:79], v[36:39]
	s_add_u32 m0, s44, 0x3000
	s_nop 0
	global_load_lds_dwordx4 v71, s[98:99]
	ds_read_b128 v[198:201], v120 offset:22528
	v_mfma_f32_16x16x32_bf16 v[20:23], v[134:137], v[76:79], v[20:23]
	v_mfma_f32_16x16x32_bf16 v[4:7], v[170:173], v[76:79], v[4:7]
	s_add_u32 m0, s44, 0x8000
	s_nop 0
	global_load_lds_dwordx4 v68, s[100:101]
	ds_read_b128 v[202:205], v121 offset:49152
	v_mfma_f32_16x16x32_bf16 v[48:51], v[84:87], v[92:95], v[48:51]
	v_mfma_f32_16x16x32_bf16 v[32:35], v[88:91], v[92:95], v[32:35]
	s_add_u32 m0, s44, 0x9000
	s_nop 0
	global_load_lds_dwordx4 v69, s[100:101]
	ds_read_b128 v[206:209], v121 offset:51200
	v_mfma_f32_16x16x32_bf16 v[16:19], v[134:137], v[92:95], v[16:19]
	v_mfma_f32_16x16x32_bf16 v[0:3], v[170:173], v[92:95], v[0:3]
	s_add_u32 m0, s44, 0xa000
	s_nop 0
	global_load_lds_dwordx4 v70, s[100:101]
	ds_read_b128 v[134:137], v121 offset:53248
	s_waitcnt lgkmcnt(2)
	v_mfma_f32_16x16x32_bf16 v[64:67], v[202:205], v[178:181], v[64:67]
	s_waitcnt lgkmcnt(1)
	v_mfma_f32_16x16x32_bf16 v[40:43], v[206:209], v[178:181], v[40:43]
	s_add_u32 m0, s44, 0xb000
	s_nop 0
	global_load_lds_dwordx4 v71, s[100:101]
	s_add_u32 s98, s98, 0x80
	s_addc_u32 s99, s99, 0
	s_add_u32 s100, s100, 0x80
	s_addc_u32 s101, s101, 0
	ds_read_b128 v[170:173], v121 offset:55296
	s_waitcnt lgkmcnt(1)
	v_mfma_f32_16x16x32_bf16 v[28:31], v[134:137], v[178:181], v[28:31]
	s_waitcnt lgkmcnt(0)
	v_mfma_f32_16x16x32_bf16 v[12:15], v[170:173], v[178:181], v[12:15]
	v_mfma_f32_16x16x32_bf16 v[60:63], v[202:205], v[186:189], v[60:63]
	v_mfma_f32_16x16x32_bf16 v[44:47], v[206:209], v[186:189], v[44:47]
	v_mfma_f32_16x16x32_bf16 v[24:27], v[134:137], v[186:189], v[24:27]
	v_mfma_f32_16x16x32_bf16 v[8:11], v[170:173], v[186:189], v[8:11]
	v_mfma_f32_16x16x32_bf16 v[52:55], v[202:205], v[190:193], v[52:55]
	v_mfma_f32_16x16x32_bf16 v[36:39], v[206:209], v[190:193], v[36:39]
	v_mfma_f32_16x16x32_bf16 v[20:23], v[134:137], v[190:193], v[20:23]
	v_mfma_f32_16x16x32_bf16 v[4:7], v[170:173], v[190:193], v[4:7]
	v_mfma_f32_16x16x32_bf16 v[48:51], v[202:205], v[198:201], v[48:51]
	v_mfma_f32_16x16x32_bf16 v[32:35], v[206:209], v[198:201], v[32:35]
	v_mfma_f32_16x16x32_bf16 v[16:19], v[134:137], v[198:201], v[16:19]
	v_mfma_f32_16x16x32_bf16 v[0:3], v[170:173], v[198:201], v[0:3]
	s_setprio 0
	s_mov_b32 s42, s33
	s_waitcnt vmcnt(0) lgkmcnt(0)
	s_barrier
	s_cmp_lt_u32 s42, 16
	s_cbranch_scc1 .LBB0_676
	s_waitcnt vmcnt(1)
	v_add_u32_e32 v88, s1, v122
	s_addk_i32 s1, 0xf000
	s_ashr_i32 s1, s1, 10
	s_add_i32 s1, s1, 1
	s_and_b64 s[42:43], s[22:23], exec
	s_cselect_b32 s1, 0, s1
	s_mul_i32 s2, s1, 0x3000
	s_add_i32 s28, s1, 5
	s_add_i32 s33, s2, 0xf000
	s_mul_hi_u32 s28, s28, 0x3000
	s_add_u32 s33, s4, s33
	s_addc_u32 s28, s5, s28
	s_add_u32 s44, s33, 0x2000
	s_addc_u32 s45, s28, 0
	s_add_i32 s1, s1, 10
	s_add_i32 s2, s2, 0x1e000
	s_mul_hi_u32 s1, s1, 0x3000
	s_add_u32 s2, s4, s2
	s_addc_u32 s1, s5, s1
	s_add_u32 s42, s2, 0x1000
	v_or_b32_e32 v96, s0, v123
	v_lshlrev_b64 v[72:73], 2, v[96:97]
	s_addc_u32 s43, s1, 0
	v_lshl_add_u64 v[56:57], s[44:45], 0, v[72:73]
	v_lshl_add_u64 v[70:71], s[12:13], 0, v[72:73]
	v_lshlrev_b32_e32 v58, 12, v88
	v_mov_b32_e32 v59, v97
	v_lshl_add_u64 v[74:75], s[42:43], 0, v[72:73]
	v_lshl_add_u64 v[68:69], v[70:71], 0, v[58:59]
	global_load_dwordx4 v[90:93], v[56:57], off
	s_nop 0
	global_load_dwordx4 v[56:59], v[68:69], off
	global_load_dwordx4 v[78:81], v[74:75], off
	v_lshl_add_u64 v[72:73], s[14:15], 0, v[72:73]
	global_load_dwordx4 v[82:85], v[72:73], off
	v_mov_b32_e32 v75, v97
	v_lshlrev_b32_e32 v74, 1, v96
	v_lshlrev_b32_e32 v89, 10, v88
	v_mov_b32_e32 v87, v97
	v_lshlrev_b32_e32 v86, 11, v88
	s_waitcnt vmcnt(4)
	v_lshl_add_u64 v[94:95], s[24:25], 0, v[74:75]
	v_or_b32_e32 v104, 0x4000, v89
	v_mov_b32_e32 v77, v97
	v_lshl_add_u64 v[74:75], v[94:95], 0, v[86:87]
	v_lshlrev_b32_e32 v76, 2, v104
	v_lshl_add_u64 v[98:99], v[70:71], 0, v[76:77]
	v_mov_b32_e32 v107, v97
	v_or_b32_e32 v106, 16, v96
	v_lshl_add_u64 v[86:87], s[24:25], 0, v[86:87]
	s_waitcnt vmcnt(2)
	v_pk_fma_f32 v[64:65], v[64:65], v[90:91], v[56:57]
	v_pk_fma_f32 v[66:67], v[66:67], v[92:93], v[58:59]
	s_waitcnt vmcnt(1)
	v_pk_add_f32 v[56:57], v[78:79], 1.0 op_sel_hi:[1,0]
	v_pk_add_f32 v[58:59], v[80:81], 1.0 op_sel_hi:[1,0]
	s_waitcnt vmcnt(0)
	v_pk_mul_f32 v[100:101], v[82:83], v[56:57]
	v_pk_mul_f32 v[102:103], v[84:85], v[58:59]
	v_pk_mul_f32 v[56:57], v[100:101], v[64:65]
	v_pk_mul_f32 v[58:59], v[102:103], v[66:67]
	v_cvt_pk_bf16_f32 v56, v56, v57
	v_cvt_pk_bf16_f32 v57, v58, v59
	global_store_dwordx4 v[68:69], v[64:67], off
	global_store_dwordx2 v[74:75], v[56:57], off
	global_load_dwordx4 v[56:59], v[98:99], off
	v_mov_b32_e32 v79, v97
	v_or_b32_e32 v82, 0x8000, v89
	v_lshlrev_b32_e32 v78, 1, v104
	v_mov_b32_e32 v81, v97
	v_lshlrev_b32_e32 v80, 2, v82
	v_lshl_add_u64 v[74:75], v[94:95], 0, v[78:79]
	v_lshl_add_u64 v[104:105], v[70:71], 0, v[80:81]
	v_mov_b32_e32 v83, v97
	v_or_b32_e32 v89, 0xc000, v89
	v_lshlrev_b32_e32 v82, 1, v82
	v_mov_b32_e32 v85, v97
	v_lshlrev_b32_e32 v84, 2, v89
	v_pk_mul_f32 v[64:65], v[64:65], v[64:65]
	v_pk_mul_f32 v[66:67], v[66:67], v[66:67]
	v_add_f32_e32 v64, v64, v65
	v_add_f32_e32 v64, v66, v64
	v_add_f32_e32 v64, v67, v64
	s_waitcnt vmcnt(0)
	v_pk_fma_f32 v[56:57], v[60:61], v[90:91], v[56:57]
	v_pk_fma_f32 v[58:59], v[62:63], v[92:93], v[58:59]
	v_pk_mul_f32 v[60:61], v[100:101], v[56:57]
	v_pk_mul_f32 v[62:63], v[102:103], v[58:59]
	v_cvt_pk_bf16_f32 v60, v60, v61
	v_cvt_pk_bf16_f32 v61, v62, v63
	global_store_dwordx4 v[98:99], v[56:59], off
	global_store_dwordx2 v[74:75], v[60:61], off
	global_load_dwordx4 v[60:63], v[104:105], off
	v_lshl_add_u64 v[74:75], v[94:95], 0, v[82:83]
	v_lshl_add_u64 v[98:99], v[70:71], 0, v[84:85]
	s_waitcnt vmcnt(0)
	v_pk_fma_f32 v[52:53], v[52:53], v[90:91], v[60:61]
	v_pk_fma_f32 v[54:55], v[54:55], v[92:93], v[62:63]
	v_pk_mul_f32 v[60:61], v[100:101], v[52:53]
	v_pk_mul_f32 v[62:63], v[102:103], v[54:55]
	v_cvt_pk_bf16_f32 v60, v60, v61
	v_cvt_pk_bf16_f32 v61, v62, v63
	global_store_dwordx4 v[104:105], v[52:55], off
	global_store_dwordx2 v[74:75], v[60:61], off
	global_load_dwordx4 v[60:63], v[98:99], off
	v_mov_b32_e32 v75, v97
	v_lshlrev_b32_e32 v74, 1, v89
	v_lshlrev_b64 v[104:105], 2, v[106:107]
	v_lshl_add_u64 v[94:95], v[94:95], 0, v[74:75]
	v_lshl_add_u64 v[108:109], s[44:45], 0, v[104:105]
	s_waitcnt vmcnt(0)
	v_pk_fma_f32 v[48:49], v[48:49], v[90:91], v[60:61]
	v_pk_fma_f32 v[50:51], v[50:51], v[92:93], v[62:63]
	v_pk_mul_f32 v[60:61], v[100:101], v[48:49]
	v_pk_mul_f32 v[62:63], v[102:103], v[50:51]
	v_cvt_pk_bf16_f32 v60, v60, v61
	v_cvt_pk_bf16_f32 v61, v62, v63
	global_store_dwordx4 v[98:99], v[48:51], off
	global_store_dwordx2 v[94:95], v[60:61], off
	global_load_dwordx4 v[90:93], v[108:109], off
	s_nop 0
	global_load_dwordx4 v[60:63], v[68:69], off offset:64
	v_lshl_add_u64 v[94:95], s[42:43], 0, v[104:105]
	global_load_dwordx4 v[98:101], v[94:95], off
	global_load_dwordx4 v[102:105], v[72:73], off offset:64
	v_mov_b32_e32 v95, v97
	v_lshlrev_b32_e32 v94, 1, v106
	v_lshl_add_u64 v[106:107], v[70:71], 0, 64
	v_lshl_add_u64 v[108:109], v[86:87], 0, v[94:95]
	v_lshl_add_u64 v[110:111], v[106:107], 0, v[76:77]
	v_lshl_add_u64 v[94:95], s[24:25], 0, v[94:95]
	s_waitcnt vmcnt(2)
	v_pk_fma_f32 v[60:61], v[40:41], v[90:91], v[60:61]
	v_pk_fma_f32 v[62:63], v[42:43], v[92:93], v[62:63]
	s_waitcnt vmcnt(1)
	v_pk_add_f32 v[40:41], v[98:99], 1.0 op_sel_hi:[1,0]
	v_pk_add_f32 v[42:43], v[100:101], 1.0 op_sel_hi:[1,0]
	s_waitcnt vmcnt(0)
	v_pk_mul_f32 v[98:99], v[102:103], v[40:41]
	v_pk_mul_f32 v[100:101], v[104:105], v[42:43]
	v_pk_mul_f32 v[40:41], v[98:99], v[60:61]
	v_pk_mul_f32 v[42:43], v[100:101], v[62:63]
	v_cvt_pk_bf16_f32 v40, v40, v41
	v_cvt_pk_bf16_f32 v41, v42, v43
	global_store_dwordx4 v[68:69], v[60:63], off offset:64
	global_store_dwordx2 v[108:109], v[40:41], off
	global_load_dwordx4 v[40:43], v[110:111], off
	v_lshl_add_u64 v[102:103], v[94:95], 0, v[78:79]
	v_lshl_add_u64 v[104:105], v[106:107], 0, v[80:81]
	v_lshl_add_u64 v[106:107], v[106:107], 0, v[84:85]
	v_mov_b32_e32 v109, v97
	v_or_b32_e32 v108, 32, v96
	v_or_b32_e32 v96, 48, v96
	v_pk_mul_f32 v[60:61], v[60:61], v[60:61]
	v_pk_mul_f32 v[62:63], v[62:63], v[62:63]
	v_add_f32_e32 v60, v60, v61
	v_add_f32_e32 v60, v62, v60
	v_add_f32_e32 v60, v63, v60
	v_add_f32_e32 v60, v64, v60
	s_waitcnt vmcnt(0)
	v_pk_fma_f32 v[40:41], v[44:45], v[90:91], v[40:41]
	v_pk_fma_f32 v[42:43], v[46:47], v[92:93], v[42:43]
	v_pk_mul_f32 v[44:45], v[98:99], v[40:41]
	v_pk_mul_f32 v[46:47], v[100:101], v[42:43]
	v_cvt_pk_bf16_f32 v44, v44, v45
	v_cvt_pk_bf16_f32 v45, v46, v47
	global_store_dwordx4 v[110:111], v[40:43], off
	global_store_dwordx2 v[102:103], v[44:45], off
	global_load_dwordx4 v[44:47], v[104:105], off
	v_lshl_add_u64 v[102:103], v[94:95], 0, v[82:83]
	v_lshl_add_u64 v[94:95], v[94:95], 0, v[74:75]
	s_waitcnt vmcnt(0)
	v_pk_fma_f32 v[36:37], v[36:37], v[90:91], v[44:45]
	v_pk_fma_f32 v[38:39], v[38:39], v[92:93], v[46:47]
	v_pk_mul_f32 v[44:45], v[98:99], v[36:37]
	v_pk_mul_f32 v[46:47], v[100:101], v[38:39]
	v_cvt_pk_bf16_f32 v44, v44, v45
	v_cvt_pk_bf16_f32 v45, v46, v47
	global_store_dwordx4 v[104:105], v[36:39], off
	global_store_dwordx2 v[102:103], v[44:45], off
	global_load_dwordx4 v[44:47], v[106:107], off
	v_lshlrev_b64 v[102:103], 2, v[108:109]
	v_lshl_add_u64 v[104:105], s[44:45], 0, v[102:103]
	s_waitcnt vmcnt(0)
	v_pk_fma_f32 v[32:33], v[32:33], v[90:91], v[44:45]
	v_pk_fma_f32 v[34:35], v[34:35], v[92:93], v[46:47]
	v_pk_mul_f32 v[44:45], v[98:99], v[32:33]
	v_pk_mul_f32 v[46:47], v[100:101], v[34:35]
	v_cvt_pk_bf16_f32 v44, v44, v45
	v_cvt_pk_bf16_f32 v45, v46, v47
	global_store_dwordx4 v[106:107], v[32:35], off
	global_store_dwordx2 v[94:95], v[44:45], off
	global_load_dwordx4 v[44:47], v[104:105], off
	s_nop 0
	global_load_dwordx4 v[90:93], v[68:69], off offset:128
	v_lshl_add_u64 v[94:95], s[42:43], 0, v[102:103]
	global_load_dwordx4 v[98:101], v[94:95], off
	global_load_dwordx4 v[102:105], v[72:73], off offset:128
	v_mov_b32_e32 v95, v97
	v_lshlrev_b32_e32 v94, 1, v108
	v_lshl_add_u64 v[106:107], v[70:71], 0, s[38:39]
	v_lshl_add_u64 v[108:109], v[86:87], 0, v[94:95]
	v_lshl_add_u64 v[110:111], v[106:107], 0, v[76:77]
	v_lshl_add_u64 v[94:95], s[24:25], 0, v[94:95]
	s_waitcnt vmcnt(2)
	v_pk_fma_f32 v[28:29], v[28:29], v[44:45], v[90:91]
	v_pk_fma_f32 v[30:31], v[30:31], v[46:47], v[92:93]
	s_waitcnt vmcnt(1)
	v_pk_add_f32 v[90:91], v[98:99], 1.0 op_sel_hi:[1,0]
	v_pk_add_f32 v[92:93], v[100:101], 1.0 op_sel_hi:[1,0]
	s_waitcnt vmcnt(0)
	v_pk_mul_f32 v[98:99], v[102:103], v[90:91]
	v_pk_mul_f32 v[100:101], v[104:105], v[92:93]
	v_pk_mul_f32 v[90:91], v[98:99], v[28:29]
	v_pk_mul_f32 v[92:93], v[100:101], v[30:31]
	v_cvt_pk_bf16_f32 v90, v90, v91
	v_cvt_pk_bf16_f32 v91, v92, v93
	global_store_dwordx4 v[68:69], v[28:31], off offset:128
	global_store_dwordx2 v[108:109], v[90:91], off
	global_load_dwordx4 v[90:93], v[110:111], off
	v_lshl_add_u64 v[102:103], v[94:95], 0, v[78:79]
	v_lshl_add_u64 v[104:105], v[106:107], 0, v[80:81]
	v_lshl_add_u64 v[106:107], v[106:107], 0, v[84:85]
	v_pk_mul_f32 v[28:29], v[28:29], v[28:29]
	v_pk_mul_f32 v[30:31], v[30:31], v[30:31]
	v_add_f32_e32 v28, v28, v29
	v_add_f32_e32 v28, v30, v28
	v_add_f32_e32 v28, v31, v28
	v_add_f32_e32 v28, v60, v28
	s_waitcnt vmcnt(0)
	v_pk_fma_f32 v[24:25], v[24:25], v[44:45], v[90:91]
	v_pk_fma_f32 v[26:27], v[26:27], v[46:47], v[92:93]
	v_pk_mul_f32 v[90:91], v[98:99], v[24:25]
	v_pk_mul_f32 v[92:93], v[100:101], v[26:27]
	v_cvt_pk_bf16_f32 v90, v90, v91
	v_cvt_pk_bf16_f32 v91, v92, v93
	global_store_dwordx4 v[110:111], v[24:27], off
	global_store_dwordx2 v[102:103], v[90:91], off
	global_load_dwordx4 v[90:93], v[104:105], off
	v_lshl_add_u64 v[102:103], v[94:95], 0, v[82:83]
	v_lshl_add_u64 v[94:95], v[94:95], 0, v[74:75]
	s_waitcnt vmcnt(0)
	v_pk_fma_f32 v[20:21], v[20:21], v[44:45], v[90:91]
	v_pk_fma_f32 v[22:23], v[22:23], v[46:47], v[92:93]
	v_pk_mul_f32 v[90:91], v[98:99], v[20:21]
	v_pk_mul_f32 v[92:93], v[100:101], v[22:23]
	v_cvt_pk_bf16_f32 v90, v90, v91
	v_cvt_pk_bf16_f32 v91, v92, v93
	global_store_dwordx4 v[104:105], v[20:23], off
	global_store_dwordx2 v[102:103], v[90:91], off
	global_load_dwordx4 v[90:93], v[106:107], off
	v_lshlrev_b64 v[102:103], 2, v[96:97]
	v_lshl_add_u64 v[104:105], s[44:45], 0, v[102:103]
	v_lshlrev_b32_e32 v96, 1, v96
	s_waitcnt vmcnt(0)
	v_pk_fma_f32 v[16:17], v[16:17], v[44:45], v[90:91]
	v_pk_fma_f32 v[18:19], v[18:19], v[46:47], v[92:93]
	v_pk_mul_f32 v[44:45], v[98:99], v[16:17]
	v_pk_mul_f32 v[46:47], v[100:101], v[18:19]
	v_cvt_pk_bf16_f32 v44, v44, v45
	v_cvt_pk_bf16_f32 v45, v46, v47
	global_store_dwordx4 v[106:107], v[16:19], off
	global_store_dwordx2 v[94:95], v[44:45], off
	global_load_dwordx4 v[44:47], v[104:105], off
	s_nop 0
	global_load_dwordx4 v[90:93], v[68:69], off offset:192
	v_lshl_add_u64 v[94:95], s[42:43], 0, v[102:103]
	global_load_dwordx4 v[98:101], v[94:95], off
	global_load_dwordx4 v[102:105], v[72:73], off offset:192
	v_lshl_add_u64 v[72:73], v[70:71], 0, s[40:41]
	v_lshl_add_u64 v[70:71], v[86:87], 0, v[96:97]
	v_lshl_add_u64 v[76:77], v[72:73], 0, v[76:77]
	v_lshl_add_u64 v[80:81], v[72:73], 0, v[80:81]
	v_lshl_add_u64 v[72:73], v[72:73], 0, v[84:85]
	s_waitcnt vmcnt(2)
	v_pk_fma_f32 v[12:13], v[12:13], v[44:45], v[90:91]
	s_waitcnt vmcnt(1)
	v_pk_add_f32 v[86:87], v[98:99], 1.0 op_sel_hi:[1,0]
	v_pk_add_f32 v[90:91], v[100:101], 1.0 op_sel_hi:[1,0]
	v_pk_fma_f32 v[14:15], v[14:15], v[46:47], v[92:93]
	s_waitcnt vmcnt(0)
	v_pk_mul_f32 v[86:87], v[102:103], v[86:87]
	v_pk_mul_f32 v[90:91], v[104:105], v[90:91]
	global_store_dwordx4 v[68:69], v[12:15], off offset:192
	v_pk_mul_f32 v[68:69], v[86:87], v[12:13]
	v_pk_mul_f32 v[92:93], v[90:91], v[14:15]
	v_cvt_pk_bf16_f32 v68, v68, v69
	v_cvt_pk_bf16_f32 v69, v92, v93
	global_store_dwordx2 v[70:71], v[68:69], off
	global_load_dwordx4 v[68:71], v[76:77], off
	v_lshl_add_u64 v[92:93], s[24:25], 0, v[96:97]
	v_lshl_add_u64 v[78:79], v[92:93], 0, v[78:79]
	v_pk_mul_f32 v[12:13], v[12:13], v[12:13]
	v_pk_mul_f32 v[14:15], v[14:15], v[14:15]
	v_add_f32_e32 v12, v12, v13
	v_add_f32_e32 v12, v14, v12
	v_add_f32_e32 v12, v15, v12
	v_add_f32_e32 v14, v28, v12
	ds_bpermute_b32 v15, v124, v14
	v_lshlrev_b32_e32 v96, 2, v88
	v_lshl_add_u64 v[12:13], v[92:93], 0, v[74:75]
	s_waitcnt lgkmcnt(0)
	v_add_f32_e32 v14, v14, v15
	ds_bpermute_b32 v15, v125, v14
	s_waitcnt vmcnt(0)
	v_pk_fma_f32 v[8:9], v[8:9], v[44:45], v[68:69]
	v_pk_fma_f32 v[10:11], v[10:11], v[46:47], v[70:71]
	v_pk_mul_f32 v[68:69], v[86:87], v[8:9]
	v_pk_mul_f32 v[70:71], v[90:91], v[10:11]
	v_cvt_pk_bf16_f32 v68, v68, v69
	v_cvt_pk_bf16_f32 v69, v70, v71
	global_store_dwordx4 v[76:77], v[8:11], off
	global_store_dwordx2 v[78:79], v[68:69], off
	global_load_dwordx4 v[68:71], v[80:81], off
	v_lshl_add_u64 v[76:77], v[92:93], 0, v[82:83]
	s_waitcnt vmcnt(0)
	v_pk_fma_f32 v[4:5], v[4:5], v[44:45], v[68:69]
	v_pk_fma_f32 v[6:7], v[6:7], v[46:47], v[70:71]
	v_pk_mul_f32 v[68:69], v[86:87], v[4:5]
	v_pk_mul_f32 v[70:71], v[90:91], v[6:7]
	v_cvt_pk_bf16_f32 v68, v68, v69
	v_cvt_pk_bf16_f32 v69, v70, v71
	global_store_dwordx4 v[80:81], v[4:7], off
	global_store_dwordx2 v[76:77], v[68:69], off
	global_load_dwordx4 v[68:71], v[72:73], off
	s_waitcnt vmcnt(0)
	v_pk_fma_f32 v[0:1], v[0:1], v[44:45], v[68:69]
	v_pk_fma_f32 v[2:3], v[2:3], v[46:47], v[70:71]
	v_pk_mul_f32 v[28:29], v[86:87], v[0:1]
	v_pk_mul_f32 v[30:31], v[90:91], v[2:3]
	v_cvt_pk_bf16_f32 v28, v28, v29
	v_cvt_pk_bf16_f32 v29, v30, v31
	global_store_dwordx4 v[72:73], v[0:3], off
	global_store_dwordx2 v[12:13], v[28:29], off
	v_lshl_add_u64 v[12:13], s[26:27], 0, v[96:97]
	s_and_saveexec_b64 s[42:43], s[10:11]
	s_cbranch_execz .LBB0_679
	s_waitcnt lgkmcnt(0)
	v_add_f32_e32 v14, v14, v15
	global_atomic_add_f32 v[12:13], v14, off

.LBB0_739:
	s_and_b32 s8, s7, 7
	s_or_b32 s8, s8, s0
	s_lshl_b32 s8, s8, 7
	v_or_b32_e32 v0, s8, v149
	v_lshl_or_b32 v96, v0, 11, v116
	s_waitcnt vmcnt(1)
	v_lshl_add_u64 v[100:101], s[18:19], 0, v[96:97]
	v_add_co_u32_e32 v2, vcc, 0x10000, v100
	s_lshl_b32 s9, s7, 4
	s_nop 0
	v_addc_co_u32_e32 v3, vcc, 0, v101, vcc
	s_and_b32 s9, s9, 0x7fffff80
	v_add_co_u32_e32 v4, vcc, 0x20000, v100
	v_or_b32_e32 v0, s9, v149
	s_nop 0
	v_addc_co_u32_e32 v5, vcc, 0, v101, vcc
	v_lshl_or_b32 v98, v0, 11, v116
	v_add_co_u32_e32 v6, vcc, 0x30000, v100
	v_mov_b32_e32 v99, v97
	s_nop 0
	v_addc_co_u32_e32 v7, vcc, 0, v101, vcc
	v_lshl_add_u64 v[102:103], s[16:17], 0, v[98:99]
	v_add_co_u32_e32 v12, vcc, s3, v102
	s_nop 0
	v_addc_co_u32_e32 v13, vcc, 0, v103, vcc
	v_add_co_u32_e32 v14, vcc, s4, v102
	s_nop 0
	v_addc_co_u32_e32 v15, vcc, 0, v103, vcc
	v_add_co_u32_e32 v48, vcc, s5, v102
	s_nop 0
	v_addc_co_u32_e32 v49, vcc, 0, v103, vcc
	s_movk_i32 s10, 0x100
	s_mov_b32 s12, s35
	v_mov_b32_e32 v8, 0
	v_mov_b32_e32 v9, v97
	v_mov_b32_e32 v10, v97
	v_mov_b32_e32 v11, v97
	v_mov_b32_e32 v0, 0
	v_mov_b32_e32 v1, v97
	v_mov_b32_e32 v2, v97
	v_mov_b32_e32 v3, v97
	v_mov_b32_e32 v12, 0
	v_mov_b32_e32 v13, v97
	v_mov_b32_e32 v14, v97
	v_mov_b32_e32 v15, v97
	v_mov_b32_e32 v4, 0
	v_mov_b32_e32 v5, v97
	v_lshl_add_u64 v[104:105], v[102:103], 0, s[26:27]
	v_lshl_add_u64 v[106:107], v[102:103], 0, s[28:29]
	v_lshl_add_u64 v[108:109], v[102:103], 0, s[30:31]
	v_lshl_add_u64 v[110:111], v[100:101], 0, s[26:27]
	v_lshl_add_u64 v[112:113], v[100:101], 0, s[28:29]
	v_lshl_add_u64 v[114:115], v[100:101], 0, s[30:31]
	s_barrier
	v_mov_b32_e32 v6, v97
	v_mov_b32_e32 v7, v97
	v_mov_b32_e32 v48, 0
	v_mov_b32_e32 v49, v97
	v_mov_b32_e32 v50, v97
	v_mov_b32_e32 v51, v97
	v_mov_b32_e32 v60, 0
	v_mov_b32_e32 v61, v97
	v_mov_b32_e32 v62, v97
	v_mov_b32_e32 v63, v97
	v_mov_b32_e32 v56, 0
	v_mov_b32_e32 v57, v97
	v_mov_b32_e32 v58, v97
	v_mov_b32_e32 v59, v97
	v_mov_b32_e32 v52, 0
	v_mov_b32_e32 v53, v97
	v_mov_b32_e32 v54, v97
	v_mov_b32_e32 v55, v97
	v_mov_b32_e32 v32, 0
	v_mov_b32_e32 v33, v97
	v_mov_b32_e32 v34, v97
	v_mov_b32_e32 v35, v97
	v_mov_b32_e32 v24, 0
	v_mov_b32_e32 v25, v97
	v_mov_b32_e32 v26, v97
	v_mov_b32_e32 v27, v97
	v_mov_b32_e32 v20, 0
	v_mov_b32_e32 v21, v97
	v_mov_b32_e32 v22, v97
	v_mov_b32_e32 v23, v97
	v_mov_b32_e32 v16, 0
	v_mov_b32_e32 v17, v97
	v_mov_b32_e32 v18, v97
	v_mov_b32_e32 v19, v97
	v_mov_b32_e32 v40, 0
	v_mov_b32_e32 v41, v97
	v_mov_b32_e32 v42, v97
	v_mov_b32_e32 v43, v97
	v_mov_b32_e32 v36, 0
	v_mov_b32_e32 v37, v97
	v_mov_b32_e32 v38, v97
	v_mov_b32_e32 v39, v97
	v_mov_b32_e32 v28, 0
	v_mov_b32_e32 v29, v97
	v_mov_b32_e32 v30, v97
	v_mov_b32_e32 v31, v97
	v_mov_b32_e32 v44, 0
	v_mov_b32_e32 v45, v97
	v_mov_b32_e32 v46, v97
	v_mov_b32_e32 v47, v97
	v_readlane_b32 s100, v253, 0
	v_readlane_b32 s101, v253, 1
	s_load_dwordx2 s[100:101], s[100:101], 0x160
	v_lshrrev_b32_e32 v71, 6, v146
	s_nop 0
	v_readfirstlane_b32 s14, v71
	v_lshrrev_b32_e32 v69, 3, v146
	v_and_b32_e32 v70, 7, v146
	v_xor_b32_e32 v70, v69, v70
	v_and_b32_e32 v70, 7, v70
	v_lshlrev_b32_e32 v70, 4, v70
	v_lshl_or_b32 v68, v69, 11, v70
	v_add_u32_e32 v69, 0x10000, v68
	v_add_u32_e32 v70, 0x20000, v68
	v_add_u32_e32 v71, 0x30000, v68
	s_and_b32 s98, s7, 7
	s_and_b32 s99, s69, 7
	s_lshl_b32 s99, s99, 3
	s_or_b32 s98, s98, s99
	s_lshl_b32 s98, s98, 18
	s_add_u32 s98, s98, 0xdc40000
	s_lshr_b32 s99, s7, 3
	s_lshl_b32 s99, s99, 18
	s_add_u32 s99, s99, 0x7f00000
	s_lshl_b32 s14, s14, 10
	s_waitcnt lgkmcnt(0)
	s_mov_b32 m0, s99
	s_add_u32 s98, s100, s98
	s_addc_u32 s99, s101, 0
	s_add_u32 s100, s100, m0
	s_addc_u32 s101, s101, 0
	s_add_u32 m0, s14, 0x0
	s_nop 0
	global_load_lds_dwordx4 v68, s[98:99]
	s_add_u32 m0, s14, 0x1000
	s_nop 0
	global_load_lds_dwordx4 v69, s[98:99]
	s_add_u32 m0, s14, 0x2000
	s_nop 0
	global_load_lds_dwordx4 v70, s[98:99]
	s_add_u32 m0, s14, 0x3000
	s_nop 0
	global_load_lds_dwordx4 v71, s[98:99]
	s_add_u32 m0, s14, 0x8000
	s_nop 0
	global_load_lds_dwordx4 v68, s[100:101]
	s_add_u32 m0, s14, 0x9000
	s_nop 0
	global_load_lds_dwordx4 v69, s[100:101]
	s_add_u32 m0, s14, 0xa000
	s_nop 0
	global_load_lds_dwordx4 v70, s[100:101]
	s_add_u32 m0, s14, 0xb000
	s_nop 0
	global_load_lds_dwordx4 v71, s[100:101]
	s_add_u32 s98, s98, 0x80
	s_addc_u32 s99, s99, 0
	s_add_u32 s100, s100, 0x80
	s_addc_u32 s101, s101, 0
	s_waitcnt vmcnt(0)
	s_waitcnt lgkmcnt(0)
	s_barrier
.LBB0_740:
	s_add_i32 s11, s12, 2
	s_setprio 1
	ds_read_b128 v[124:127], v119 offset:32768
	ds_read_b128 v[132:135], v119 offset:34816
	ds_read_b128 v[128:131], v118
	ds_read_b128 v[136:139], v118 offset:2048
	ds_read_b128 v[140:143], v118 offset:4096
	ds_read_b128 v[162:165], v118 offset:6144
	s_waitcnt lgkmcnt(3)
	v_mfma_f32_16x16x32_bf16 v[8:11], v[124:127], v[128:131], v[8:11]
	ds_read_b128 v[166:169], v119 offset:36864
	v_mfma_f32_16x16x32_bf16 v[0:3], v[132:135], v[128:131], v[0:3]
	ds_read_b128 v[170:173], v119 offset:38912
	s_waitcnt lgkmcnt(1)
	v_mfma_f32_16x16x32_bf16 v[12:15], v[166:169], v[128:131], v[12:15]
	s_waitcnt lgkmcnt(0)
	v_mfma_f32_16x16x32_bf16 v[4:7], v[170:173], v[128:131], v[4:7]
	s_add_u32 m0, s14, 0x4000
	s_nop 0
	global_load_lds_dwordx4 v68, s[98:99]
	ds_read_b128 v[174:177], v120
	v_mfma_f32_16x16x32_bf16 v[32:35], v[124:127], v[136:139], v[32:35]
	v_mfma_f32_16x16x32_bf16 v[24:27], v[132:135], v[136:139], v[24:27]
	s_add_u32 m0, s14, 0x5000
	s_nop 0
	global_load_lds_dwordx4 v69, s[98:99]
	ds_read_b128 v[182:185], v120 offset:2048
	v_mfma_f32_16x16x32_bf16 v[20:23], v[166:169], v[136:139], v[20:23]
	v_mfma_f32_16x16x32_bf16 v[16:19], v[170:173], v[136:139], v[16:19]
	s_add_u32 m0, s14, 0x6000
	s_nop 0
	global_load_lds_dwordx4 v70, s[98:99]
	ds_read_b128 v[186:189], v120 offset:4096
	v_mfma_f32_16x16x32_bf16 v[48:51], v[124:127], v[140:143], v[48:51]
	v_mfma_f32_16x16x32_bf16 v[40:43], v[132:135], v[140:143], v[40:43]
	s_add_u32 m0, s14, 0x7000
	s_nop 0
	global_load_lds_dwordx4 v71, s[98:99]
	ds_read_b128 v[194:197], v120 offset:6144
	v_mfma_f32_16x16x32_bf16 v[36:39], v[166:169], v[140:143], v[36:39]
	v_mfma_f32_16x16x32_bf16 v[28:31], v[170:173], v[140:143], v[28:31]
	s_add_u32 m0, s14, 0xc000
	s_nop 0
	global_load_lds_dwordx4 v68, s[100:101]
	ds_read_b128 v[198:201], v121 offset:32768
	v_mfma_f32_16x16x32_bf16 v[60:63], v[124:127], v[162:165], v[60:63]
	v_mfma_f32_16x16x32_bf16 v[56:59], v[132:135], v[162:165], v[56:59]
	s_add_u32 m0, s14, 0xd000
	s_nop 0
	global_load_lds_dwordx4 v69, s[100:101]
	ds_read_b128 v[132:135], v121 offset:34816
	v_mfma_f32_16x16x32_bf16 v[52:55], v[166:169], v[162:165], v[52:55]
	v_mfma_f32_16x16x32_bf16 v[44:47], v[170:173], v[162:165], v[44:47]
	s_add_u32 m0, s14, 0xe000
	s_nop 0
	global_load_lds_dwordx4 v70, s[100:101]
	ds_read_b128 v[166:169], v121 offset:36864
	s_waitcnt lgkmcnt(2)
	v_mfma_f32_16x16x32_bf16 v[8:11], v[198:201], v[174:177], v[8:11]
	s_waitcnt lgkmcnt(1)
	v_mfma_f32_16x16x32_bf16 v[0:3], v[132:135], v[174:177], v[0:3]
	s_add_u32 m0, s14, 0xf000
	s_nop 0
	global_load_lds_dwordx4 v71, s[100:101]
	s_add_u32 s98, s98, 0x80
	s_addc_u32 s99, s99, 0
	s_add_u32 s100, s100, 0x80
	s_addc_u32 s101, s101, 0
	ds_read_b128 v[202:205], v121 offset:38912
	s_waitcnt lgkmcnt(1)
	v_mfma_f32_16x16x32_bf16 v[12:15], v[166:169], v[174:177], v[12:15]
	s_waitcnt lgkmcnt(0)
	v_mfma_f32_16x16x32_bf16 v[4:7], v[202:205], v[174:177], v[4:7]
	v_mfma_f32_16x16x32_bf16 v[32:35], v[198:201], v[182:185], v[32:35]
	v_mfma_f32_16x16x32_bf16 v[24:27], v[132:135], v[182:185], v[24:27]
	v_mfma_f32_16x16x32_bf16 v[20:23], v[166:169], v[182:185], v[20:23]
	v_mfma_f32_16x16x32_bf16 v[16:19], v[202:205], v[182:185], v[16:19]
	v_mfma_f32_16x16x32_bf16 v[48:51], v[198:201], v[186:189], v[48:51]
	v_mfma_f32_16x16x32_bf16 v[40:43], v[132:135], v[186:189], v[40:43]
	v_mfma_f32_16x16x32_bf16 v[36:39], v[166:169], v[186:189], v[36:39]
	v_mfma_f32_16x16x32_bf16 v[28:31], v[202:205], v[186:189], v[28:31]
	v_mfma_f32_16x16x32_bf16 v[60:63], v[198:201], v[194:197], v[60:63]
	v_mfma_f32_16x16x32_bf16 v[56:59], v[132:135], v[194:197], v[56:59]
	v_mfma_f32_16x16x32_bf16 v[52:55], v[166:169], v[194:197], v[52:55]
	v_mfma_f32_16x16x32_bf16 v[44:47], v[202:205], v[194:197], v[44:47]
	s_setprio 0
	s_waitcnt vmcnt(0) lgkmcnt(0)
	s_barrier
	s_setprio 1
	ds_read_b128 v[84:87], v119 offset:49152
	ds_read_b128 v[88:91], v119 offset:51200
	ds_read_b128 v[64:67], v118 offset:16384
	ds_read_b128 v[72:75], v118 offset:18432
	ds_read_b128 v[76:79], v118 offset:20480
	ds_read_b128 v[92:95], v118 offset:22528
	s_waitcnt lgkmcnt(3)
	v_mfma_f32_16x16x32_bf16 v[8:11], v[84:87], v[64:67], v[8:11]
	ds_read_b128 v[132:135], v119 offset:53248
	v_mfma_f32_16x16x32_bf16 v[0:3], v[88:91], v[64:67], v[0:3]
	ds_read_b128 v[166:169], v119 offset:55296
	s_waitcnt lgkmcnt(1)
	v_mfma_f32_16x16x32_bf16 v[12:15], v[132:135], v[64:67], v[12:15]
	s_waitcnt lgkmcnt(0)
	v_mfma_f32_16x16x32_bf16 v[4:7], v[166:169], v[64:67], v[4:7]
	s_add_u32 m0, s14, 0x0
	s_nop 0
	global_load_lds_dwordx4 v68, s[98:99]
	ds_read_b128 v[174:177], v120 offset:16384
	v_mfma_f32_16x16x32_bf16 v[32:35], v[84:87], v[72:75], v[32:35]
	v_mfma_f32_16x16x32_bf16 v[24:27], v[88:91], v[72:75], v[24:27]
	s_add_u32 m0, s14, 0x1000
	s_nop 0
	global_load_lds_dwordx4 v69, s[98:99]
	ds_read_b128 v[182:185], v120 offset:18432
	v_mfma_f32_16x16x32_bf16 v[20:23], v[132:135], v[72:75], v[20:23]
	v_mfma_f32_16x16x32_bf16 v[16:19], v[166:169], v[72:75], v[16:19]
	s_add_u32 m0, s14, 0x2000
	s_nop 0
	global_load_lds_dwordx4 v70, s[98:99]
	ds_read_b128 v[186:189], v120 offset:20480
	v_mfma_f32_16x16x32_bf16 v[48:51], v[84:87], v[76:79], v[48:51]
	v_mfma_f32_16x16x32_bf16 v[40:43], v[88:91], v[76:79], v[40:43]
	s_add_u32 m0, s14, 0x3000
	s_nop 0
	global_load_lds_dwordx4 v71, s[98:99]
	ds_read_b128 v[194:197], v120 offset:22528
	v_mfma_f32_16x16x32_bf16 v[36:39], v[132:135], v[76:79], v[36:39]
	v_mfma_f32_16x16x32_bf16 v[28:31], v[166:169], v[76:79], v[28:31]
	s_add_u32 m0, s14, 0x8000
	s_nop 0
	global_load_lds_dwordx4 v68, s[100:101]
	ds_read_b128 v[198:201], v121 offset:49152
	v_mfma_f32_16x16x32_bf16 v[60:63], v[84:87], v[92:95], v[60:63]
	v_mfma_f32_16x16x32_bf16 v[56:59], v[88:91], v[92:95], v[56:59]
	s_add_u32 m0, s14, 0x9000
	s_nop 0
	global_load_lds_dwordx4 v69, s[100:101]
	ds_read_b128 v[202:205], v121 offset:51200
	v_mfma_f32_16x16x32_bf16 v[52:55], v[132:135], v[92:95], v[52:55]
	v_mfma_f32_16x16x32_bf16 v[44:47], v[166:169], v[92:95], v[44:47]
	s_add_u32 m0, s14, 0xa000
	s_nop 0
	global_load_lds_dwordx4 v70, s[100:101]
	ds_read_b128 v[132:135], v121 offset:53248
	s_waitcnt lgkmcnt(2)
	v_mfma_f32_16x16x32_bf16 v[8:11], v[198:201], v[174:177], v[8:11]
	s_waitcnt lgkmcnt(1)
	v_mfma_f32_16x16x32_bf16 v[0:3], v[202:205], v[174:177], v[0:3]
	s_add_u32 m0, s14, 0xb000
	s_nop 0
	global_load_lds_dwordx4 v71, s[100:101]
	s_add_u32 s98, s98, 0x80
	s_addc_u32 s99, s99, 0
	s_add_u32 s100, s100, 0x80
	s_addc_u32 s101, s101, 0
	ds_read_b128 v[166:169], v121 offset:55296
	s_waitcnt lgkmcnt(1)
	v_mfma_f32_16x16x32_bf16 v[12:15], v[132:135], v[174:177], v[12:15]
	s_waitcnt lgkmcnt(0)
	v_mfma_f32_16x16x32_bf16 v[4:7], v[166:169], v[174:177], v[4:7]
	v_mfma_f32_16x16x32_bf16 v[32:35], v[198:201], v[182:185], v[32:35]
	v_mfma_f32_16x16x32_bf16 v[24:27], v[202:205], v[182:185], v[24:27]
	v_mfma_f32_16x16x32_bf16 v[20:23], v[132:135], v[182:185], v[20:23]
	v_mfma_f32_16x16x32_bf16 v[16:19], v[166:169], v[182:185], v[16:19]
	v_mfma_f32_16x16x32_bf16 v[48:51], v[198:201], v[186:189], v[48:51]
	v_mfma_f32_16x16x32_bf16 v[40:43], v[202:205], v[186:189], v[40:43]
	v_mfma_f32_16x16x32_bf16 v[36:39], v[132:135], v[186:189], v[36:39]
	v_mfma_f32_16x16x32_bf16 v[28:31], v[166:169], v[186:189], v[28:31]
	v_mfma_f32_16x16x32_bf16 v[60:63], v[198:201], v[194:197], v[60:63]
	v_mfma_f32_16x16x32_bf16 v[56:59], v[202:205], v[194:197], v[56:59]
	v_mfma_f32_16x16x32_bf16 v[52:55], v[132:135], v[194:197], v[52:55]
	v_mfma_f32_16x16x32_bf16 v[44:47], v[166:169], v[194:197], v[44:47]
	s_setprio 0
	s_mov_b32 s12, s11
	s_waitcnt vmcnt(0) lgkmcnt(0)
	s_barrier
	s_cmp_lt_u32 s12, 16
	s_cbranch_scc1 .LBB0_740
	s_waitcnt vmcnt(4)
	v_add_u32_e32 v80, s8, v122
	s_addk_i32 s8, 0xf000
	v_lshlrev_b32_e32 v64, 2, v80
	s_ashr_i32 s8, s8, 10
	global_load_dword v84, v64, s[24:25]
	global_load_dword v85, v64, s[24:25] offset:64
	global_load_dword v86, v64, s[24:25] offset:128
	global_load_dword v87, v64, s[24:25] offset:192
	s_add_i32 s10, s8, 11
	v_or_b32_e32 v96, s9, v234
	s_and_b64 s[8:9], s[22:23], exec
	s_cselect_b32 s8, 10, s10
	s_mul_hi_u32 s9, s8, 0x4200
	s_mulk_i32 s8, 0x4200
	s_add_u32 s8, s1, s8
	s_addc_u32 s9, s2, s9
	v_lshlrev_b32_e32 v64, 2, v154
	v_mov_b32_e32 v65, v97
	v_lshl_add_u64 v[66:67], v[96:97], 2, s[8:9]
	s_waitcnt vmcnt(7)
	v_lshl_add_u64 v[76:77], v[66:67], 0, v[64:65]
	global_load_dwordx4 v[64:67], v[76:77], off
	global_load_dwordx4 v[68:71], v[76:77], off offset:64
	global_load_dwordx4 v[72:75], v[76:77], off offset:128
	s_nop 0
	global_load_dwordx4 v[76:79], v[76:77], off offset:192
	v_mul_u32_u24_e32 v80, 0x1080, v80
	v_or_b32_e32 v82, v96, v154
	v_lshlrev_b32_e32 v96, 1, v80
	v_lshl_add_u64 v[80:81], s[20:21], 0, v[96:97]
	v_lshlrev_b32_e32 v96, 1, v82
	v_lshl_add_u64 v[82:83], v[80:81], 0, v[96:97]
	s_add_i32 s7, s7, s96
	s_cmpk_gt_u32 s7, 0xff
	s_waitcnt vmcnt(7)
	v_fmamk_f32 v84, v84, 0x3a800000, v123
	v_mul_f32_e32 v88, 0x4b800000, v84
	v_cmp_gt_f32_e32 vcc, s6, v84
	s_waitcnt vmcnt(6)
	v_fmamk_f32 v85, v85, 0x3a800000, v123
	v_mul_f32_e32 v89, 0x4b800000, v85
	v_cndmask_b32_e32 v84, v84, v88, vcc
	v_cmp_gt_f32_e64 s[10:11], s6, v85
	v_rsq_f32_e32 v84, v84
	s_waitcnt vmcnt(5)
	v_fmamk_f32 v86, v86, 0x3a800000, v123
	v_cndmask_b32_e64 v85, v85, v89, s[10:11]
	v_mul_f32_e32 v90, 0x4b800000, v86
	v_cmp_gt_f32_e64 s[12:13], s6, v86
	v_rsq_f32_e32 v85, v85
	s_waitcnt vmcnt(4)
	v_fmamk_f32 v87, v87, 0x3a800000, v123
	v_cndmask_b32_e64 v86, v86, v90, s[12:13]
	v_mul_f32_e32 v91, 0x4b800000, v87
	v_cmp_gt_f32_e64 s[14:15], s6, v87
	v_rsq_f32_e32 v88, v86
	v_mul_f32_e32 v86, 0x45800000, v84
	v_cndmask_b32_e64 v87, v87, v91, s[14:15]
	v_cndmask_b32_e32 v84, v84, v86, vcc
	v_rsq_f32_e32 v87, v87
	s_waitcnt vmcnt(2)
	v_pk_fma_f32 v[0:1], v[0:1], v[84:85], v[68:69] op_sel_hi:[1,0,1]
	v_pk_fma_f32 v[2:3], v[2:3], v[84:85], v[70:71] op_sel_hi:[1,0,1]
	s_waitcnt vmcnt(1)
	v_pk_fma_f32 v[12:13], v[12:13], v[84:85], v[72:73] op_sel_hi:[1,0,1]
	v_pk_fma_f32 v[14:15], v[14:15], v[84:85], v[74:75] op_sel_hi:[1,0,1]
	v_cvt_pk_bf16_f32 v0, v0, v1
	v_cvt_pk_bf16_f32 v1, v2, v3
	v_mul_f32_e32 v89, 0x45800000, v85
	s_waitcnt vmcnt(0)
	v_pk_fma_f32 v[4:5], v[4:5], v[84:85], v[76:77] op_sel_hi:[1,0,1]
	v_pk_fma_f32 v[6:7], v[6:7], v[84:85], v[78:79] op_sel_hi:[1,0,1]
	global_store_dwordx2 v[82:83], v[0:1], off offset:32
	v_cvt_pk_bf16_f32 v0, v12, v13
	v_cvt_pk_bf16_f32 v1, v14, v15
	v_cndmask_b32_e64 v86, v85, v89, s[10:11]
	global_store_dwordx2 v[82:83], v[0:1], off offset:64
	v_cvt_pk_bf16_f32 v0, v4, v5
	v_cvt_pk_bf16_f32 v1, v6, v7
	v_pk_fma_f32 v[32:33], v[32:33], v[86:87], v[64:65] op_sel_hi:[1,0,1]
	v_pk_fma_f32 v[34:35], v[34:35], v[86:87], v[66:67] op_sel_hi:[1,0,1]
	global_store_dwordx2 v[82:83], v[0:1], off offset:96
	v_lshl_add_u64 v[0:1], v[80:81], 0, s[36:37]
	v_cvt_pk_bf16_f32 v2, v32, v33
	v_cvt_pk_bf16_f32 v3, v34, v35
	v_lshl_add_u64 v[4:5], v[0:1], 0, v[96:97]
	v_pk_fma_f32 v[24:25], v[24:25], v[86:87], v[68:69] op_sel_hi:[1,0,1]
	v_pk_fma_f32 v[26:27], v[26:27], v[86:87], v[70:71] op_sel_hi:[1,0,1]
	global_store_dwordx2 v[4:5], v[2:3], off
	v_or_b32_e32 v4, 32, v96
	v_mov_b32_e32 v5, v97
	v_pk_fma_f32 v[8:9], v[8:9], v[84:85], v[64:65] op_sel_hi:[1,0,1]
	v_pk_fma_f32 v[10:11], v[10:11], v[84:85], v[66:67] op_sel_hi:[1,0,1]
	v_cvt_pk_bf16_f32 v2, v24, v25
	v_cvt_pk_bf16_f32 v3, v26, v27
	v_lshl_add_u64 v[6:7], v[0:1], 0, v[4:5]
	v_pk_fma_f32 v[20:21], v[20:21], v[86:87], v[72:73] op_sel_hi:[1,0,1]
	v_pk_fma_f32 v[22:23], v[22:23], v[86:87], v[74:75] op_sel_hi:[1,0,1]
	v_cvt_pk_bf16_f32 v8, v8, v9
	v_cvt_pk_bf16_f32 v9, v10, v11
	global_store_dwordx2 v[6:7], v[2:3], off
	v_or_b32_e32 v6, 64, v96
	v_mov_b32_e32 v7, v97
	global_store_dwordx2 v[82:83], v[8:9], off
	v_cvt_pk_bf16_f32 v2, v20, v21
	v_cvt_pk_bf16_f32 v3, v22, v23
	v_lshl_add_u64 v[8:9], v[0:1], 0, v[6:7]
	v_mul_f32_e32 v90, 0x45800000, v88
	v_pk_fma_f32 v[16:17], v[16:17], v[86:87], v[76:77] op_sel_hi:[1,0,1]
	v_pk_fma_f32 v[18:19], v[18:19], v[86:87], v[78:79] op_sel_hi:[1,0,1]
	global_store_dwordx2 v[8:9], v[2:3], off
	v_or_b32_e32 v8, 0x60, v96
	v_mov_b32_e32 v9, v97
	v_cndmask_b32_e64 v88, v88, v90, s[12:13]
	v_cvt_pk_bf16_f32 v2, v16, v17
	v_cvt_pk_bf16_f32 v3, v18, v19
	v_lshl_add_u64 v[0:1], v[0:1], 0, v[8:9]
	v_pk_fma_f32 v[48:49], v[48:49], v[88:89], v[64:65] op_sel_hi:[1,0,1]
	v_pk_fma_f32 v[50:51], v[50:51], v[88:89], v[66:67] op_sel_hi:[1,0,1]
	global_store_dwordx2 v[0:1], v[2:3], off
	v_lshl_add_u64 v[0:1], v[80:81], 0, s[38:39]
	v_pk_fma_f32 v[40:41], v[40:41], v[88:89], v[68:69] op_sel_hi:[1,0,1]
	v_pk_fma_f32 v[42:43], v[42:43], v[88:89], v[70:71] op_sel_hi:[1,0,1]
	v_cvt_pk_bf16_f32 v2, v48, v49
	v_cvt_pk_bf16_f32 v3, v50, v51
	v_lshl_add_u64 v[10:11], v[0:1], 0, v[96:97]
	v_pk_fma_f32 v[36:37], v[36:37], v[88:89], v[72:73] op_sel_hi:[1,0,1]
	v_pk_fma_f32 v[38:39], v[38:39], v[88:89], v[74:75] op_sel_hi:[1,0,1]
	global_store_dwordx2 v[10:11], v[2:3], off
	v_cvt_pk_bf16_f32 v2, v40, v41
	v_cvt_pk_bf16_f32 v3, v42, v43
	v_lshl_add_u64 v[10:11], v[0:1], 0, v[4:5]
	v_mul_f32_e32 v91, 0x45800000, v87
	v_pk_fma_f32 v[28:29], v[28:29], v[88:89], v[76:77] op_sel_hi:[1,0,1]
	v_pk_fma_f32 v[30:31], v[30:31], v[88:89], v[78:79] op_sel_hi:[1,0,1]
	global_store_dwordx2 v[10:11], v[2:3], off
	v_cvt_pk_bf16_f32 v2, v36, v37
	v_cvt_pk_bf16_f32 v3, v38, v39
	v_lshl_add_u64 v[10:11], v[0:1], 0, v[6:7]
	v_cndmask_b32_e64 v90, v87, v91, s[14:15]
	global_store_dwordx2 v[10:11], v[2:3], off
	v_cvt_pk_bf16_f32 v2, v28, v29
	v_cvt_pk_bf16_f32 v3, v30, v31
	v_lshl_add_u64 v[0:1], v[0:1], 0, v[8:9]
	v_pk_fma_f32 v[60:61], v[60:61], v[90:91], v[64:65] op_sel_hi:[1,0,1]
	v_pk_fma_f32 v[62:63], v[62:63], v[90:91], v[66:67] op_sel_hi:[1,0,1]
	global_store_dwordx2 v[0:1], v[2:3], off
	v_lshl_add_u64 v[0:1], v[80:81], 0, s[40:41]
	v_pk_fma_f32 v[56:57], v[56:57], v[90:91], v[68:69] op_sel_hi:[1,0,1]
	v_pk_fma_f32 v[58:59], v[58:59], v[90:91], v[70:71] op_sel_hi:[1,0,1]
	v_cvt_pk_bf16_f32 v2, v60, v61
	v_cvt_pk_bf16_f32 v3, v62, v63
	v_lshl_add_u64 v[10:11], v[0:1], 0, v[96:97]
	v_pk_fma_f32 v[52:53], v[52:53], v[90:91], v[72:73] op_sel_hi:[1,0,1]
	v_pk_fma_f32 v[54:55], v[54:55], v[90:91], v[74:75] op_sel_hi:[1,0,1]
	global_store_dwordx2 v[10:11], v[2:3], off
	v_cvt_pk_bf16_f32 v2, v56, v57
	v_cvt_pk_bf16_f32 v3, v58, v59
	v_lshl_add_u64 v[4:5], v[0:1], 0, v[4:5]
	v_pk_fma_f32 v[44:45], v[44:45], v[90:91], v[76:77] op_sel_hi:[1,0,1]
	v_pk_fma_f32 v[46:47], v[46:47], v[90:91], v[78:79] op_sel_hi:[1,0,1]
	global_store_dwordx2 v[4:5], v[2:3], off
	v_cvt_pk_bf16_f32 v2, v52, v53
	v_cvt_pk_bf16_f32 v3, v54, v55
	v_lshl_add_u64 v[4:5], v[0:1], 0, v[6:7]
	global_store_dwordx2 v[4:5], v[2:3], off
	v_cvt_pk_bf16_f32 v2, v44, v45
	v_cvt_pk_bf16_f32 v3, v46, v47
	v_lshl_add_u64 v[0:1], v[0:1], 0, v[8:9]
	global_store_dwordx2 v[0:1], v[2:3], off
	s_cbranch_scc0 .LBB0_739

.LBB0_1100:
	s_and_b32 s0, s9, 7
	s_or_b32 s0, s0, s3
	s_lshl_b32 s1, s0, 7
	v_or_b32_e32 v0, s1, v149
	v_lshl_or_b32 v96, v0, 11, v116
	s_waitcnt vmcnt(1)
	v_lshl_add_u64 v[100:101], s[18:19], 0, v[96:97]
	v_add_co_u32_e32 v12, vcc, 0x10000, v100
	s_lshl_b32 s2, s9, 4
	s_nop 0
	v_addc_co_u32_e32 v13, vcc, 0, v101, vcc
	s_and_b32 s0, s2, 0x7fffff80
	v_add_co_u32_e32 v26, vcc, 0x20000, v100
	v_or_b32_e32 v0, s0, v149
	s_nop 0
	v_addc_co_u32_e32 v27, vcc, 0, v101, vcc
	v_lshl_or_b32 v98, v0, 11, v116
	v_add_co_u32_e32 v28, vcc, 0x30000, v100
	v_mov_b32_e32 v99, v97
	s_nop 0
	v_addc_co_u32_e32 v29, vcc, 0, v101, vcc
	v_lshl_add_u64 v[102:103], s[16:17], 0, v[98:99]
	v_add_co_u32_e32 v30, vcc, s6, v102
	s_waitcnt lgkmcnt(0)
	v_addc_co_u32_e32 v31, vcc, 0, v103, vcc
	v_add_co_u32_e32 v42, vcc, s7, v102
	s_nop 0
	v_addc_co_u32_e32 v43, vcc, 0, v103, vcc
	v_add_co_u32_e32 v44, vcc, s8, v102
	s_nop 0
	v_addc_co_u32_e32 v45, vcc, 0, v103, vcc
	s_movk_i32 s2, 0x100
	s_mov_b32 s40, s27
	v_mov_b32_e32 v64, 0
	v_mov_b32_e32 v65, v97
	v_mov_b32_e32 v66, v97
	v_mov_b32_e32 v67, v97
	v_mov_b32_e32 v40, 0
	v_mov_b32_e32 v41, v97
	v_mov_b32_e32 v42, v97
	v_mov_b32_e32 v43, v97
	v_mov_b32_e32 v28, 0
	v_mov_b32_e32 v29, v97
	v_mov_b32_e32 v30, v97
	v_mov_b32_e32 v31, v97
	v_mov_b32_e32 v12, 0
	v_mov_b32_e32 v13, v97
	v_lshl_add_u64 v[104:105], v[102:103], 0, s[28:29]
	v_lshl_add_u64 v[106:107], v[102:103], 0, s[30:31]
	v_lshl_add_u64 v[108:109], v[102:103], 0, s[34:35]
	v_lshl_add_u64 v[110:111], v[100:101], 0, s[28:29]
	v_lshl_add_u64 v[112:113], v[100:101], 0, s[30:31]
	v_lshl_add_u64 v[114:115], v[100:101], 0, s[34:35]
	s_waitcnt lgkmcnt(0)
	s_barrier
	v_mov_b32_e32 v60, 0
	v_mov_b32_e32 v61, v97
	v_mov_b32_e32 v62, v97
	v_mov_b32_e32 v63, v97
	v_mov_b32_e32 v44, 0
	v_mov_b32_e32 v45, v97
	v_mov_b32_e32 v46, v97
	v_mov_b32_e32 v47, v97
	v_mov_b32_e32 v26, v97
	v_mov_b32_e32 v27, v97
	v_mov_b32_e32 v52, 0
	v_mov_b32_e32 v53, v97
	v_mov_b32_e32 v54, v97
	v_mov_b32_e32 v55, v97
	v_mov_b32_e32 v48, 0
	v_mov_b32_e32 v49, v97
	v_mov_b32_e32 v50, v97
	v_mov_b32_e32 v51, v97
	v_mov_b32_e32 v14, v97
	v_mov_b32_e32 v15, v97
	v_mov_b32_e32 v24, 0
	v_mov_b32_e32 v25, v97
	v_mov_b32_e32 v8, 0
	v_mov_b32_e32 v9, v97
	v_mov_b32_e32 v10, v97
	v_mov_b32_e32 v11, v97
	v_mov_b32_e32 v36, 0
	v_mov_b32_e32 v37, v97
	v_mov_b32_e32 v38, v97
	v_mov_b32_e32 v39, v97
	v_mov_b32_e32 v20, 0
	v_mov_b32_e32 v21, v97
	v_mov_b32_e32 v22, v97
	v_mov_b32_e32 v23, v97
	v_mov_b32_e32 v4, 0
	v_mov_b32_e32 v5, v97
	v_mov_b32_e32 v6, v97
	v_mov_b32_e32 v7, v97
	v_mov_b32_e32 v32, 0
	v_mov_b32_e32 v33, v97
	v_mov_b32_e32 v34, v97
	v_mov_b32_e32 v35, v97
	v_mov_b32_e32 v16, 0
	v_mov_b32_e32 v17, v97
	v_mov_b32_e32 v18, v97
	v_mov_b32_e32 v19, v97
	v_mov_b32_e32 v0, 0
	v_mov_b32_e32 v1, v97
	v_mov_b32_e32 v2, v97
	v_mov_b32_e32 v3, v97
	v_readlane_b32 s100, v253, 0
	v_readlane_b32 s101, v253, 1
	s_load_dwordx2 s[100:101], s[100:101], 0x160
	v_lshrrev_b32_e32 v71, 6, v146
	s_nop 0
	v_readfirstlane_b32 s42, v71
	v_lshrrev_b32_e32 v69, 3, v146
	v_and_b32_e32 v70, 7, v146
	v_xor_b32_e32 v70, v69, v70
	v_and_b32_e32 v70, 7, v70
	v_lshlrev_b32_e32 v70, 4, v70
	v_lshl_or_b32 v68, v69, 11, v70
	v_add_u32_e32 v69, 0x10000, v68
	v_add_u32_e32 v70, 0x20000, v68
	v_add_u32_e32 v71, 0x30000, v68
	s_and_b32 s98, s9, 7
	s_and_b32 s99, s69, 7
	s_lshl_b32 s99, s99, 3
	s_or_b32 s98, s98, s99
	s_lshl_b32 s98, s98, 18
	s_add_u32 s98, s98, 0x2000000
	s_lshr_b32 s99, s9, 3
	s_lshl_b32 s99, s99, 18
	s_add_u32 s99, s99, 0x9040000
	s_lshl_b32 s42, s42, 10
	s_waitcnt lgkmcnt(0)
	s_mov_b32 m0, s99
	s_add_u32 s98, s100, s98
	s_addc_u32 s99, s101, 0
	s_add_u32 s100, s100, m0
	s_addc_u32 s101, s101, 0
	s_add_u32 m0, s42, 0x0
	s_nop 0
	global_load_lds_dwordx4 v68, s[98:99]
	s_add_u32 m0, s42, 0x1000
	s_nop 0
	global_load_lds_dwordx4 v69, s[98:99]
	s_add_u32 m0, s42, 0x2000
	s_nop 0
	global_load_lds_dwordx4 v70, s[98:99]
	s_add_u32 m0, s42, 0x3000
	s_nop 0
	global_load_lds_dwordx4 v71, s[98:99]
	s_add_u32 m0, s42, 0x8000
	s_nop 0
	global_load_lds_dwordx4 v68, s[100:101]
	s_add_u32 m0, s42, 0x9000
	s_nop 0
	global_load_lds_dwordx4 v69, s[100:101]
	s_add_u32 m0, s42, 0xa000
	s_nop 0
	global_load_lds_dwordx4 v70, s[100:101]
	s_add_u32 m0, s42, 0xb000
	s_nop 0
	global_load_lds_dwordx4 v71, s[100:101]
	s_add_u32 s98, s98, 0x80
	s_addc_u32 s99, s99, 0
	s_add_u32 s100, s100, 0x80
	s_addc_u32 s101, s101, 0
	s_waitcnt vmcnt(0)
	s_waitcnt lgkmcnt(0)
	s_barrier
.LBB0_1101:
	s_add_i32 s33, s40, 2
	s_setprio 1
	ds_read_b128 v[126:129], v119 offset:32768
	ds_read_b128 v[134:137], v119 offset:34816
	ds_read_b128 v[130:133], v118
	ds_read_b128 v[138:141], v118 offset:2048
	ds_read_b128 v[160:163], v118 offset:4096
	ds_read_b128 v[164:167], v118 offset:6144
	s_waitcnt lgkmcnt(3)
	v_mfma_f32_16x16x32_bf16 v[64:67], v[126:129], v[130:133], v[64:67]
	ds_read_b128 v[168:171], v119 offset:36864
	v_mfma_f32_16x16x32_bf16 v[40:43], v[134:137], v[130:133], v[40:43]
	ds_read_b128 v[172:175], v119 offset:38912
	s_waitcnt lgkmcnt(1)
	v_mfma_f32_16x16x32_bf16 v[28:31], v[168:171], v[130:133], v[28:31]
	s_waitcnt lgkmcnt(0)
	v_mfma_f32_16x16x32_bf16 v[12:15], v[172:175], v[130:133], v[12:15]
	s_add_u32 m0, s42, 0x4000
	s_nop 0
	global_load_lds_dwordx4 v68, s[98:99]
	ds_read_b128 v[176:179], v120
	v_mfma_f32_16x16x32_bf16 v[60:63], v[126:129], v[138:141], v[60:63]
	v_mfma_f32_16x16x32_bf16 v[44:47], v[134:137], v[138:141], v[44:47]
	s_add_u32 m0, s42, 0x5000
	s_nop 0
	global_load_lds_dwordx4 v69, s[98:99]
	ds_read_b128 v[184:187], v120 offset:2048
	v_mfma_f32_16x16x32_bf16 v[24:27], v[168:171], v[138:141], v[24:27]
	v_mfma_f32_16x16x32_bf16 v[8:11], v[172:175], v[138:141], v[8:11]
	s_add_u32 m0, s42, 0x6000
	s_nop 0
	global_load_lds_dwordx4 v70, s[98:99]
	ds_read_b128 v[188:191], v120 offset:4096
	v_mfma_f32_16x16x32_bf16 v[52:55], v[126:129], v[160:163], v[52:55]
	v_mfma_f32_16x16x32_bf16 v[36:39], v[134:137], v[160:163], v[36:39]
	s_add_u32 m0, s42, 0x7000
	s_nop 0
	global_load_lds_dwordx4 v71, s[98:99]
	ds_read_b128 v[196:199], v120 offset:6144
	v_mfma_f32_16x16x32_bf16 v[20:23], v[168:171], v[160:163], v[20:23]
	v_mfma_f32_16x16x32_bf16 v[4:7], v[172:175], v[160:163], v[4:7]
	s_add_u32 m0, s42, 0xc000
	s_nop 0
	global_load_lds_dwordx4 v68, s[100:101]
	ds_read_b128 v[200:203], v121 offset:32768
	v_mfma_f32_16x16x32_bf16 v[48:51], v[126:129], v[164:167], v[48:51]
	v_mfma_f32_16x16x32_bf16 v[32:35], v[134:137], v[164:167], v[32:35]
	s_add_u32 m0, s42, 0xd000
	s_nop 0
	global_load_lds_dwordx4 v69, s[100:101]
	ds_read_b128 v[134:137], v121 offset:34816
	v_mfma_f32_16x16x32_bf16 v[16:19], v[168:171], v[164:167], v[16:19]
	v_mfma_f32_16x16x32_bf16 v[0:3], v[172:175], v[164:167], v[0:3]
	s_add_u32 m0, s42, 0xe000
	s_nop 0
	global_load_lds_dwordx4 v70, s[100:101]
	ds_read_b128 v[168:171], v121 offset:36864
	s_waitcnt lgkmcnt(2)
	v_mfma_f32_16x16x32_bf16 v[64:67], v[200:203], v[176:179], v[64:67]
	s_waitcnt lgkmcnt(1)
	v_mfma_f32_16x16x32_bf16 v[40:43], v[134:137], v[176:179], v[40:43]
	s_add_u32 m0, s42, 0xf000
	s_nop 0
	global_load_lds_dwordx4 v71, s[100:101]
	s_add_u32 s98, s98, 0x80
	s_addc_u32 s99, s99, 0
	s_add_u32 s100, s100, 0x80
	s_addc_u32 s101, s101, 0
	ds_read_b128 v[204:207], v121 offset:38912
	s_waitcnt lgkmcnt(1)
	v_mfma_f32_16x16x32_bf16 v[28:31], v[168:171], v[176:179], v[28:31]
	s_waitcnt lgkmcnt(0)
	v_mfma_f32_16x16x32_bf16 v[12:15], v[204:207], v[176:179], v[12:15]
	v_mfma_f32_16x16x32_bf16 v[60:63], v[200:203], v[184:187], v[60:63]
	v_mfma_f32_16x16x32_bf16 v[44:47], v[134:137], v[184:187], v[44:47]
	v_mfma_f32_16x16x32_bf16 v[24:27], v[168:171], v[184:187], v[24:27]
	v_mfma_f32_16x16x32_bf16 v[8:11], v[204:207], v[184:187], v[8:11]
	v_mfma_f32_16x16x32_bf16 v[52:55], v[200:203], v[188:191], v[52:55]
	v_mfma_f32_16x16x32_bf16 v[36:39], v[134:137], v[188:191], v[36:39]
	v_mfma_f32_16x16x32_bf16 v[20:23], v[168:171], v[188:191], v[20:23]
	v_mfma_f32_16x16x32_bf16 v[4:7], v[204:207], v[188:191], v[4:7]
	v_mfma_f32_16x16x32_bf16 v[48:51], v[200:203], v[196:199], v[48:51]
	v_mfma_f32_16x16x32_bf16 v[32:35], v[134:137], v[196:199], v[32:35]
	v_mfma_f32_16x16x32_bf16 v[16:19], v[168:171], v[196:199], v[16:19]
	v_mfma_f32_16x16x32_bf16 v[0:3], v[204:207], v[196:199], v[0:3]
	s_setprio 0
	s_waitcnt vmcnt(0) lgkmcnt(0)
	s_barrier
	s_setprio 1
	ds_read_b128 v[84:87], v119 offset:49152
	ds_read_b128 v[88:91], v119 offset:51200
	ds_read_b128 v[56:59], v118 offset:16384
	ds_read_b128 v[72:75], v118 offset:18432
	ds_read_b128 v[76:79], v118 offset:20480
	ds_read_b128 v[92:95], v118 offset:22528
	s_waitcnt lgkmcnt(3)
	v_mfma_f32_16x16x32_bf16 v[64:67], v[84:87], v[56:59], v[64:67]
	ds_read_b128 v[134:137], v119 offset:53248
	v_mfma_f32_16x16x32_bf16 v[40:43], v[88:91], v[56:59], v[40:43]
	ds_read_b128 v[168:171], v119 offset:55296
	s_waitcnt lgkmcnt(1)
	v_mfma_f32_16x16x32_bf16 v[28:31], v[134:137], v[56:59], v[28:31]
	s_waitcnt lgkmcnt(0)
	v_mfma_f32_16x16x32_bf16 v[12:15], v[168:171], v[56:59], v[12:15]
	s_add_u32 m0, s42, 0x0
	s_nop 0
	global_load_lds_dwordx4 v68, s[98:99]
	ds_read_b128 v[176:179], v120 offset:16384
	v_mfma_f32_16x16x32_bf16 v[60:63], v[84:87], v[72:75], v[60:63]
	v_mfma_f32_16x16x32_bf16 v[44:47], v[88:91], v[72:75], v[44:47]
	s_add_u32 m0, s42, 0x1000
	s_nop 0
	global_load_lds_dwordx4 v69, s[98:99]
	ds_read_b128 v[184:187], v120 offset:18432
	v_mfma_f32_16x16x32_bf16 v[24:27], v[134:137], v[72:75], v[24:27]
	v_mfma_f32_16x16x32_bf16 v[8:11], v[168:171], v[72:75], v[8:11]
	s_add_u32 m0, s42, 0x2000
	s_nop 0
	global_load_lds_dwordx4 v70, s[98:99]
	ds_read_b128 v[188:191], v120 offset:20480
	v_mfma_f32_16x16x32_bf16 v[52:55], v[84:87], v[76:79], v[52:55]
	v_mfma_f32_16x16x32_bf16 v[36:39], v[88:91], v[76:79], v[36:39]
	s_add_u32 m0, s42, 0x3000
	s_nop 0
	global_load_lds_dwordx4 v71, s[98:99]
	ds_read_b128 v[196:199], v120 offset:22528
	v_mfma_f32_16x16x32_bf16 v[20:23], v[134:137], v[76:79], v[20:23]
	v_mfma_f32_16x16x32_bf16 v[4:7], v[168:171], v[76:79], v[4:7]
	s_add_u32 m0, s42, 0x8000
	s_nop 0
	global_load_lds_dwordx4 v68, s[100:101]
	ds_read_b128 v[200:203], v121 offset:49152
	v_mfma_f32_16x16x32_bf16 v[48:51], v[84:87], v[92:95], v[48:51]
	v_mfma_f32_16x16x32_bf16 v[32:35], v[88:91], v[92:95], v[32:35]
	s_add_u32 m0, s42, 0x9000
	s_nop 0
	global_load_lds_dwordx4 v69, s[100:101]
	ds_read_b128 v[204:207], v121 offset:51200
	v_mfma_f32_16x16x32_bf16 v[16:19], v[134:137], v[92:95], v[16:19]
	v_mfma_f32_16x16x32_bf16 v[0:3], v[168:171], v[92:95], v[0:3]
	s_add_u32 m0, s42, 0xa000
	s_nop 0
	global_load_lds_dwordx4 v70, s[100:101]
	ds_read_b128 v[134:137], v121 offset:53248
	s_waitcnt lgkmcnt(2)
	v_mfma_f32_16x16x32_bf16 v[64:67], v[200:203], v[176:179], v[64:67]
	s_waitcnt lgkmcnt(1)
	v_mfma_f32_16x16x32_bf16 v[40:43], v[204:207], v[176:179], v[40:43]
	s_add_u32 m0, s42, 0xb000
	s_nop 0
	global_load_lds_dwordx4 v71, s[100:101]
	s_add_u32 s98, s98, 0x80
	s_addc_u32 s99, s99, 0
	s_add_u32 s100, s100, 0x80
	s_addc_u32 s101, s101, 0
	ds_read_b128 v[168:171], v121 offset:55296
	s_waitcnt lgkmcnt(1)
	v_mfma_f32_16x16x32_bf16 v[28:31], v[134:137], v[176:179], v[28:31]
	s_waitcnt lgkmcnt(0)
	v_mfma_f32_16x16x32_bf16 v[12:15], v[168:171], v[176:179], v[12:15]
	v_mfma_f32_16x16x32_bf16 v[60:63], v[200:203], v[184:187], v[60:63]
	v_mfma_f32_16x16x32_bf16 v[44:47], v[204:207], v[184:187], v[44:47]
	v_mfma_f32_16x16x32_bf16 v[24:27], v[134:137], v[184:187], v[24:27]
	v_mfma_f32_16x16x32_bf16 v[8:11], v[168:171], v[184:187], v[8:11]
	v_mfma_f32_16x16x32_bf16 v[52:55], v[200:203], v[188:191], v[52:55]
	v_mfma_f32_16x16x32_bf16 v[36:39], v[204:207], v[188:191], v[36:39]
	v_mfma_f32_16x16x32_bf16 v[20:23], v[134:137], v[188:191], v[20:23]
	v_mfma_f32_16x16x32_bf16 v[4:7], v[168:171], v[188:191], v[4:7]
	v_mfma_f32_16x16x32_bf16 v[48:51], v[200:203], v[196:199], v[48:51]
	v_mfma_f32_16x16x32_bf16 v[32:35], v[204:207], v[196:199], v[32:35]
	v_mfma_f32_16x16x32_bf16 v[16:19], v[134:137], v[196:199], v[16:19]
	v_mfma_f32_16x16x32_bf16 v[0:3], v[168:171], v[196:199], v[0:3]
	s_setprio 0
	s_mov_b32 s40, s33
	s_waitcnt vmcnt(0) lgkmcnt(0)
	s_barrier
	s_cmp_lt_u32 s40, 16
	s_cbranch_scc1 .LBB0_1101
	s_waitcnt vmcnt(1)
	v_add_u32_e32 v88, s1, v122
	s_addk_i32 s1, 0xf000
	s_ashr_i32 s1, s1, 10
	s_add_i32 s1, s1, 1
	s_and_b64 s[40:41], s[20:21], exec
	s_cselect_b32 s1, 0, s1
	s_mul_i32 s2, s1, 0x3000
	s_add_i32 s26, s1, 10
	s_add_i32 s33, s2, 0x1e000
	s_mul_hi_u32 s26, s26, 0x3000
	s_add_u32 s33, s4, s33
	s_addc_u32 s26, s5, s26
	s_add_u32 s42, s33, 0x2000
	s_addc_u32 s43, s26, 0
	s_add_i32 s1, s1, 15
	s_add_i32 s2, s2, 0x2d000
	s_mul_hi_u32 s1, s1, 0x3000
	s_add_u32 s2, s4, s2
	s_addc_u32 s1, s5, s1
	s_add_u32 s40, s2, 0x1000
	v_or_b32_e32 v96, s0, v123
	v_lshlrev_b64 v[72:73], 2, v[96:97]
	s_addc_u32 s41, s1, 0
	v_lshl_add_u64 v[56:57], s[42:43], 0, v[72:73]
	v_lshl_add_u64 v[70:71], s[12:13], 0, v[72:73]
	v_lshlrev_b32_e32 v58, 12, v88
	v_mov_b32_e32 v59, v97
	v_lshl_add_u64 v[74:75], s[40:41], 0, v[72:73]
	v_lshl_add_u64 v[68:69], v[70:71], 0, v[58:59]
	global_load_dwordx4 v[90:93], v[56:57], off
	s_nop 0
	global_load_dwordx4 v[56:59], v[68:69], off
	global_load_dwordx4 v[78:81], v[74:75], off
	v_lshl_add_u64 v[72:73], s[14:15], 0, v[72:73]
	global_load_dwordx4 v[82:85], v[72:73], off
	v_mov_b32_e32 v75, v97
	v_lshlrev_b32_e32 v74, 1, v96
	v_lshlrev_b32_e32 v89, 10, v88
	v_mov_b32_e32 v87, v97
	v_lshlrev_b32_e32 v86, 11, v88
	s_waitcnt vmcnt(4)
	v_lshl_add_u64 v[94:95], s[22:23], 0, v[74:75]
	v_or_b32_e32 v104, 0x4000, v89
	v_mov_b32_e32 v77, v97
	v_lshl_add_u64 v[74:75], v[94:95], 0, v[86:87]
	v_lshlrev_b32_e32 v76, 2, v104
	v_lshl_add_u64 v[98:99], v[70:71], 0, v[76:77]
	v_mov_b32_e32 v107, v97
	v_or_b32_e32 v106, 16, v96
	v_lshl_add_u64 v[86:87], s[22:23], 0, v[86:87]
	s_waitcnt vmcnt(2)
	v_pk_fma_f32 v[64:65], v[64:65], v[90:91], v[56:57]
	v_pk_fma_f32 v[66:67], v[66:67], v[92:93], v[58:59]
	s_waitcnt vmcnt(1)
	v_pk_add_f32 v[56:57], v[78:79], 1.0 op_sel_hi:[1,0]
	v_pk_add_f32 v[58:59], v[80:81], 1.0 op_sel_hi:[1,0]
	s_waitcnt vmcnt(0)
	v_pk_mul_f32 v[100:101], v[82:83], v[56:57]
	v_pk_mul_f32 v[102:103], v[84:85], v[58:59]
	v_pk_mul_f32 v[56:57], v[100:101], v[64:65]
	v_pk_mul_f32 v[58:59], v[102:103], v[66:67]
	v_cvt_pk_bf16_f32 v56, v56, v57
	v_cvt_pk_bf16_f32 v57, v58, v59
	global_store_dwordx4 v[68:69], v[64:67], off
	global_store_dwordx2 v[74:75], v[56:57], off
	global_load_dwordx4 v[56:59], v[98:99], off
	v_mov_b32_e32 v79, v97
	v_or_b32_e32 v82, 0x8000, v89
	v_lshlrev_b32_e32 v78, 1, v104
	v_mov_b32_e32 v81, v97
	v_lshlrev_b32_e32 v80, 2, v82
	v_lshl_add_u64 v[74:75], v[94:95], 0, v[78:79]
	v_lshl_add_u64 v[104:105], v[70:71], 0, v[80:81]
	v_mov_b32_e32 v83, v97
	v_or_b32_e32 v89, 0xc000, v89
	v_lshlrev_b32_e32 v82, 1, v82
	v_mov_b32_e32 v85, v97
	v_lshlrev_b32_e32 v84, 2, v89
	v_pk_mul_f32 v[64:65], v[64:65], v[64:65]
	v_pk_mul_f32 v[66:67], v[66:67], v[66:67]
	v_add_f32_e32 v64, v64, v65
	v_add_f32_e32 v64, v66, v64
	v_add_f32_e32 v64, v67, v64
	s_waitcnt vmcnt(0)
	v_pk_fma_f32 v[56:57], v[60:61], v[90:91], v[56:57]
	v_pk_fma_f32 v[58:59], v[62:63], v[92:93], v[58:59]
	v_pk_mul_f32 v[60:61], v[100:101], v[56:57]
	v_pk_mul_f32 v[62:63], v[102:103], v[58:59]
	v_cvt_pk_bf16_f32 v60, v60, v61
	v_cvt_pk_bf16_f32 v61, v62, v63
	global_store_dwordx4 v[98:99], v[56:59], off
	global_store_dwordx2 v[74:75], v[60:61], off
	global_load_dwordx4 v[60:63], v[104:105], off
	v_lshl_add_u64 v[74:75], v[94:95], 0, v[82:83]
	v_lshl_add_u64 v[98:99], v[70:71], 0, v[84:85]
	s_waitcnt vmcnt(0)
	v_pk_fma_f32 v[52:53], v[52:53], v[90:91], v[60:61]
	v_pk_fma_f32 v[54:55], v[54:55], v[92:93], v[62:63]
	v_pk_mul_f32 v[60:61], v[100:101], v[52:53]
	v_pk_mul_f32 v[62:63], v[102:103], v[54:55]
	v_cvt_pk_bf16_f32 v60, v60, v61
	v_cvt_pk_bf16_f32 v61, v62, v63
	global_store_dwordx4 v[104:105], v[52:55], off
	global_store_dwordx2 v[74:75], v[60:61], off
	global_load_dwordx4 v[60:63], v[98:99], off
	v_mov_b32_e32 v75, v97
	v_lshlrev_b32_e32 v74, 1, v89
	v_lshlrev_b64 v[104:105], 2, v[106:107]
	v_lshl_add_u64 v[94:95], v[94:95], 0, v[74:75]
	v_lshl_add_u64 v[108:109], s[42:43], 0, v[104:105]
	s_waitcnt vmcnt(0)
	v_pk_fma_f32 v[48:49], v[48:49], v[90:91], v[60:61]
	v_pk_fma_f32 v[50:51], v[50:51], v[92:93], v[62:63]
	v_pk_mul_f32 v[60:61], v[100:101], v[48:49]
	v_pk_mul_f32 v[62:63], v[102:103], v[50:51]
	v_cvt_pk_bf16_f32 v60, v60, v61
	v_cvt_pk_bf16_f32 v61, v62, v63
	global_store_dwordx4 v[98:99], v[48:51], off
	global_store_dwordx2 v[94:95], v[60:61], off
	global_load_dwordx4 v[90:93], v[108:109], off
	s_nop 0
	global_load_dwordx4 v[60:63], v[68:69], off offset:64
	v_lshl_add_u64 v[94:95], s[40:41], 0, v[104:105]
	global_load_dwordx4 v[98:101], v[94:95], off
	global_load_dwordx4 v[102:105], v[72:73], off offset:64
	v_mov_b32_e32 v95, v97
	v_lshlrev_b32_e32 v94, 1, v106
	v_lshl_add_u64 v[106:107], v[70:71], 0, 64
	v_lshl_add_u64 v[108:109], v[86:87], 0, v[94:95]
	v_lshl_add_u64 v[110:111], v[106:107], 0, v[76:77]
	v_lshl_add_u64 v[94:95], s[22:23], 0, v[94:95]
	s_waitcnt vmcnt(2)
	v_pk_fma_f32 v[60:61], v[40:41], v[90:91], v[60:61]
	v_pk_fma_f32 v[62:63], v[42:43], v[92:93], v[62:63]
	s_waitcnt vmcnt(1)
	v_pk_add_f32 v[40:41], v[98:99], 1.0 op_sel_hi:[1,0]
	v_pk_add_f32 v[42:43], v[100:101], 1.0 op_sel_hi:[1,0]
	s_waitcnt vmcnt(0)
	v_pk_mul_f32 v[98:99], v[102:103], v[40:41]
	v_pk_mul_f32 v[100:101], v[104:105], v[42:43]
	v_pk_mul_f32 v[40:41], v[98:99], v[60:61]
	v_pk_mul_f32 v[42:43], v[100:101], v[62:63]
	v_cvt_pk_bf16_f32 v40, v40, v41
	v_cvt_pk_bf16_f32 v41, v42, v43
	global_store_dwordx4 v[68:69], v[60:63], off offset:64
	global_store_dwordx2 v[108:109], v[40:41], off
	global_load_dwordx4 v[40:43], v[110:111], off
	v_lshl_add_u64 v[102:103], v[94:95], 0, v[78:79]
	v_lshl_add_u64 v[104:105], v[106:107], 0, v[80:81]
	v_lshl_add_u64 v[106:107], v[106:107], 0, v[84:85]
	v_mov_b32_e32 v109, v97
	v_or_b32_e32 v108, 32, v96
	v_or_b32_e32 v96, 48, v96
	v_pk_mul_f32 v[60:61], v[60:61], v[60:61]
	v_pk_mul_f32 v[62:63], v[62:63], v[62:63]
	v_add_f32_e32 v60, v60, v61
	v_add_f32_e32 v60, v62, v60
	v_add_f32_e32 v60, v63, v60
	v_add_f32_e32 v60, v64, v60
	s_waitcnt vmcnt(0)
	v_pk_fma_f32 v[40:41], v[44:45], v[90:91], v[40:41]
	v_pk_fma_f32 v[42:43], v[46:47], v[92:93], v[42:43]
	v_pk_mul_f32 v[44:45], v[98:99], v[40:41]
	v_pk_mul_f32 v[46:47], v[100:101], v[42:43]
	v_cvt_pk_bf16_f32 v44, v44, v45
	v_cvt_pk_bf16_f32 v45, v46, v47
	global_store_dwordx4 v[110:111], v[40:43], off
	global_store_dwordx2 v[102:103], v[44:45], off
	global_load_dwordx4 v[44:47], v[104:105], off
	v_lshl_add_u64 v[102:103], v[94:95], 0, v[82:83]
	v_lshl_add_u64 v[94:95], v[94:95], 0, v[74:75]
	s_waitcnt vmcnt(0)
	v_pk_fma_f32 v[36:37], v[36:37], v[90:91], v[44:45]
	v_pk_fma_f32 v[38:39], v[38:39], v[92:93], v[46:47]
	v_pk_mul_f32 v[44:45], v[98:99], v[36:37]
	v_pk_mul_f32 v[46:47], v[100:101], v[38:39]
	v_cvt_pk_bf16_f32 v44, v44, v45
	v_cvt_pk_bf16_f32 v45, v46, v47
	global_store_dwordx4 v[104:105], v[36:39], off
	global_store_dwordx2 v[102:103], v[44:45], off
	global_load_dwordx4 v[44:47], v[106:107], off
	v_lshlrev_b64 v[102:103], 2, v[108:109]
	v_lshl_add_u64 v[104:105], s[42:43], 0, v[102:103]
	s_waitcnt vmcnt(0)
	v_pk_fma_f32 v[32:33], v[32:33], v[90:91], v[44:45]
	v_pk_fma_f32 v[34:35], v[34:35], v[92:93], v[46:47]
	v_pk_mul_f32 v[44:45], v[98:99], v[32:33]
	v_pk_mul_f32 v[46:47], v[100:101], v[34:35]
	v_cvt_pk_bf16_f32 v44, v44, v45
	v_cvt_pk_bf16_f32 v45, v46, v47
	global_store_dwordx4 v[106:107], v[32:35], off
	global_store_dwordx2 v[94:95], v[44:45], off
	global_load_dwordx4 v[44:47], v[104:105], off
	s_nop 0
	global_load_dwordx4 v[90:93], v[68:69], off offset:128
	v_lshl_add_u64 v[94:95], s[40:41], 0, v[102:103]
	global_load_dwordx4 v[98:101], v[94:95], off
	global_load_dwordx4 v[102:105], v[72:73], off offset:128
	v_mov_b32_e32 v95, v97
	v_lshlrev_b32_e32 v94, 1, v108
	v_lshl_add_u64 v[106:107], v[70:71], 0, s[36:37]
	v_lshl_add_u64 v[108:109], v[86:87], 0, v[94:95]
	v_lshl_add_u64 v[110:111], v[106:107], 0, v[76:77]
	v_lshl_add_u64 v[94:95], s[22:23], 0, v[94:95]
	s_waitcnt vmcnt(2)
	v_pk_fma_f32 v[28:29], v[28:29], v[44:45], v[90:91]
	v_pk_fma_f32 v[30:31], v[30:31], v[46:47], v[92:93]
	s_waitcnt vmcnt(1)
	v_pk_add_f32 v[90:91], v[98:99], 1.0 op_sel_hi:[1,0]
	v_pk_add_f32 v[92:93], v[100:101], 1.0 op_sel_hi:[1,0]
	s_waitcnt vmcnt(0)
	v_pk_mul_f32 v[98:99], v[102:103], v[90:91]
	v_pk_mul_f32 v[100:101], v[104:105], v[92:93]
	v_pk_mul_f32 v[90:91], v[98:99], v[28:29]
	v_pk_mul_f32 v[92:93], v[100:101], v[30:31]
	v_cvt_pk_bf16_f32 v90, v90, v91
	v_cvt_pk_bf16_f32 v91, v92, v93
	global_store_dwordx4 v[68:69], v[28:31], off offset:128
	global_store_dwordx2 v[108:109], v[90:91], off
	global_load_dwordx4 v[90:93], v[110:111], off
	v_lshl_add_u64 v[102:103], v[94:95], 0, v[78:79]
	v_lshl_add_u64 v[104:105], v[106:107], 0, v[80:81]
	v_lshl_add_u64 v[106:107], v[106:107], 0, v[84:85]
	v_pk_mul_f32 v[28:29], v[28:29], v[28:29]
	v_pk_mul_f32 v[30:31], v[30:31], v[30:31]
	v_add_f32_e32 v28, v28, v29
	v_add_f32_e32 v28, v30, v28
	v_add_f32_e32 v28, v31, v28
	v_add_f32_e32 v28, v60, v28
	s_waitcnt vmcnt(0)
	v_pk_fma_f32 v[24:25], v[24:25], v[44:45], v[90:91]
	v_pk_fma_f32 v[26:27], v[26:27], v[46:47], v[92:93]
	v_pk_mul_f32 v[90:91], v[98:99], v[24:25]
	v_pk_mul_f32 v[92:93], v[100:101], v[26:27]
	v_cvt_pk_bf16_f32 v90, v90, v91
	v_cvt_pk_bf16_f32 v91, v92, v93
	global_store_dwordx4 v[110:111], v[24:27], off
	global_store_dwordx2 v[102:103], v[90:91], off
	global_load_dwordx4 v[90:93], v[104:105], off
	v_lshl_add_u64 v[102:103], v[94:95], 0, v[82:83]
	v_lshl_add_u64 v[94:95], v[94:95], 0, v[74:75]
	s_waitcnt vmcnt(0)
	v_pk_fma_f32 v[20:21], v[20:21], v[44:45], v[90:91]
	v_pk_fma_f32 v[22:23], v[22:23], v[46:47], v[92:93]
	v_pk_mul_f32 v[90:91], v[98:99], v[20:21]
	v_pk_mul_f32 v[92:93], v[100:101], v[22:23]
	v_cvt_pk_bf16_f32 v90, v90, v91
	v_cvt_pk_bf16_f32 v91, v92, v93
	global_store_dwordx4 v[104:105], v[20:23], off
	global_store_dwordx2 v[102:103], v[90:91], off
	global_load_dwordx4 v[90:93], v[106:107], off
	v_lshlrev_b64 v[102:103], 2, v[96:97]
	v_lshl_add_u64 v[104:105], s[42:43], 0, v[102:103]
	v_lshlrev_b32_e32 v96, 1, v96
	s_waitcnt vmcnt(0)
	v_pk_fma_f32 v[16:17], v[16:17], v[44:45], v[90:91]
	v_pk_fma_f32 v[18:19], v[18:19], v[46:47], v[92:93]
	v_pk_mul_f32 v[44:45], v[98:99], v[16:17]
	v_pk_mul_f32 v[46:47], v[100:101], v[18:19]
	v_cvt_pk_bf16_f32 v44, v44, v45
	v_cvt_pk_bf16_f32 v45, v46, v47
	global_store_dwordx4 v[106:107], v[16:19], off
	global_store_dwordx2 v[94:95], v[44:45], off
	global_load_dwordx4 v[44:47], v[104:105], off
	s_nop 0
	global_load_dwordx4 v[90:93], v[68:69], off offset:192
	v_lshl_add_u64 v[94:95], s[40:41], 0, v[102:103]
	global_load_dwordx4 v[98:101], v[94:95], off
	global_load_dwordx4 v[102:105], v[72:73], off offset:192
	v_lshl_add_u64 v[72:73], v[70:71], 0, s[38:39]
	v_lshl_add_u64 v[70:71], v[86:87], 0, v[96:97]
	v_lshl_add_u64 v[76:77], v[72:73], 0, v[76:77]
	v_lshl_add_u64 v[80:81], v[72:73], 0, v[80:81]
	v_lshl_add_u64 v[72:73], v[72:73], 0, v[84:85]
	s_waitcnt vmcnt(2)
	v_pk_fma_f32 v[12:13], v[12:13], v[44:45], v[90:91]
	s_waitcnt vmcnt(1)
	v_pk_add_f32 v[86:87], v[98:99], 1.0 op_sel_hi:[1,0]
	v_pk_add_f32 v[90:91], v[100:101], 1.0 op_sel_hi:[1,0]
	v_pk_fma_f32 v[14:15], v[14:15], v[46:47], v[92:93]
	s_waitcnt vmcnt(0)
	v_pk_mul_f32 v[86:87], v[102:103], v[86:87]
	v_pk_mul_f32 v[90:91], v[104:105], v[90:91]
	global_store_dwordx4 v[68:69], v[12:15], off offset:192
	v_pk_mul_f32 v[68:69], v[86:87], v[12:13]
	v_pk_mul_f32 v[92:93], v[90:91], v[14:15]
	v_cvt_pk_bf16_f32 v68, v68, v69
	v_cvt_pk_bf16_f32 v69, v92, v93
	global_store_dwordx2 v[70:71], v[68:69], off
	global_load_dwordx4 v[68:71], v[76:77], off
	v_lshl_add_u64 v[92:93], s[22:23], 0, v[96:97]
	v_lshl_add_u64 v[78:79], v[92:93], 0, v[78:79]
	v_pk_mul_f32 v[12:13], v[12:13], v[12:13]
	v_pk_mul_f32 v[14:15], v[14:15], v[14:15]
	v_add_f32_e32 v12, v12, v13
	v_add_f32_e32 v12, v14, v12
	v_add_f32_e32 v12, v15, v12
	v_add_f32_e32 v14, v28, v12
	ds_bpermute_b32 v15, v124, v14
	v_lshlrev_b32_e32 v96, 2, v88
	v_lshl_add_u64 v[12:13], v[92:93], 0, v[74:75]
	s_waitcnt lgkmcnt(0)
	v_add_f32_e32 v14, v14, v15
	ds_bpermute_b32 v15, v125, v14
	s_waitcnt vmcnt(0)
	v_pk_fma_f32 v[8:9], v[8:9], v[44:45], v[68:69]
	v_pk_fma_f32 v[10:11], v[10:11], v[46:47], v[70:71]
	v_pk_mul_f32 v[68:69], v[86:87], v[8:9]
	v_pk_mul_f32 v[70:71], v[90:91], v[10:11]
	v_cvt_pk_bf16_f32 v68, v68, v69
	v_cvt_pk_bf16_f32 v69, v70, v71
	global_store_dwordx4 v[76:77], v[8:11], off
	global_store_dwordx2 v[78:79], v[68:69], off
	global_load_dwordx4 v[68:71], v[80:81], off
	v_lshl_add_u64 v[76:77], v[92:93], 0, v[82:83]
	s_waitcnt vmcnt(0)
	v_pk_fma_f32 v[4:5], v[4:5], v[44:45], v[68:69]
	v_pk_fma_f32 v[6:7], v[6:7], v[46:47], v[70:71]
	v_pk_mul_f32 v[68:69], v[86:87], v[4:5]
	v_pk_mul_f32 v[70:71], v[90:91], v[6:7]
	v_cvt_pk_bf16_f32 v68, v68, v69
	v_cvt_pk_bf16_f32 v69, v70, v71
	global_store_dwordx4 v[80:81], v[4:7], off
	global_store_dwordx2 v[76:77], v[68:69], off
	global_load_dwordx4 v[68:71], v[72:73], off
	s_waitcnt vmcnt(0)
	v_pk_fma_f32 v[0:1], v[0:1], v[44:45], v[68:69]
	v_pk_fma_f32 v[2:3], v[2:3], v[46:47], v[70:71]
	v_pk_mul_f32 v[28:29], v[86:87], v[0:1]
	v_pk_mul_f32 v[30:31], v[90:91], v[2:3]
	v_cvt_pk_bf16_f32 v28, v28, v29
	v_cvt_pk_bf16_f32 v29, v30, v31
	global_store_dwordx4 v[72:73], v[0:3], off
	global_store_dwordx2 v[12:13], v[28:29], off
	v_lshl_add_u64 v[12:13], s[24:25], 0, v[96:97]
	s_and_saveexec_b64 s[40:41], s[10:11]
	s_cbranch_execz .LBB0_1104
	s_waitcnt lgkmcnt(0)
	v_add_f32_e32 v14, v14, v15
	global_atomic_add_f32 v[12:13], v14, off

.LBB0_1165:
	s_and_b32 s0, s45, 7
	s_or_b32 s0, s0, s3
	s_lshl_b32 s46, s0, 7
	v_or_b32_e32 v0, s46, v149
	v_lshl_or_b32 v130, v0, 11, v129
	v_lshl_add_u64 v[30:31], s[22:23], 0, v[130:131]
	v_add_co_u32_e32 v4, vcc, 0x10000, v30
	s_lshl_b32 s1, s45, 4
	s_nop 0
	v_addc_co_u32_e32 v5, vcc, 0, v31, vcc
	s_and_b32 s0, s1, 0x7fffff80
	v_add_co_u32_e32 v12, vcc, 0x20000, v30
	v_or_b32_e32 v0, s0, v149
	s_nop 0
	v_addc_co_u32_e32 v13, vcc, 0, v31, vcc
	v_lshl_or_b32 v24, v0, 11, v129
	v_add_co_u32_e32 v16, vcc, 0x30000, v30
	v_mov_b32_e32 v25, v131
	s_nop 0
	v_addc_co_u32_e32 v17, vcc, 0, v31, vcc
	v_lshl_add_u64 v[52:53], s[20:21], 0, v[24:25]
	v_add_co_u32_e32 v18, vcc, s8, v52
	s_nop 0
	v_addc_co_u32_e32 v19, vcc, 0, v53, vcc
	v_add_co_u32_e32 v28, vcc, s9, v52
	s_nop 0
	v_addc_co_u32_e32 v29, vcc, 0, v53, vcc
	v_add_co_u32_e32 v58, vcc, s38, v52
	s_nop 0
	v_addc_co_u32_e32 v59, vcc, 0, v53, vcc
	s_nop 0
	s_nop 0
	s_nop 0
	s_movk_i32 s1, 0x100
	s_mov_b32 s6, s37
	v_mov_b32_e32 v8, 0
	v_mov_b32_e32 v9, v131
	v_mov_b32_e32 v10, v131
	v_mov_b32_e32 v11, v131
	v_mov_b32_e32 v26, 0
	v_mov_b32_e32 v27, v131
	v_mov_b32_e32 v28, v131
	v_mov_b32_e32 v29, v131
	v_mov_b32_e32 v16, 0
	v_mov_b32_e32 v17, v131
	v_mov_b32_e32 v18, v131
	v_mov_b32_e32 v19, v131
	v_mov_b32_e32 v60, 0
	v_mov_b32_e32 v61, v131
	v_lshl_add_u64 v[58:59], v[52:53], 0, s[18:19]
	v_lshl_add_u64 v[104:105], v[52:53], 0, s[30:31]
	v_lshl_add_u64 v[106:107], v[52:53], 0, s[34:35]
	v_lshl_add_u64 v[108:109], v[30:31], 0, s[18:19]
	v_lshl_add_u64 v[110:111], v[30:31], 0, s[30:31]
	v_lshl_add_u64 v[112:113], v[30:31], 0, s[34:35]
	s_barrier
	v_mov_b32_e32 v88, 0
	v_mov_b32_e32 v89, v131
	v_mov_b32_e32 v90, v131
	v_mov_b32_e32 v91, v131
	v_mov_b32_e32 v76, 0
	v_mov_b32_e32 v77, v131
	v_mov_b32_e32 v78, v131
	v_mov_b32_e32 v79, v131
	v_mov_b32_e32 v80, 0
	v_mov_b32_e32 v81, v131
	v_mov_b32_e32 v82, v131
	v_mov_b32_e32 v83, v131
	v_mov_b32_e32 v84, 0
	v_mov_b32_e32 v85, v131
	v_mov_b32_e32 v86, v131
	v_mov_b32_e32 v87, v131
	v_mov_b32_e32 v74, v131
	v_mov_b32_e32 v75, v131
	v_mov_b32_e32 v62, v131
	v_mov_b32_e32 v63, v131
	v_mov_b32_e32 v36, 0
	v_mov_b32_e32 v37, v131
	v_mov_b32_e32 v38, v131
	v_mov_b32_e32 v39, v131
	v_mov_b32_e32 v54, 0
	v_mov_b32_e32 v55, v131
	v_mov_b32_e32 v56, v131
	v_mov_b32_e32 v57, v131
	v_mov_b32_e32 v32, 0
	v_mov_b32_e32 v33, v131
	v_mov_b32_e32 v34, v131
	v_mov_b32_e32 v35, v131
	v_mov_b32_e32 v64, 0
	v_mov_b32_e32 v65, v131
	v_mov_b32_e32 v66, v131
	v_mov_b32_e32 v67, v131
	v_mov_b32_e32 v40, 0
	v_mov_b32_e32 v41, v131
	v_mov_b32_e32 v42, v131
	v_mov_b32_e32 v43, v131
	v_mov_b32_e32 v48, 0
	v_mov_b32_e32 v49, v131
	v_mov_b32_e32 v50, v131
	v_mov_b32_e32 v51, v131
	v_mov_b32_e32 v68, 0
	v_mov_b32_e32 v69, v131
	v_mov_b32_e32 v70, v131
	v_mov_b32_e32 v71, v131
	v_mov_b32_e32 v72, 0
	v_mov_b32_e32 v73, v131
	v_readlane_b32 s100, v253, 0
	v_readlane_b32 s101, v253, 1
	s_load_dwordx2 s[100:101], s[100:101], 0x160
	v_lshrrev_b32_e32 v7, 6, v146
	s_nop 0
	v_readfirstlane_b32 s10, v7
	v_lshrrev_b32_e32 v5, 3, v146
	v_and_b32_e32 v6, 7, v146
	v_xor_b32_e32 v6, v5, v6
	v_and_b32_e32 v6, 7, v6
	v_lshlrev_b32_e32 v6, 4, v6
	v_lshl_or_b32 v4, v5, 11, v6
	v_add_u32_e32 v5, 0x10000, v4
	v_add_u32_e32 v6, 0x20000, v4
	v_add_u32_e32 v7, 0x30000, v4
	s_and_b32 s98, s45, 7
	s_and_b32 s99, s69, 7
	s_lshl_b32 s99, s99, 3
	s_or_b32 s98, s98, s99
	s_lshl_b32 s98, s98, 18
	s_add_u32 s98, s98, 0xdc40000
	s_lshr_b32 s99, s45, 3
	s_lshl_b32 s99, s99, 18
	s_add_u32 s99, s99, 0x8740000
	s_lshl_b32 s10, s10, 10
	s_waitcnt lgkmcnt(0)
	s_mov_b32 m0, s99
	s_add_u32 s98, s100, s98
	s_addc_u32 s99, s101, 0
	s_add_u32 s100, s100, m0
	s_addc_u32 s101, s101, 0
	s_add_u32 m0, s10, 0x0
	s_nop 0
	global_load_lds_dwordx4 v4, s[98:99]
	s_add_u32 m0, s10, 0x1000
	s_nop 0
	global_load_lds_dwordx4 v5, s[98:99]
	s_add_u32 m0, s10, 0x2000
	s_nop 0
	global_load_lds_dwordx4 v6, s[98:99]
	s_add_u32 m0, s10, 0x3000
	s_nop 0
	global_load_lds_dwordx4 v7, s[98:99]
	s_add_u32 m0, s10, 0x8000
	s_nop 0
	global_load_lds_dwordx4 v4, s[100:101]
	s_add_u32 m0, s10, 0x9000
	s_nop 0
	global_load_lds_dwordx4 v5, s[100:101]
	s_add_u32 m0, s10, 0xa000
	s_nop 0
	global_load_lds_dwordx4 v6, s[100:101]
	s_add_u32 m0, s10, 0xb000
	s_nop 0
	global_load_lds_dwordx4 v7, s[100:101]
	s_add_u32 s98, s98, 0x80
	s_addc_u32 s99, s99, 0
	s_add_u32 s100, s100, 0x80
	s_addc_u32 s101, s101, 0
	s_waitcnt vmcnt(0)
	s_waitcnt lgkmcnt(0)
	s_barrier
.LBB0_1166:
	s_add_i32 s2, s6, 2
	s_setprio 1
	ds_read_b128 v[114:117], v171 offset:32768
	ds_read_b128 v[122:125], v171 offset:34816
	ds_read_b128 v[118:121], v155
	ds_read_b128 v[140:143], v155 offset:2048
	ds_read_b128 v[160:163], v155 offset:4096
	ds_read_b128 v[164:167], v155 offset:6144
	s_waitcnt lgkmcnt(3)
	v_mfma_f32_16x16x32_bf16 v[8:11], v[114:117], v[118:121], v[8:11]
	ds_read_b128 v[188:191], v171 offset:36864
	v_mfma_f32_16x16x32_bf16 v[26:29], v[122:125], v[118:121], v[26:29]
	ds_read_b128 v[192:195], v171 offset:38912
	s_waitcnt lgkmcnt(1)
	v_mfma_f32_16x16x32_bf16 v[16:19], v[188:191], v[118:121], v[16:19]
	s_waitcnt lgkmcnt(0)
	v_mfma_f32_16x16x32_bf16 v[60:63], v[192:195], v[118:121], v[60:63]
	s_add_u32 m0, s10, 0x4000
	s_nop 0
	global_load_lds_dwordx4 v4, s[98:99]
	ds_read_b128 v[196:199], v172
	v_mfma_f32_16x16x32_bf16 v[36:39], v[114:117], v[140:143], v[36:39]
	v_mfma_f32_16x16x32_bf16 v[54:57], v[122:125], v[140:143], v[54:57]
	s_add_u32 m0, s10, 0x5000
	s_nop 0
	global_load_lds_dwordx4 v5, s[98:99]
	ds_read_b128 v[204:207], v172 offset:2048
	v_mfma_f32_16x16x32_bf16 v[32:35], v[188:191], v[140:143], v[32:35]
	v_mfma_f32_16x16x32_bf16 v[64:67], v[192:195], v[140:143], v[64:67]
	s_add_u32 m0, s10, 0x6000
	s_nop 0
	global_load_lds_dwordx4 v6, s[98:99]
	ds_read_b128 v[208:211], v172 offset:4096
	v_mfma_f32_16x16x32_bf16 v[40:43], v[114:117], v[160:163], v[40:43]
	v_mfma_f32_16x16x32_bf16 v[88:91], v[122:125], v[160:163], v[88:91]
	s_add_u32 m0, s10, 0x7000
	s_nop 0
	global_load_lds_dwordx4 v7, s[98:99]
	ds_read_b128 v[216:219], v172 offset:6144
	v_mfma_f32_16x16x32_bf16 v[48:51], v[188:191], v[160:163], v[48:51]
	v_mfma_f32_16x16x32_bf16 v[76:79], v[192:195], v[160:163], v[76:79]
	s_add_u32 m0, s10, 0xc000
	s_nop 0
	global_load_lds_dwordx4 v4, s[100:101]
	ds_read_b128 v[222:225], v173 offset:32768
	v_mfma_f32_16x16x32_bf16 v[80:83], v[114:117], v[164:167], v[80:83]
	v_mfma_f32_16x16x32_bf16 v[84:87], v[122:125], v[164:167], v[84:87]
	s_add_u32 m0, s10, 0xd000
	s_nop 0
	global_load_lds_dwordx4 v5, s[100:101]
	ds_read_b128 v[122:125], v173 offset:34816
	v_mfma_f32_16x16x32_bf16 v[68:71], v[188:191], v[164:167], v[68:71]
	v_mfma_f32_16x16x32_bf16 v[72:75], v[192:195], v[164:167], v[72:75]
	s_add_u32 m0, s10, 0xe000
	s_nop 0
	global_load_lds_dwordx4 v6, s[100:101]
	ds_read_b128 v[188:191], v173 offset:36864
	s_waitcnt lgkmcnt(2)
	v_mfma_f32_16x16x32_bf16 v[8:11], v[222:225], v[196:199], v[8:11]
	s_waitcnt lgkmcnt(1)
	v_mfma_f32_16x16x32_bf16 v[26:29], v[122:125], v[196:199], v[26:29]
	s_add_u32 m0, s10, 0xf000
	s_nop 0
	global_load_lds_dwordx4 v7, s[100:101]
	s_add_u32 s98, s98, 0x80
	s_addc_u32 s99, s99, 0
	s_add_u32 s100, s100, 0x80
	s_addc_u32 s101, s101, 0
	ds_read_b128 v[226:229], v173 offset:38912
	s_waitcnt lgkmcnt(1)
	v_mfma_f32_16x16x32_bf16 v[16:19], v[188:191], v[196:199], v[16:19]
	s_waitcnt lgkmcnt(0)
	v_mfma_f32_16x16x32_bf16 v[60:63], v[226:229], v[196:199], v[60:63]
	v_mfma_f32_16x16x32_bf16 v[36:39], v[222:225], v[204:207], v[36:39]
	v_mfma_f32_16x16x32_bf16 v[54:57], v[122:125], v[204:207], v[54:57]
	v_mfma_f32_16x16x32_bf16 v[32:35], v[188:191], v[204:207], v[32:35]
	v_mfma_f32_16x16x32_bf16 v[64:67], v[226:229], v[204:207], v[64:67]
	v_mfma_f32_16x16x32_bf16 v[40:43], v[222:225], v[208:211], v[40:43]
	v_mfma_f32_16x16x32_bf16 v[88:91], v[122:125], v[208:211], v[88:91]
	v_mfma_f32_16x16x32_bf16 v[48:51], v[188:191], v[208:211], v[48:51]
	v_mfma_f32_16x16x32_bf16 v[76:79], v[226:229], v[208:211], v[76:79]
	v_mfma_f32_16x16x32_bf16 v[80:83], v[222:225], v[216:219], v[80:83]
	v_mfma_f32_16x16x32_bf16 v[84:87], v[122:125], v[216:219], v[84:87]
	v_mfma_f32_16x16x32_bf16 v[68:71], v[188:191], v[216:219], v[68:71]
	v_mfma_f32_16x16x32_bf16 v[72:75], v[226:229], v[216:219], v[72:75]
	s_setprio 0
	s_waitcnt vmcnt(0) lgkmcnt(0)
	s_barrier
	s_setprio 1
	ds_read_b128 v[92:95], v171 offset:49152
	ds_read_b128 v[96:99], v171 offset:51200
	ds_read_b128 v[0:3], v155 offset:16384
	ds_read_b128 v[12:15], v155 offset:18432
	ds_read_b128 v[20:23], v155 offset:20480
	ds_read_b128 v[100:103], v155 offset:22528
	s_waitcnt lgkmcnt(3)
	v_mfma_f32_16x16x32_bf16 v[8:11], v[92:95], v[0:3], v[8:11]
	ds_read_b128 v[122:125], v171 offset:53248
	v_mfma_f32_16x16x32_bf16 v[26:29], v[96:99], v[0:3], v[26:29]
	ds_read_b128 v[188:191], v171 offset:55296
	s_waitcnt lgkmcnt(1)
	v_mfma_f32_16x16x32_bf16 v[16:19], v[122:125], v[0:3], v[16:19]
	s_waitcnt lgkmcnt(0)
	v_mfma_f32_16x16x32_bf16 v[60:63], v[188:191], v[0:3], v[60:63]
	s_add_u32 m0, s10, 0x0
	s_nop 0
	global_load_lds_dwordx4 v4, s[98:99]
	ds_read_b128 v[196:199], v172 offset:16384
	v_mfma_f32_16x16x32_bf16 v[36:39], v[92:95], v[12:15], v[36:39]
	v_mfma_f32_16x16x32_bf16 v[54:57], v[96:99], v[12:15], v[54:57]
	s_add_u32 m0, s10, 0x1000
	s_nop 0
	global_load_lds_dwordx4 v5, s[98:99]
	ds_read_b128 v[204:207], v172 offset:18432
	v_mfma_f32_16x16x32_bf16 v[32:35], v[122:125], v[12:15], v[32:35]
	v_mfma_f32_16x16x32_bf16 v[64:67], v[188:191], v[12:15], v[64:67]
	s_add_u32 m0, s10, 0x2000
	s_nop 0
	global_load_lds_dwordx4 v6, s[98:99]
	ds_read_b128 v[208:211], v172 offset:20480
	v_mfma_f32_16x16x32_bf16 v[40:43], v[92:95], v[20:23], v[40:43]
	v_mfma_f32_16x16x32_bf16 v[88:91], v[96:99], v[20:23], v[88:91]
	s_add_u32 m0, s10, 0x3000
	s_nop 0
	global_load_lds_dwordx4 v7, s[98:99]
	ds_read_b128 v[216:219], v172 offset:22528
	v_mfma_f32_16x16x32_bf16 v[48:51], v[122:125], v[20:23], v[48:51]
	v_mfma_f32_16x16x32_bf16 v[76:79], v[188:191], v[20:23], v[76:79]
	s_add_u32 m0, s10, 0x8000
	s_nop 0
	global_load_lds_dwordx4 v4, s[100:101]
	ds_read_b128 v[222:225], v173 offset:49152
	v_mfma_f32_16x16x32_bf16 v[80:83], v[92:95], v[100:103], v[80:83]
	v_mfma_f32_16x16x32_bf16 v[84:87], v[96:99], v[100:103], v[84:87]
	s_add_u32 m0, s10, 0x9000
	s_nop 0
	global_load_lds_dwordx4 v5, s[100:101]
	ds_read_b128 v[226:229], v173 offset:51200
	v_mfma_f32_16x16x32_bf16 v[68:71], v[122:125], v[100:103], v[68:71]
	v_mfma_f32_16x16x32_bf16 v[72:75], v[188:191], v[100:103], v[72:75]
	s_add_u32 m0, s10, 0xa000
	s_nop 0
	global_load_lds_dwordx4 v6, s[100:101]
	ds_read_b128 v[122:125], v173 offset:53248
	s_waitcnt lgkmcnt(2)
	v_mfma_f32_16x16x32_bf16 v[8:11], v[222:225], v[196:199], v[8:11]
	s_waitcnt lgkmcnt(1)
	v_mfma_f32_16x16x32_bf16 v[26:29], v[226:229], v[196:199], v[26:29]
	s_add_u32 m0, s10, 0xb000
	s_nop 0
	global_load_lds_dwordx4 v7, s[100:101]
	s_add_u32 s98, s98, 0x80
	s_addc_u32 s99, s99, 0
	s_add_u32 s100, s100, 0x80
	s_addc_u32 s101, s101, 0
	ds_read_b128 v[188:191], v173 offset:55296
	s_waitcnt lgkmcnt(1)
	v_mfma_f32_16x16x32_bf16 v[16:19], v[122:125], v[196:199], v[16:19]
	s_waitcnt lgkmcnt(0)
	v_mfma_f32_16x16x32_bf16 v[60:63], v[188:191], v[196:199], v[60:63]
	v_mfma_f32_16x16x32_bf16 v[36:39], v[222:225], v[204:207], v[36:39]
	v_mfma_f32_16x16x32_bf16 v[54:57], v[226:229], v[204:207], v[54:57]
	v_mfma_f32_16x16x32_bf16 v[32:35], v[122:125], v[204:207], v[32:35]
	v_mfma_f32_16x16x32_bf16 v[64:67], v[188:191], v[204:207], v[64:67]
	v_mfma_f32_16x16x32_bf16 v[40:43], v[222:225], v[208:211], v[40:43]
	v_mfma_f32_16x16x32_bf16 v[88:91], v[226:229], v[208:211], v[88:91]
	v_mfma_f32_16x16x32_bf16 v[48:51], v[122:125], v[208:211], v[48:51]
	v_mfma_f32_16x16x32_bf16 v[76:79], v[188:191], v[208:211], v[76:79]
	v_mfma_f32_16x16x32_bf16 v[80:83], v[222:225], v[216:219], v[80:83]
	v_mfma_f32_16x16x32_bf16 v[84:87], v[226:229], v[216:219], v[84:87]
	v_mfma_f32_16x16x32_bf16 v[68:71], v[122:125], v[216:219], v[68:71]
	v_mfma_f32_16x16x32_bf16 v[72:75], v[188:191], v[216:219], v[72:75]
	s_setprio 0
	s_mov_b32 s6, s2
	s_waitcnt vmcnt(0) lgkmcnt(0)
	s_barrier
	s_cmp_lt_u32 s6, 16
	s_cbranch_scc1 .LBB0_1166
	s_waitcnt vmcnt(5)
	v_add_u32_e32 v15, s46, v170
	v_or_b32_e32 v188, v15, v148
	v_or_b32_e32 v130, s0, v234
	s_add_i32 s0, s46, 0xfffff000
	v_lshlrev_b32_e32 v0, 2, v188
	s_ashr_i32 s0, s0, 10
	global_load_dword v14, v0, s[28:29]
	global_load_dword v30, v0, s[28:29] offset:64
	global_load_dword v31, v0, s[28:29] offset:128
	global_load_dword v44, v0, s[28:29] offset:192
	s_add_i32 s2, s0, 16
	s_and_b64 s[0:1], s[24:25], exec
	s_cselect_b32 s0, 15, s2
	s_mul_hi_u32 s1, s0, 0x4200
	s_mulk_i32 s0, 0x4200
	s_add_u32 s0, s4, s0
	s_addc_u32 s1, s5, s1
	v_mov_b32_e32 v139, v131
	v_lshl_add_u64 v[0:1], v[130:131], 2, s[0:1]
	v_lshl_add_u64 v[4:5], v[0:1], 0, v[138:139]
	global_load_dwordx4 v[22:25], v[4:5], off
	global_load_dwordx4 v[0:3], v[4:5], off offset:64
	global_load_dwordx4 v[92:95], v[4:5], off offset:128
	s_nop 0
	global_load_dwordx4 v[4:7], v[4:5], off offset:192
	v_mov_b32_e32 v12, v26
	v_mov_b32_e32 v13, v9
	v_mov_b32_e32 v9, v27
	s_waitcnt vmcnt(11)
	v_mov_b32_e32 v20, v54
	v_mov_b32_e32 v21, v37
	v_mov_b32_e32 v37, v55
	s_cmpk_lt_u32 s45, 0x50
	s_waitcnt vmcnt(7)
	v_fmamk_f32 v14, v14, 0x3a800000, v183
	s_waitcnt vmcnt(6)
	v_fmamk_f32 v26, v30, 0x3a800000, v183
	v_cmp_gt_f32_e64 s[10:11], s39, v26
	s_waitcnt vmcnt(4)
	v_fmamk_f32 v30, v44, 0x3a800000, v183
	v_mul_f32_e32 v44, 0x4b800000, v26
	v_fmamk_f32 v27, v31, 0x3a800000, v183
	v_mul_f32_e32 v46, 0x4b800000, v30
	v_cndmask_b32_e64 v26, v26, v44, s[10:11]
	v_cmp_gt_f32_e64 s[14:15], s39, v30
	v_mul_f32_e32 v31, 0x4b800000, v14
	v_mul_f32_e32 v45, 0x4b800000, v27
	v_cmp_gt_f32_e32 vcc, s39, v14
	v_cmp_gt_f32_e64 s[12:13], s39, v27
	v_cndmask_b32_e64 v30, v30, v46, s[14:15]
	v_rsq_f32_e32 v26, v26
	v_cndmask_b32_e32 v14, v14, v31, vcc
	v_cndmask_b32_e64 v27, v27, v45, s[12:13]
	v_rsq_f32_e32 v30, v30
	v_rsq_f32_e32 v14, v14
	v_rsq_f32_e32 v27, v27
	s_waitcnt vmcnt(2)
	v_mov_b32_e32 v97, v3
	v_mul_f32_e32 v3, 0x45800000, v26
	v_mov_b32_e32 v96, v25
	v_mul_f32_e32 v25, 0x45800000, v30
	v_cndmask_b32_e64 v102, v26, v3, s[10:11]
	v_mul_f32_e32 v31, 0x45800000, v14
	s_waitcnt vmcnt(0)
	v_mov_b32_e32 v99, v7
	v_mul_f32_e32 v7, 0x45800000, v27
	v_cndmask_b32_e64 v106, v30, v25, s[14:15]
	v_fma_f32 v30, v56, v102, v2
	v_mov_b32_e32 v56, v39
	v_mov_b32_e32 v53, v1
	v_mov_b32_e32 v1, v23
	v_cndmask_b32_e32 v100, v14, v31, vcc
	v_cndmask_b32_e64 v104, v27, v7, s[12:13]
	v_pk_fma_f32 v[152:153], v[56:57], v[102:103], v[96:97] op_sel_hi:[1,0,1]
	v_mov_b32_e32 v56, v88
	v_mov_b32_e32 v57, v41
	v_mov_b32_e32 v98, v95
	v_mov_b32_e32 v52, v22
	v_fma_f32 v14, v28, v100, v2
	v_mov_b32_e32 v28, v11
	v_fma_f32 v26, v38, v102, v24
	v_fma_f32 v38, v66, v102, v6
	v_mov_b32_e32 v66, v35
	v_mov_b32_e32 v41, v89
	v_pk_fma_f32 v[160:161], v[56:57], v[104:105], v[0:1] op_sel_hi:[1,0,1]
	v_mov_b32_e32 v56, v80
	v_mov_b32_e32 v57, v85
	v_mov_b32_e32 v85, v81
	v_fma_f32 v10, v10, v100, v24
	v_fma_f32 v42, v42, v104, v24
	v_fma_f32 v58, v82, v106, v24
	v_pk_fma_f32 v[8:9], v[8:9], v[100:101], v[52:53] op_sel_hi:[1,0,1]
	v_pk_fma_f32 v[140:141], v[12:13], v[100:101], v[0:1] op_sel_hi:[1,0,1]
	v_pk_fma_f32 v[24:25], v[36:37], v[102:103], v[52:53] op_sel_hi:[1,0,1]
	v_pk_fma_f32 v[20:21], v[20:21], v[102:103], v[0:1] op_sel_hi:[1,0,1]
	v_pk_fma_f32 v[142:143], v[28:29], v[100:101], v[96:97] op_sel_hi:[1,0,1]
	v_pk_fma_f32 v[28:29], v[66:67], v[102:103], v[98:99] op_sel_hi:[1,0,1]
	v_pk_fma_f32 v[40:41], v[40:41], v[104:105], v[52:53] op_sel_hi:[1,0,1]
	v_pk_fma_f32 v[56:57], v[56:57], v[106:107], v[52:53] op_sel_hi:[1,0,1]
	v_pk_fma_f32 v[52:53], v[84:85], v[106:107], v[0:1] op_sel_hi:[1,0,1]
	v_mov_b32_e32 v0, v60
	v_mov_b32_e32 v1, v17
	v_mov_b32_e32 v66, v4
	v_mov_b32_e32 v67, v93
	v_pk_fma_f32 v[156:157], v[0:1], v[100:101], v[66:67] op_sel_hi:[1,0,1]
	v_mov_b32_e32 v0, v64
	v_mov_b32_e32 v1, v33
	v_pk_fma_f32 v[162:163], v[0:1], v[102:103], v[66:67] op_sel_hi:[1,0,1]
	v_mov_b32_e32 v0, v76
	v_mov_b32_e32 v1, v49
	v_fma_f32 v22, v62, v100, v6
	v_mov_b32_e32 v62, v19
	v_fma_f32 v46, v90, v104, v2
	v_mov_b32_e32 v90, v43
	v_fma_f32 v54, v78, v104, v6
	v_mov_b32_e32 v78, v51
	v_fmac_f32_e32 v2, v86, v106
	v_mov_b32_e32 v86, v83
	v_mov_b32_e32 v17, v61
	v_mov_b32_e32 v93, v5
	v_mov_b32_e32 v33, v65
	v_pk_fma_f32 v[166:167], v[0:1], v[104:105], v[66:67] op_sel_hi:[1,0,1]
	v_mov_b32_e32 v49, v77
	v_mov_b32_e32 v0, v68
	v_mov_b32_e32 v1, v73
	v_mov_b32_e32 v73, v69
	v_fmac_f32_e32 v6, v74, v106
	v_mov_b32_e32 v74, v71
	s_cselect_b64 s[12:13], -1, 0
	s_and_b32 s0, s45, 0x7ffffff0
	v_fma_f32 v18, v18, v100, v94
	v_fma_f32 v34, v34, v102, v94
	v_fma_f32 v50, v50, v104, v94
	v_pk_fma_f32 v[12:13], v[62:63], v[100:101], v[98:99] op_sel_hi:[1,0,1]
	v_pk_fma_f32 v[36:37], v[90:91], v[104:105], v[96:97] op_sel_hi:[1,0,1]
	v_pk_fma_f32 v[44:45], v[78:79], v[104:105], v[98:99] op_sel_hi:[1,0,1]
	v_pk_fma_f32 v[164:165], v[86:87], v[106:107], v[96:97] op_sel_hi:[1,0,1]
	v_fma_f32 v62, v70, v106, v94
	v_pk_fma_f32 v[16:17], v[16:17], v[100:101], v[92:93] op_sel_hi:[1,0,1]
	v_pk_fma_f32 v[32:33], v[32:33], v[102:103], v[92:93] op_sel_hi:[1,0,1]
	v_pk_fma_f32 v[48:49], v[48:49], v[104:105], v[92:93] op_sel_hi:[1,0,1]
	v_pk_fma_f32 v[60:61], v[0:1], v[106:107], v[92:93] op_sel_hi:[1,0,1]
	v_pk_fma_f32 v[0:1], v[72:73], v[106:107], v[66:67] op_sel_hi:[1,0,1]
	v_pk_fma_f32 v[168:169], v[74:75], v[106:107], v[98:99] op_sel_hi:[1,0,1]
	s_cmpk_lg_i32 s0, 0x50
	s_mov_b64 s[10:11], -1
	s_cbranch_scc0 .LBB0_1181
	v_lshlrev_b32_e32 v3, 1, v15
	s_and_b64 s[0:1], s[26:27], s[12:13]
	v_and_b32_e32 v4, 0x780, v3
	v_mov_b32_e32 v5, v131
	v_cndmask_b32_e64 v3, 0, 1, s[0:1]
	v_lshl_add_u64 v[112:113], v[134:135], 0, v[4:5]
	v_cmp_ne_u32_e64 s[10:11], 1, v3
	s_andn2_b64 vcc, exec, s[0:1]
	v_lshlrev_b32_e32 v3, 7, v188
	s_cbranch_vccnz .LBB0_1170
	v_and_b32_e32 v4, 0x780, v3
	v_mov_b32_e32 v5, v131
	global_load_dwordx4 v[64:67], v[112:113], off
	global_load_dwordx4 v[68:71], v[112:113], off offset:16
	v_lshl_add_u64 v[4:5], v[134:135], 0, v[4:5]
	global_load_dwordx4 v[72:75], v[4:5], off
	global_load_dwordx4 v[76:79], v[4:5], off offset:16
	v_mov_b32_e32 v4, v140
	v_mov_b32_e32 v5, v9
	v_mov_b32_e32 v80, v8
	v_mov_b32_e32 v81, v141
	v_mov_b32_e32 v82, v156
	v_mov_b32_e32 v83, v17
	v_mov_b32_e32 v84, v16
	v_mov_b32_e32 v85, v157
	s_waitcnt vmcnt(3)
	v_mov_b32_e32 v90, v65
	v_mov_b32_e32 v91, v67
	v_mov_b32_e32 v86, v65
	v_mov_b32_e32 v65, v66
	v_pk_mul_f32 v[4:5], v[4:5], v[90:91]
	v_mov_b32_e32 v87, v66
	v_mov_b32_e32 v88, v64
	v_mov_b32_e32 v89, v67
	s_waitcnt vmcnt(2)
	v_mul_f32_e32 v66, v10, v68
	v_mul_f32_e32 v92, v14, v69
	v_mul_f32_e32 v94, v14, v68
	v_mul_f32_e32 v96, v10, v69
	v_pk_mul_f32 v[68:69], v[142:143], v[70:71]
	v_pk_mul_f32 v[70:71], v[142:143], v[70:71] op_sel:[1,0] op_sel_hi:[0,1]
	s_waitcnt vmcnt(1)
	v_mov_b32_e32 v90, v73
	v_mov_b32_e32 v91, v74
	v_mov_b32_e32 v98, v72
	v_mov_b32_e32 v99, v75
	v_mov_b32_e32 v100, v73
	v_mov_b32_e32 v101, v75
	v_mov_b32_e32 v73, v74
	s_waitcnt vmcnt(0)
	v_mul_f32_e32 v74, v18, v76
	v_mul_f32_e32 v102, v22, v77
	v_mul_f32_e32 v104, v22, v76
	v_mul_f32_e32 v106, v18, v77
	v_pk_fma_f32 v[64:65], v[80:81], v[64:65], v[4:5] neg_lo:[0,0,1] neg_hi:[0,0,1]
	v_pk_mul_f32 v[4:5], v[12:13], v[78:79]
	v_pk_mul_f32 v[76:77], v[12:13], v[78:79] op_sel:[1,0] op_sel_hi:[0,1]
	v_pk_mul_f32 v[88:89], v[140:141], v[88:89]
	v_mov_b32_e32 v67, v68
	v_mov_b32_e32 v93, v69
	v_mov_b32_e32 v95, v70
	v_mov_b32_e32 v97, v71
	v_pk_mul_f32 v[78:79], v[156:157], v[98:99]
	v_pk_mul_f32 v[80:81], v[82:83], v[100:101]
	v_mov_b32_e32 v75, v4
	v_mov_b32_e32 v103, v5
	v_mov_b32_e32 v105, v76
	v_mov_b32_e32 v107, v77
	v_pk_add_f32 v[66:67], v[66:67], v[92:93] neg_lo:[0,1] neg_hi:[0,1]
	v_pk_fma_f32 v[68:69], v[8:9], v[86:87], v[88:89]
	v_pk_add_f32 v[70:71], v[94:95], v[96:97]
	v_pk_fma_f32 v[72:73], v[84:85], v[72:73], v[80:81] neg_lo:[0,0,1] neg_hi:[0,0,1]
	v_pk_add_f32 v[74:75], v[74:75], v[102:103] neg_lo:[0,1] neg_hi:[0,1]
	v_pk_fma_f32 v[76:77], v[16:17], v[90:91], v[78:79]
	v_pk_add_f32 v[78:79], v[104:105], v[106:107]
	s_branch .LBB0_1171

.LBB0_1344:
	s_and_b32 s18, s97, 7
	s_or_b32 s18, s18, s0
	s_lshl_b32 s26, s18, 7
	s_lshl_b32 s24, s97, 4
	v_or_b32_e32 v0, s26, v149
	s_and_b32 s27, s24, 0x7fffff80
	v_lshl_or_b32 v96, v0, 11, v116
	v_or_b32_e32 v0, s27, v149
	s_waitcnt vmcnt(1)
	v_lshl_add_u64 v[100:101], s[10:11], 0, v[96:97]
	v_lshl_or_b32 v98, v0, 11, v116
	v_add_co_u32_e32 v0, vcc, 0x10000, v100
	v_mov_b32_e32 v99, v97
	s_nop 0
	v_addc_co_u32_e32 v1, vcc, 0, v101, vcc
	v_add_co_u32_e32 v2, vcc, 0x20000, v100
	v_lshl_add_u64 v[102:103], s[8:9], 0, v[98:99]
	s_nop 0
	v_addc_co_u32_e32 v3, vcc, 0, v101, vcc
	v_add_co_u32_e32 v6, vcc, 0x30000, v100
	s_nop 0
	v_addc_co_u32_e32 v7, vcc, 0, v101, vcc
	v_add_co_u32_e32 v12, vcc, s1, v102
	s_nop 0
	v_addc_co_u32_e32 v13, vcc, 0, v103, vcc
	v_add_co_u32_e32 v14, vcc, s4, v102
	s_nop 0
	v_addc_co_u32_e32 v15, vcc, 0, v103, vcc
	v_add_co_u32_e32 v48, vcc, s5, v102
	s_nop 0
	v_addc_co_u32_e32 v49, vcc, 0, v103, vcc
	s_movk_i32 s24, 0x100
	s_mov_b32 s28, s19
	v_mov_b32_e32 v8, 0
	v_mov_b32_e32 v9, v97
	v_mov_b32_e32 v10, v97
	v_mov_b32_e32 v11, v97
	v_mov_b32_e32 v4, 0
	v_mov_b32_e32 v5, v97
	v_mov_b32_e32 v6, v97
	v_mov_b32_e32 v7, v97
	v_mov_b32_e32 v12, 0
	v_mov_b32_e32 v13, v97
	v_mov_b32_e32 v14, v97
	v_mov_b32_e32 v15, v97
	v_mov_b32_e32 v0, 0
	v_mov_b32_e32 v1, v97
	v_lshl_add_u64 v[104:105], v[102:103], 0, s[12:13]
	v_lshl_add_u64 v[106:107], v[102:103], 0, s[14:15]
	v_lshl_add_u64 v[108:109], v[102:103], 0, s[16:17]
	v_lshl_add_u64 v[110:111], v[100:101], 0, s[12:13]
	v_lshl_add_u64 v[112:113], v[100:101], 0, s[14:15]
	v_lshl_add_u64 v[114:115], v[100:101], 0, s[16:17]
	s_barrier
	v_mov_b32_e32 v2, v97
	v_mov_b32_e32 v3, v97
	v_mov_b32_e32 v52, 0
	v_mov_b32_e32 v53, v97
	v_mov_b32_e32 v54, v97
	v_mov_b32_e32 v55, v97
	v_mov_b32_e32 v48, 0
	v_mov_b32_e32 v49, v97
	v_mov_b32_e32 v50, v97
	v_mov_b32_e32 v51, v97
	v_mov_b32_e32 v60, 0
	v_mov_b32_e32 v61, v97
	v_mov_b32_e32 v62, v97
	v_mov_b32_e32 v63, v97
	v_mov_b32_e32 v56, 0
	v_mov_b32_e32 v57, v97
	v_mov_b32_e32 v58, v97
	v_mov_b32_e32 v59, v97
	v_mov_b32_e32 v44, 0
	v_mov_b32_e32 v45, v97
	v_mov_b32_e32 v46, v97
	v_mov_b32_e32 v47, v97
	v_mov_b32_e32 v36, 0
	v_mov_b32_e32 v37, v97
	v_mov_b32_e32 v38, v97
	v_mov_b32_e32 v39, v97
	v_mov_b32_e32 v20, 0
	v_mov_b32_e32 v21, v97
	v_mov_b32_e32 v22, v97
	v_mov_b32_e32 v23, v97
	v_mov_b32_e32 v16, 0
	v_mov_b32_e32 v17, v97
	v_mov_b32_e32 v18, v97
	v_mov_b32_e32 v19, v97
	v_mov_b32_e32 v32, 0
	v_mov_b32_e32 v33, v97
	v_mov_b32_e32 v34, v97
	v_mov_b32_e32 v35, v97
	v_mov_b32_e32 v24, 0
	v_mov_b32_e32 v25, v97
	v_mov_b32_e32 v26, v97
	v_mov_b32_e32 v27, v97
	v_mov_b32_e32 v40, 0
	v_mov_b32_e32 v41, v97
	v_mov_b32_e32 v42, v97
	v_mov_b32_e32 v43, v97
	v_mov_b32_e32 v28, 0
	v_mov_b32_e32 v29, v97
	v_mov_b32_e32 v30, v97
	v_mov_b32_e32 v31, v97
	v_readlane_b32 s100, v253, 0
	v_readlane_b32 s101, v253, 1
	s_load_dwordx2 s[100:101], s[100:101], 0x160
	v_lshrrev_b32_e32 v71, 6, v146
	s_nop 0
	v_readfirstlane_b32 s30, v71
	v_lshrrev_b32_e32 v69, 3, v146
	v_and_b32_e32 v70, 7, v146
	v_xor_b32_e32 v70, v69, v70
	v_and_b32_e32 v70, 7, v70
	v_lshlrev_b32_e32 v70, 4, v70
	v_lshl_or_b32 v68, v69, 11, v70
	v_add_u32_e32 v69, 0x10000, v68
	v_add_u32_e32 v70, 0x20000, v68
	v_add_u32_e32 v71, 0x30000, v68
	s_and_b32 s98, s97, 7
	s_and_b32 s99, s69, 7
	s_lshl_b32 s99, s99, 3
	s_or_b32 s98, s98, s99
	s_lshl_b32 s98, s98, 18
	s_add_u32 s98, s98, 0x2000000
	s_lshr_b32 s99, s97, 3
	s_lshl_b32 s99, s99, 18
	s_add_u32 s99, s99, 0x9240000
	s_lshl_b32 s30, s30, 10
	s_waitcnt lgkmcnt(0)
	s_mov_b32 m0, s99
	s_add_u32 s98, s100, s98
	s_addc_u32 s99, s101, 0
	s_add_u32 s100, s100, m0
	s_addc_u32 s101, s101, 0
	s_add_u32 m0, s30, 0x0
	s_nop 0
	global_load_lds_dwordx4 v68, s[98:99]
	s_add_u32 m0, s30, 0x1000
	s_nop 0
	global_load_lds_dwordx4 v69, s[98:99]
	s_add_u32 m0, s30, 0x2000
	s_nop 0
	global_load_lds_dwordx4 v70, s[98:99]
	s_add_u32 m0, s30, 0x3000
	s_nop 0
	global_load_lds_dwordx4 v71, s[98:99]
	s_add_u32 m0, s30, 0x8000
	s_nop 0
	global_load_lds_dwordx4 v68, s[100:101]
	s_add_u32 m0, s30, 0x9000
	s_nop 0
	global_load_lds_dwordx4 v69, s[100:101]
	s_add_u32 m0, s30, 0xa000
	s_nop 0
	global_load_lds_dwordx4 v70, s[100:101]
	s_add_u32 m0, s30, 0xb000
	s_nop 0
	global_load_lds_dwordx4 v71, s[100:101]
	s_add_u32 s98, s98, 0x80
	s_addc_u32 s99, s99, 0
	s_add_u32 s100, s100, 0x80
	s_addc_u32 s101, s101, 0
	s_waitcnt vmcnt(0)
	s_waitcnt lgkmcnt(0)
	s_barrier
.LBB0_1345:
	s_add_i32 s25, s28, 2
	s_setprio 1
	ds_read_b128 v[124:127], v119 offset:32768
	ds_read_b128 v[132:135], v119 offset:34816
	ds_read_b128 v[128:131], v118
	ds_read_b128 v[136:139], v118 offset:2048
	ds_read_b128 v[140:143], v118 offset:4096
	ds_read_b128 v[152:155], v118 offset:6144
	s_waitcnt lgkmcnt(3)
	v_mfma_f32_16x16x32_bf16 v[8:11], v[124:127], v[128:131], v[8:11]
	ds_read_b128 v[156:159], v119 offset:36864
	v_mfma_f32_16x16x32_bf16 v[4:7], v[132:135], v[128:131], v[4:7]
	ds_read_b128 v[160:163], v119 offset:38912
	s_waitcnt lgkmcnt(1)
	v_mfma_f32_16x16x32_bf16 v[12:15], v[156:159], v[128:131], v[12:15]
	s_waitcnt lgkmcnt(0)
	v_mfma_f32_16x16x32_bf16 v[0:3], v[160:163], v[128:131], v[0:3]
	s_add_u32 m0, s30, 0x4000
	s_nop 0
	global_load_lds_dwordx4 v68, s[98:99]
	ds_read_b128 v[164:167], v120
	v_mfma_f32_16x16x32_bf16 v[44:47], v[124:127], v[136:139], v[44:47]
	v_mfma_f32_16x16x32_bf16 v[36:39], v[132:135], v[136:139], v[36:39]
	s_add_u32 m0, s30, 0x5000
	s_nop 0
	global_load_lds_dwordx4 v69, s[98:99]
	ds_read_b128 v[172:175], v120 offset:2048
	v_mfma_f32_16x16x32_bf16 v[20:23], v[156:159], v[136:139], v[20:23]
	v_mfma_f32_16x16x32_bf16 v[16:19], v[160:163], v[136:139], v[16:19]
	s_add_u32 m0, s30, 0x6000
	s_nop 0
	global_load_lds_dwordx4 v70, s[98:99]
	ds_read_b128 v[176:179], v120 offset:4096
	v_mfma_f32_16x16x32_bf16 v[52:55], v[124:127], v[140:143], v[52:55]
	v_mfma_f32_16x16x32_bf16 v[48:51], v[132:135], v[140:143], v[48:51]
	s_add_u32 m0, s30, 0x7000
	s_nop 0
	global_load_lds_dwordx4 v71, s[98:99]
	ds_read_b128 v[184:187], v120 offset:6144
	v_mfma_f32_16x16x32_bf16 v[32:35], v[156:159], v[140:143], v[32:35]
	v_mfma_f32_16x16x32_bf16 v[24:27], v[160:163], v[140:143], v[24:27]
	s_add_u32 m0, s30, 0xc000
	s_nop 0
	global_load_lds_dwordx4 v68, s[100:101]
	ds_read_b128 v[188:191], v121 offset:32768
	v_mfma_f32_16x16x32_bf16 v[60:63], v[124:127], v[152:155], v[60:63]
	v_mfma_f32_16x16x32_bf16 v[56:59], v[132:135], v[152:155], v[56:59]
	s_add_u32 m0, s30, 0xd000
	s_nop 0
	global_load_lds_dwordx4 v69, s[100:101]
	ds_read_b128 v[132:135], v121 offset:34816
	v_mfma_f32_16x16x32_bf16 v[40:43], v[156:159], v[152:155], v[40:43]
	v_mfma_f32_16x16x32_bf16 v[28:31], v[160:163], v[152:155], v[28:31]
	s_add_u32 m0, s30, 0xe000
	s_nop 0
	global_load_lds_dwordx4 v70, s[100:101]
	ds_read_b128 v[156:159], v121 offset:36864
	s_waitcnt lgkmcnt(2)
	v_mfma_f32_16x16x32_bf16 v[8:11], v[188:191], v[164:167], v[8:11]
	s_waitcnt lgkmcnt(1)
	v_mfma_f32_16x16x32_bf16 v[4:7], v[132:135], v[164:167], v[4:7]
	s_add_u32 m0, s30, 0xf000
	s_nop 0
	global_load_lds_dwordx4 v71, s[100:101]
	s_add_u32 s98, s98, 0x80
	s_addc_u32 s99, s99, 0
	s_add_u32 s100, s100, 0x80
	s_addc_u32 s101, s101, 0
	ds_read_b128 v[192:195], v121 offset:38912
	s_waitcnt lgkmcnt(1)
	v_mfma_f32_16x16x32_bf16 v[12:15], v[156:159], v[164:167], v[12:15]
	s_waitcnt lgkmcnt(0)
	v_mfma_f32_16x16x32_bf16 v[0:3], v[192:195], v[164:167], v[0:3]
	v_mfma_f32_16x16x32_bf16 v[44:47], v[188:191], v[172:175], v[44:47]
	v_mfma_f32_16x16x32_bf16 v[36:39], v[132:135], v[172:175], v[36:39]
	v_mfma_f32_16x16x32_bf16 v[20:23], v[156:159], v[172:175], v[20:23]
	v_mfma_f32_16x16x32_bf16 v[16:19], v[192:195], v[172:175], v[16:19]
	v_mfma_f32_16x16x32_bf16 v[52:55], v[188:191], v[176:179], v[52:55]
	v_mfma_f32_16x16x32_bf16 v[48:51], v[132:135], v[176:179], v[48:51]
	v_mfma_f32_16x16x32_bf16 v[32:35], v[156:159], v[176:179], v[32:35]
	v_mfma_f32_16x16x32_bf16 v[24:27], v[192:195], v[176:179], v[24:27]
	v_mfma_f32_16x16x32_bf16 v[60:63], v[188:191], v[184:187], v[60:63]
	v_mfma_f32_16x16x32_bf16 v[56:59], v[132:135], v[184:187], v[56:59]
	v_mfma_f32_16x16x32_bf16 v[40:43], v[156:159], v[184:187], v[40:43]
	v_mfma_f32_16x16x32_bf16 v[28:31], v[192:195], v[184:187], v[28:31]
	s_setprio 0
	s_waitcnt vmcnt(0) lgkmcnt(0)
	s_barrier
	s_setprio 1
	ds_read_b128 v[84:87], v119 offset:49152
	ds_read_b128 v[88:91], v119 offset:51200
	ds_read_b128 v[64:67], v118 offset:16384
	ds_read_b128 v[72:75], v118 offset:18432
	ds_read_b128 v[76:79], v118 offset:20480
	ds_read_b128 v[92:95], v118 offset:22528
	s_waitcnt lgkmcnt(3)
	v_mfma_f32_16x16x32_bf16 v[8:11], v[84:87], v[64:67], v[8:11]
	ds_read_b128 v[132:135], v119 offset:53248
	v_mfma_f32_16x16x32_bf16 v[4:7], v[88:91], v[64:67], v[4:7]
	ds_read_b128 v[156:159], v119 offset:55296
	s_waitcnt lgkmcnt(1)
	v_mfma_f32_16x16x32_bf16 v[12:15], v[132:135], v[64:67], v[12:15]
	s_waitcnt lgkmcnt(0)
	v_mfma_f32_16x16x32_bf16 v[0:3], v[156:159], v[64:67], v[0:3]
	s_add_u32 m0, s30, 0x0
	s_nop 0
	global_load_lds_dwordx4 v68, s[98:99]
	ds_read_b128 v[164:167], v120 offset:16384
	v_mfma_f32_16x16x32_bf16 v[44:47], v[84:87], v[72:75], v[44:47]
	v_mfma_f32_16x16x32_bf16 v[36:39], v[88:91], v[72:75], v[36:39]
	s_add_u32 m0, s30, 0x1000
	s_nop 0
	global_load_lds_dwordx4 v69, s[98:99]
	ds_read_b128 v[172:175], v120 offset:18432
	v_mfma_f32_16x16x32_bf16 v[20:23], v[132:135], v[72:75], v[20:23]
	v_mfma_f32_16x16x32_bf16 v[16:19], v[156:159], v[72:75], v[16:19]
	s_add_u32 m0, s30, 0x2000
	s_nop 0
	global_load_lds_dwordx4 v70, s[98:99]
	ds_read_b128 v[176:179], v120 offset:20480
	v_mfma_f32_16x16x32_bf16 v[52:55], v[84:87], v[76:79], v[52:55]
	v_mfma_f32_16x16x32_bf16 v[48:51], v[88:91], v[76:79], v[48:51]
	s_add_u32 m0, s30, 0x3000
	s_nop 0
	global_load_lds_dwordx4 v71, s[98:99]
	ds_read_b128 v[184:187], v120 offset:22528
	v_mfma_f32_16x16x32_bf16 v[32:35], v[132:135], v[76:79], v[32:35]
	v_mfma_f32_16x16x32_bf16 v[24:27], v[156:159], v[76:79], v[24:27]
	s_add_u32 m0, s30, 0x8000
	s_nop 0
	global_load_lds_dwordx4 v68, s[100:101]
	ds_read_b128 v[188:191], v121 offset:49152
	v_mfma_f32_16x16x32_bf16 v[60:63], v[84:87], v[92:95], v[60:63]
	v_mfma_f32_16x16x32_bf16 v[56:59], v[88:91], v[92:95], v[56:59]
	s_add_u32 m0, s30, 0x9000
	s_nop 0
	global_load_lds_dwordx4 v69, s[100:101]
	ds_read_b128 v[192:195], v121 offset:51200
	v_mfma_f32_16x16x32_bf16 v[40:43], v[132:135], v[92:95], v[40:43]
	v_mfma_f32_16x16x32_bf16 v[28:31], v[156:159], v[92:95], v[28:31]
	s_add_u32 m0, s30, 0xa000
	s_nop 0
	global_load_lds_dwordx4 v70, s[100:101]
	ds_read_b128 v[132:135], v121 offset:53248
	s_waitcnt lgkmcnt(2)
	v_mfma_f32_16x16x32_bf16 v[8:11], v[188:191], v[164:167], v[8:11]
	s_waitcnt lgkmcnt(1)
	v_mfma_f32_16x16x32_bf16 v[4:7], v[192:195], v[164:167], v[4:7]
	s_add_u32 m0, s30, 0xb000
	s_nop 0
	global_load_lds_dwordx4 v71, s[100:101]
	s_add_u32 s98, s98, 0x80
	s_addc_u32 s99, s99, 0
	s_add_u32 s100, s100, 0x80
	s_addc_u32 s101, s101, 0
	ds_read_b128 v[156:159], v121 offset:55296
	s_waitcnt lgkmcnt(1)
	v_mfma_f32_16x16x32_bf16 v[12:15], v[132:135], v[164:167], v[12:15]
	s_waitcnt lgkmcnt(0)
	v_mfma_f32_16x16x32_bf16 v[0:3], v[156:159], v[164:167], v[0:3]
	v_mfma_f32_16x16x32_bf16 v[44:47], v[188:191], v[172:175], v[44:47]
	v_mfma_f32_16x16x32_bf16 v[36:39], v[192:195], v[172:175], v[36:39]
	v_mfma_f32_16x16x32_bf16 v[20:23], v[132:135], v[172:175], v[20:23]
	v_mfma_f32_16x16x32_bf16 v[16:19], v[156:159], v[172:175], v[16:19]
	v_mfma_f32_16x16x32_bf16 v[52:55], v[188:191], v[176:179], v[52:55]
	v_mfma_f32_16x16x32_bf16 v[48:51], v[192:195], v[176:179], v[48:51]
	v_mfma_f32_16x16x32_bf16 v[32:35], v[132:135], v[176:179], v[32:35]
	v_mfma_f32_16x16x32_bf16 v[24:27], v[156:159], v[176:179], v[24:27]
	v_mfma_f32_16x16x32_bf16 v[60:63], v[188:191], v[184:187], v[60:63]
	v_mfma_f32_16x16x32_bf16 v[56:59], v[192:195], v[184:187], v[56:59]
	v_mfma_f32_16x16x32_bf16 v[40:43], v[132:135], v[184:187], v[40:43]
	v_mfma_f32_16x16x32_bf16 v[28:31], v[156:159], v[184:187], v[28:31]
	s_setprio 0
	s_mov_b32 s28, s25
	s_waitcnt vmcnt(0) lgkmcnt(0)
	s_barrier
	s_cmp_lt_u32 s28, 16
	s_cbranch_scc1 .LBB0_1345
	s_add_i32 s18, s26, 0xfffff000
	s_ashr_i32 s18, s18, 10
	s_add_i32 s18, s18, 16
	s_and_b64 s[24:25], s[2:3], exec
	s_cselect_b32 s18, 15, s18
	s_mul_hi_u32 s24, s18, 0x3000
	s_mulk_i32 s18, 0x3000
	s_add_u32 s18, s6, s18
	v_or_b32_e32 v96, s27, v123
	s_addc_u32 s25, s7, s24
	s_waitcnt vmcnt(7)
	v_lshlrev_b64 v[64:65], 2, v[96:97]
	s_add_u32 s24, s18, 0xf442000
	s_waitcnt vmcnt(0)
	v_lshl_add_u64 v[94:95], s[6:7], 0, v[64:65]
	v_add_lshl_u32 v78, s26, v122, 12
	s_addc_u32 s25, s25, 0
	v_mov_b32_e32 v79, v97
	v_or_b32_e32 v114, 0x10000, v78
	v_mov_b32_e32 v115, v97
	v_or_b32_e32 v160, 0x20000, v78
	v_mov_b32_e32 v161, v97
	v_or_b32_e32 v164, 0x30000, v78
	v_mov_b32_e32 v165, v97
	v_or_b32_e32 v86, 16, v96
	v_mov_b32_e32 v87, v97
	v_lshl_add_u64 v[102:103], v[94:95], 0, 64
	v_or_b32_e32 v110, 32, v96
	v_mov_b32_e32 v111, v97
	v_lshl_add_u64 v[136:137], v[94:95], 0, s[20:21]
	v_or_b32_e32 v96, 48, v96
	v_lshl_add_u64 v[74:75], s[24:25], 0, v[64:65]
	v_lshl_add_u64 v[64:65], v[94:95], 0, v[78:79]
	v_lshl_add_u64 v[146:147], v[94:95], 0, v[114:115]
	v_lshl_add_u64 v[168:169], v[94:95], 0, v[160:161]
	v_lshl_add_u64 v[170:171], v[94:95], 0, v[164:165]
	v_lshl_add_u64 v[90:91], v[86:87], 2, s[24:25]
	v_lshl_add_u64 v[174:175], v[102:103], 0, v[160:161]
	v_lshl_add_u64 v[110:111], v[110:111], 2, s[24:25]
	v_lshl_add_u64 v[178:179], v[136:137], 0, v[114:115]
	v_lshl_add_u64 v[180:181], v[136:137], 0, v[160:161]
	v_lshl_add_u64 v[182:183], v[136:137], 0, v[164:165]
	v_lshl_add_u64 v[140:141], v[96:97], 2, s[24:25]
	v_lshl_add_u64 v[94:95], v[94:95], 0, s[22:23]
	global_load_dwordx4 v[66:69], v[74:75], off
	global_load_dwordx4 v[70:73], v[64:65], off
	v_lshl_add_u64 v[172:173], v[102:103], 0, v[114:115]
	global_load_dwordx4 v[74:77], v[146:147], off
	global_load_dwordx4 v[78:81], v[168:169], off
	global_load_dwordx4 v[82:85], v[170:171], off
	global_load_dwordx4 v[86:89], v[64:65], off offset:64
	s_nop 0
	global_load_dwordx4 v[90:93], v[90:91], off
	s_nop 0
	global_load_dwordx4 v[98:101], v[172:173], off
	v_lshl_add_u64 v[176:177], v[102:103], 0, v[164:165]
	global_load_dwordx4 v[102:105], v[174:175], off
	global_load_dwordx4 v[106:109], v[176:177], off
	s_nop 0
	global_load_dwordx4 v[110:113], v[110:111], off
	s_nop 0
	global_load_dwordx4 v[124:127], v[64:65], off offset:128
	global_load_dwordx4 v[128:131], v[178:179], off
	global_load_dwordx4 v[132:135], v[180:181], off
	global_load_dwordx4 v[136:139], v[182:183], off
	s_nop 0
	global_load_dwordx4 v[140:143], v[140:141], off
	s_nop 0
	global_load_dwordx4 v[152:155], v[64:65], off offset:192
	v_lshl_add_u64 v[114:115], v[94:95], 0, v[114:115]
	global_load_dwordx4 v[156:159], v[114:115], off
	v_lshl_add_u64 v[184:185], v[94:95], 0, v[160:161]
	global_load_dwordx4 v[160:163], v[184:185], off
	v_lshl_add_u64 v[94:95], v[94:95], 0, v[164:165]
	global_load_dwordx4 v[164:167], v[94:95], off
	s_add_i32 s97, s97, s96
	s_cmp_gt_u32 s97, 63
	s_waitcnt vmcnt(18)
	v_pk_fma_f32 v[8:9], v[8:9], v[66:67], v[70:71]
	v_pk_fma_f32 v[10:11], v[10:11], v[68:69], v[72:73]
	s_waitcnt vmcnt(17)
	v_pk_fma_f32 v[44:45], v[44:45], v[66:67], v[74:75]
	v_pk_fma_f32 v[46:47], v[46:47], v[68:69], v[76:77]
	s_waitcnt vmcnt(13)
	v_pk_fma_f32 v[4:5], v[4:5], v[90:91], v[86:87]
	v_pk_fma_f32 v[6:7], v[6:7], v[92:93], v[88:89]
	v_pk_fma_f32 v[52:53], v[52:53], v[66:67], v[78:79]
	v_pk_fma_f32 v[54:55], v[54:55], v[68:69], v[80:81]
	v_pk_fma_f32 v[60:61], v[60:61], v[66:67], v[82:83]
	v_pk_fma_f32 v[62:63], v[62:63], v[68:69], v[84:85]
	s_waitcnt vmcnt(12)
	v_pk_fma_f32 v[36:37], v[36:37], v[90:91], v[98:99]
	v_pk_fma_f32 v[38:39], v[38:39], v[92:93], v[100:101]
	s_waitcnt vmcnt(3)
	v_pk_fma_f32 v[0:1], v[0:1], v[140:141], v[152:153]
	v_pk_fma_f32 v[2:3], v[2:3], v[142:143], v[154:155]
	v_pk_fma_f32 v[48:49], v[48:49], v[90:91], v[102:103]
	v_pk_fma_f32 v[50:51], v[50:51], v[92:93], v[104:105]
	v_pk_fma_f32 v[56:57], v[56:57], v[90:91], v[106:107]
	v_pk_fma_f32 v[58:59], v[58:59], v[92:93], v[108:109]
	v_pk_fma_f32 v[12:13], v[12:13], v[110:111], v[124:125]
	v_pk_fma_f32 v[14:15], v[14:15], v[112:113], v[126:127]
	global_store_dwordx4 v[64:65], v[8:11], off
	global_store_dwordx4 v[146:147], v[44:47], off
	global_store_dwordx4 v[168:169], v[52:55], off
	global_store_dwordx4 v[170:171], v[60:63], off
	global_store_dwordx4 v[64:65], v[4:7], off offset:64
	global_store_dwordx4 v[172:173], v[36:39], off
	global_store_dwordx4 v[174:175], v[48:51], off
	global_store_dwordx4 v[176:177], v[56:59], off
	global_store_dwordx4 v[64:65], v[12:15], off offset:128
	v_pk_fma_f32 v[4:5], v[20:21], v[110:111], v[128:129]
	v_pk_fma_f32 v[6:7], v[22:23], v[112:113], v[130:131]
	global_store_dwordx4 v[64:65], v[0:3], off offset:192
	global_store_dwordx4 v[178:179], v[4:7], off
	s_waitcnt vmcnt(13)
	v_pk_fma_f32 v[0:1], v[16:17], v[140:141], v[156:157]
	v_pk_fma_f32 v[2:3], v[18:19], v[142:143], v[158:159]
	v_pk_fma_f32 v[4:5], v[32:33], v[110:111], v[132:133]
	v_pk_fma_f32 v[6:7], v[34:35], v[112:113], v[134:135]
	global_store_dwordx4 v[114:115], v[0:3], off
	global_store_dwordx4 v[180:181], v[4:7], off
	s_waitcnt vmcnt(14)
	v_pk_fma_f32 v[0:1], v[24:25], v[140:141], v[160:161]
	v_pk_fma_f32 v[2:3], v[26:27], v[142:143], v[162:163]
	v_pk_fma_f32 v[4:5], v[40:41], v[110:111], v[136:137]
	v_pk_fma_f32 v[6:7], v[42:43], v[112:113], v[138:139]
	global_store_dwordx4 v[184:185], v[0:3], off
	global_store_dwordx4 v[182:183], v[4:7], off
	s_waitcnt vmcnt(15)
	v_pk_fma_f32 v[0:1], v[28:29], v[140:141], v[164:165]
	v_pk_fma_f32 v[2:3], v[30:31], v[142:143], v[166:167]
	global_store_dwordx4 v[94:95], v[0:3], off
	s_cbranch_scc0 .LBB0_1344
